# q4c without the per-segment s_setprio flips (A/B of priority in the 4-phase loops)
# speedup vs baseline: 1.0108x; 1.0046x over previous
; #define PG8_STAGE(bufoff, gbase, voff) do { _Pragma("unroll") for (int _i = 0; _i < 2; ++_i) \
;         __builtin_amdgcn_global_load_lds((const unsigned*)((const char*)(gbase) + (voff)[_i]), (LAS unsigned*)(lds + (bufoff) + ldsw + _i * 8192), 16, 0, 0); } while (0)
; #define PG8_LDA(dst, b, h) do { _Pragma("unroll") for (int m = 0; m < 4; ++m) _Pragma("unroll") for (int k = 0; k < 2; ++k) dst[m][k] = *(const LAS bf16x8*)(lds + PG8_SA(b, h) + aoff + m * 2048 + k * 1024); } while (0)
; #define PG8_LDB(dst, b, h) do { _Pragma("unroll") for (int n = 0; n < 2; ++n) _Pragma("unroll") for (int k = 0; k < 2; ++k) dst[n][k] = *(const LAS bf16x8*)(lds + PG8_SB(b, h) + boff + n * 2048 + k * 1024); } while (0)
; #define PG8_MMA(ai, bj, At, Bt) do { __builtin_amdgcn_s_setprio(1); _Pragma("unroll") for (int m = 0; m < 4; ++m) _Pragma("unroll") for (int n = 0; n < 2; ++n) _Pragma("unroll") for (int k = 0; k < 2; ++k) \
;         acc[ai][bj][m][n] = __builtin_amdgcn_mfma_f32_16x16x32_bf16(Bt[n][k], At[m][k], acc[ai][bj][m][n], 0, 0, 0); __builtin_amdgcn_s_setprio(0); } while (0)
; #define PG8_WAIT_L(n) asm volatile("s_waitcnt lgkmcnt(" #n ")" ::: "memory")
; #define PG8_BAR __builtin_amdgcn_s_barrier()
; #define PG8_SCHED __builtin_amdgcn_sched_barrier(0)
; template <class Epi, class Sched>
; __device__ __forceinline__ void gemm_phase(LAS unsigned char* lds, const Gemm g, const Sched& S, const Epi& E) {
;     ...
;         for (int t = 0; t < nt; t += 2) {
;             const bool last = (t == nt - 2);
;             const char* a1 = cA + (size_t)(t + 1) * kstep;
;             const char* a2 = last ? nA : cA + (size_t)(t + 2) * kstep; const char* b2 = last ? nB : cB + (size_t)(t + 2) * kstep;
;             const char* a3 = a2 + kstep; const char* b3 = b2 + kstep;
;             PG8_LDB(B0, 0, 0); PG8_SCHED; PG8_LDA(At, 0, 0); PG8_STAGE(PG8_SA(1, 1), a1 + hstep, voffA);
;             PG8_WAIT_L(8); PG8_BAR; PG8_WAIT_L(0); PG8_MMA(0, 0, At, B0); PG8_BAR; PG8_SCHED;
;             PG8_LDB(B1, 0, 1); PG8_STAGE(PG8_SB(0, 0), b2, voffB);
;             PG8_BAR; PG8_WAIT_L(0); PG8_MMA(0, 1, At, B1); PG8_BAR;
;             PG8_LDA(At, 0, 1); PG8_STAGE(PG8_SA(0, 0), a2, voffA);
;             PG8_BAR; PG8_WAIT_L(0); PG8_MMA(1, 0, At, B0); PG8_BAR; PG8_SCHED;
.LBB0_44:
	s_add_u32 s50, s28, 0x100
	s_addc_u32 s51, s29, 0
	s_cmpk_eq_i32 s75, 0x7c
	s_cselect_b32 s55, s27, s51
	s_cselect_b32 s54, s71, s50
	s_cselect_b32 s53, s25, s74
	s_cselect_b32 s52, s72, s73
	v_lshl_add_u64 v[156:157], s[28:29], 0, v[150:151]
	s_add_i32 m0, s9, 0xc000
	s_nop 0
	global_load_lds_dwordx4 v[156:157], off
	v_lshl_add_u64 v[156:157], s[28:29], 0, v[148:149]
	s_add_i32 m0, s9, 0xe000
	s_nop 0
	global_load_lds_dwordx4 v[156:157], off
	s_add_i32 s38, 0, 0x10000
	v_add_u32_e32 v78, s38, v163
	ds_read_b128 v[66:69], v78
	ds_read_b128 v[70:73], v78 offset:1024
	ds_read_b128 v[74:77], v78 offset:2048
	ds_read_b128 v[78:81], v78 offset:3072
	ds_read_b128 v[152:155], v165
	ds_read_b128 v[166:169], v165 offset:1024
	ds_read_b128 v[170:173], v165 offset:2048
	ds_read_b128 v[174:177], v165 offset:3072
	ds_read_b128 v[178:181], v165 offset:4096
	ds_read_b128 v[182:185], v165 offset:5120
	ds_read_b128 v[186:189], v165 offset:6144
	ds_read_b128 v[190:193], v165 offset:7168
	s_add_i32 s39, 0, 0x14000
	v_add_u32_e32 v156, s39, v163
	ds_read_b128 v[194:197], v156
	ds_read_b128 v[198:201], v156 offset:1024
	ds_read_b128 v[202:205], v156 offset:2048
	ds_read_b128 v[210:213], v156 offset:3072
	s_waitcnt lgkmcnt(4)
	s_barrier
	s_waitcnt lgkmcnt(0)
	v_mfma_f32_16x16x32_bf16 v[142:145], v[66:69], v[152:155], v[142:145]
	v_mfma_f32_16x16x32_bf16 v[138:141], v[74:77], v[152:155], v[138:141]
	v_mfma_f32_16x16x32_bf16 v[126:129], v[66:69], v[170:173], v[126:129]
	v_mfma_f32_16x16x32_bf16 v[122:125], v[74:77], v[170:173], v[122:125]
	v_mfma_f32_16x16x32_bf16 v[110:113], v[66:69], v[178:181], v[110:113]
	v_mfma_f32_16x16x32_bf16 v[106:109], v[74:77], v[178:181], v[106:109]
	v_mfma_f32_16x16x32_bf16 v[102:105], v[66:69], v[186:189], v[102:105]
	v_mfma_f32_16x16x32_bf16 v[98:101], v[74:77], v[186:189], v[98:101]
	v_mfma_f32_16x16x32_bf16 v[142:145], v[70:73], v[166:169], v[142:145]
	v_mfma_f32_16x16x32_bf16 v[138:141], v[78:81], v[166:169], v[138:141]
	v_mfma_f32_16x16x32_bf16 v[126:129], v[70:73], v[174:177], v[126:129]
	v_mfma_f32_16x16x32_bf16 v[122:125], v[78:81], v[174:177], v[122:125]
	v_mfma_f32_16x16x32_bf16 v[110:113], v[70:73], v[182:185], v[110:113]
	v_mfma_f32_16x16x32_bf16 v[106:109], v[78:81], v[182:185], v[106:109]
	v_mfma_f32_16x16x32_bf16 v[102:105], v[70:73], v[190:193], v[102:105]
	v_mfma_f32_16x16x32_bf16 v[98:101], v[78:81], v[190:193], v[98:101]
	v_mfma_f32_16x16x32_bf16 v[134:137], v[194:197], v[152:155], v[134:137]
	v_mfma_f32_16x16x32_bf16 v[130:133], v[202:205], v[152:155], v[130:133]
	v_mfma_f32_16x16x32_bf16 v[118:121], v[194:197], v[170:173], v[118:121]
	v_mfma_f32_16x16x32_bf16 v[114:117], v[202:205], v[170:173], v[114:117]
	v_mfma_f32_16x16x32_bf16 v[94:97], v[194:197], v[178:181], v[94:97]
	v_mfma_f32_16x16x32_bf16 v[90:93], v[202:205], v[178:181], v[90:93]
	v_mfma_f32_16x16x32_bf16 v[86:89], v[194:197], v[186:189], v[86:89]
	v_mfma_f32_16x16x32_bf16 v[82:85], v[202:205], v[186:189], v[82:85]
	v_mfma_f32_16x16x32_bf16 v[134:137], v[198:201], v[166:169], v[134:137]
	v_mfma_f32_16x16x32_bf16 v[130:133], v[210:213], v[166:169], v[130:133]
	v_mfma_f32_16x16x32_bf16 v[118:121], v[198:201], v[174:177], v[118:121]
	v_mfma_f32_16x16x32_bf16 v[114:117], v[210:213], v[174:177], v[114:117]
	v_mfma_f32_16x16x32_bf16 v[94:97], v[198:201], v[182:185], v[94:97]
	v_mfma_f32_16x16x32_bf16 v[90:93], v[210:213], v[182:185], v[90:93]
	v_mfma_f32_16x16x32_bf16 v[86:89], v[198:201], v[190:193], v[86:89]
	v_mfma_f32_16x16x32_bf16 v[82:85], v[210:213], v[190:193], v[82:85]
	s_barrier
	s_add_i32 s28, s38, s60
	v_lshl_add_u64 v[156:157], s[52:53], 0, v[0:1]
	s_mov_b32 m0, s28
	v_lshl_add_u64 v[160:161], s[52:53], 0, v[146:147]
	global_load_lds_dwordx4 v[156:157], off
	s_add_i32 m0, s28, 0x2000
	s_nop 0
	global_load_lds_dwordx4 v[160:161], off
	s_mov_b32 m0, s9
	v_lshl_add_u64 v[206:207], s[54:55], 0, v[0:1]
	global_load_lds_dwordx4 v[206:207], off
	v_lshl_add_u64 v[214:215], s[54:55], 0, v[146:147]
	s_mov_b32 m0, s61
	s_nop 0
	global_load_lds_dwordx4 v[214:215], off
	ds_read_b128 v[152:155], v165 offset:16384
	ds_read_b128 v[166:169], v165 offset:17408
	ds_read_b128 v[170:173], v165 offset:18432
	ds_read_b128 v[174:177], v165 offset:19456
	ds_read_b128 v[178:181], v165 offset:20480
	ds_read_b128 v[182:185], v165 offset:21504
	ds_read_b128 v[186:189], v165 offset:22528
	ds_read_b128 v[190:193], v165 offset:23552
	s_waitcnt vmcnt(4)
	s_waitcnt lgkmcnt(0)
	s_barrier
	v_mfma_f32_16x16x32_bf16 v[62:65], v[66:69], v[152:155], v[62:65]
	v_mfma_f32_16x16x32_bf16 v[58:61], v[74:77], v[152:155], v[58:61]
	v_mfma_f32_16x16x32_bf16 v[46:49], v[66:69], v[170:173], v[46:49]
	v_mfma_f32_16x16x32_bf16 v[42:45], v[74:77], v[170:173], v[42:45]
	v_mfma_f32_16x16x32_bf16 v[30:33], v[66:69], v[178:181], v[30:33]
	v_mfma_f32_16x16x32_bf16 v[26:29], v[74:77], v[178:181], v[26:29]
	v_mfma_f32_16x16x32_bf16 v[22:25], v[66:69], v[186:189], v[22:25]
	v_mfma_f32_16x16x32_bf16 v[14:17], v[74:77], v[186:189], v[14:17]
	v_mfma_f32_16x16x32_bf16 v[62:65], v[70:73], v[166:169], v[62:65]
	v_mfma_f32_16x16x32_bf16 v[58:61], v[78:81], v[166:169], v[58:61]
	v_mfma_f32_16x16x32_bf16 v[46:49], v[70:73], v[174:177], v[46:49]
	v_mfma_f32_16x16x32_bf16 v[42:45], v[78:81], v[174:177], v[42:45]
	v_mfma_f32_16x16x32_bf16 v[30:33], v[70:73], v[182:185], v[30:33]
	v_mfma_f32_16x16x32_bf16 v[26:29], v[78:81], v[182:185], v[26:29]
	v_mfma_f32_16x16x32_bf16 v[22:25], v[70:73], v[190:193], v[22:25]
	v_mfma_f32_16x16x32_bf16 v[14:17], v[78:81], v[190:193], v[14:17]
	v_mfma_f32_16x16x32_bf16 v[54:57], v[194:197], v[152:155], v[54:57]
	v_mfma_f32_16x16x32_bf16 v[50:53], v[202:205], v[152:155], v[50:53]
	v_mfma_f32_16x16x32_bf16 v[38:41], v[194:197], v[170:173], v[38:41]
	v_mfma_f32_16x16x32_bf16 v[34:37], v[202:205], v[170:173], v[34:37]
	v_mfma_f32_16x16x32_bf16 v[18:21], v[194:197], v[178:181], v[18:21]
	v_mfma_f32_16x16x32_bf16 v[10:13], v[202:205], v[178:181], v[10:13]
	v_mfma_f32_16x16x32_bf16 v[6:9], v[194:197], v[186:189], v[6:9]
	v_mfma_f32_16x16x32_bf16 v[2:5], v[202:205], v[186:189], v[2:5]
	v_mfma_f32_16x16x32_bf16 v[54:57], v[198:201], v[166:169], v[54:57]
	v_mfma_f32_16x16x32_bf16 v[50:53], v[210:213], v[166:169], v[50:53]
	v_mfma_f32_16x16x32_bf16 v[38:41], v[198:201], v[174:177], v[38:41]
	v_mfma_f32_16x16x32_bf16 v[34:37], v[210:213], v[174:177], v[34:37]
	v_mfma_f32_16x16x32_bf16 v[18:21], v[198:201], v[182:185], v[18:21]
	v_mfma_f32_16x16x32_bf16 v[10:13], v[210:213], v[182:185], v[10:13]
	v_mfma_f32_16x16x32_bf16 v[6:9], v[198:201], v[190:193], v[6:9]
	v_mfma_f32_16x16x32_bf16 v[2:5], v[210:213], v[190:193], v[2:5]
	s_barrier
; #define PG8_STAGE(bufoff, gbase, voff) do { _Pragma("unroll") for (int _i = 0; _i < 2; ++_i) \
;         __builtin_amdgcn_global_load_lds((const unsigned*)((const char*)(gbase) + (voff)[_i]), (LAS unsigned*)(lds + (bufoff) + ldsw + _i * 8192), 16, 0, 0); } while (0)
; #define PG8_LDA(dst, b, h) do { _Pragma("unroll") for (int m = 0; m < 4; ++m) _Pragma("unroll") for (int k = 0; k < 2; ++k) dst[m][k] = *(const LAS bf16x8*)(lds + PG8_SA(b, h) + aoff + m * 2048 + k * 1024); } while (0)
; #define PG8_LDB(dst, b, h) do { _Pragma("unroll") for (int n = 0; n < 2; ++n) _Pragma("unroll") for (int k = 0; k < 2; ++k) dst[n][k] = *(const LAS bf16x8*)(lds + PG8_SB(b, h) + boff + n * 2048 + k * 1024); } while (0)
; #define PG8_MMA(ai, bj, At, Bt) do { __builtin_amdgcn_s_setprio(1); _Pragma("unroll") for (int m = 0; m < 4; ++m) _Pragma("unroll") for (int n = 0; n < 2; ++n) _Pragma("unroll") for (int k = 0; k < 2; ++k) \
;         acc[ai][bj][m][n] = __builtin_amdgcn_mfma_f32_16x16x32_bf16(Bt[n][k], At[m][k], acc[ai][bj][m][n], 0, 0, 0); __builtin_amdgcn_s_setprio(0); } while (0)
; #define PG8_WAIT_V(n) asm volatile("s_waitcnt vmcnt(" #n ")" ::: "memory")
; #define PG8_WAIT_L(n) asm volatile("s_waitcnt lgkmcnt(" #n ")" ::: "memory")
; #define PG8_BAR __builtin_amdgcn_s_barrier()
; #define PG8_SCHED __builtin_amdgcn_sched_barrier(0)
; template <class Epi, class Sched>
; __device__ __forceinline__ void gemm_phase(LAS unsigned char* lds, const Gemm g, const Sched& S, const Epi& E) {
;     ...
;             PG8_STAGE(PG8_SB(0, 1), b2 + hstep, voffB);
;             PG8_WAIT_V(6); PG8_BAR; PG8_MMA(1, 1, At, B1); PG8_BAR;
;             PG8_LDB(B0, 1, 0); PG8_SCHED; PG8_LDA(At, 1, 0); PG8_STAGE(PG8_SA(0, 1), a2 + hstep, voffA);
;             PG8_WAIT_L(8); PG8_BAR; PG8_WAIT_L(0); PG8_MMA(0, 0, At, B0); PG8_BAR; PG8_SCHED;
	s_add_u32 s28, s52, 0x200000
	s_addc_u32 s29, s53, 0
	s_add_i32 s38, s39, s60
	v_lshl_add_u64 v[66:67], s[28:29], 0, v[0:1]
	s_mov_b32 m0, s38
	s_nop 0
	global_load_lds_dwordx4 v[66:67], off
	v_lshl_add_u64 v[66:67], s[28:29], 0, v[146:147]
	s_add_i32 m0, s38, 0x2000
	s_nop 0
	global_load_lds_dwordx4 v[66:67], off
	s_add_u32 s28, s54, 0x200000
	s_addc_u32 s29, s55, 0
	s_mov_b32 m0, s62
	v_lshl_add_u64 v[194:195], s[28:29], 0, v[0:1]
	global_load_lds_dwordx4 v[194:195], off
	v_lshl_add_u64 v[194:195], s[28:29], 0, v[146:147]
	s_mov_b32 m0, s63
	s_nop 0
	global_load_lds_dwordx4 v[194:195], off
	s_add_i32 s38, 0, 0x18000
	v_add_u32_e32 v78, s38, v163
	ds_read_b128 v[66:69], v78
	ds_read_b128 v[70:73], v78 offset:1024
	ds_read_b128 v[74:77], v78 offset:2048
	ds_read_b128 v[78:81], v78 offset:3072
	ds_read_b128 v[152:155], v165 offset:32768
	ds_read_b128 v[166:169], v165 offset:33792
	ds_read_b128 v[170:173], v165 offset:34816
	ds_read_b128 v[174:177], v165 offset:35840
	ds_read_b128 v[178:181], v165 offset:36864
	ds_read_b128 v[182:185], v165 offset:37888
	ds_read_b128 v[186:189], v165 offset:38912
	ds_read_b128 v[190:193], v165 offset:39936
	s_add_i32 s39, 0, 0x1c000
	v_add_u32_e32 v210, s39, v163
	ds_read_b128 v[194:197], v210
	ds_read_b128 v[198:201], v210 offset:1024
	ds_read_b128 v[202:205], v210 offset:2048
	ds_read_b128 v[210:213], v210 offset:3072
	s_waitcnt lgkmcnt(4)
	s_barrier
	s_waitcnt lgkmcnt(0)
	v_mfma_f32_16x16x32_bf16 v[142:145], v[66:69], v[152:155], v[142:145]
	v_mfma_f32_16x16x32_bf16 v[138:141], v[74:77], v[152:155], v[138:141]
	v_mfma_f32_16x16x32_bf16 v[126:129], v[66:69], v[170:173], v[126:129]
	v_mfma_f32_16x16x32_bf16 v[122:125], v[74:77], v[170:173], v[122:125]
	v_mfma_f32_16x16x32_bf16 v[110:113], v[66:69], v[178:181], v[110:113]
	v_mfma_f32_16x16x32_bf16 v[106:109], v[74:77], v[178:181], v[106:109]
	v_mfma_f32_16x16x32_bf16 v[102:105], v[66:69], v[186:189], v[102:105]
	v_mfma_f32_16x16x32_bf16 v[98:101], v[74:77], v[186:189], v[98:101]
	v_mfma_f32_16x16x32_bf16 v[142:145], v[70:73], v[166:169], v[142:145]
	v_mfma_f32_16x16x32_bf16 v[138:141], v[78:81], v[166:169], v[138:141]
	v_mfma_f32_16x16x32_bf16 v[126:129], v[70:73], v[174:177], v[126:129]
	v_mfma_f32_16x16x32_bf16 v[122:125], v[78:81], v[174:177], v[122:125]
	v_mfma_f32_16x16x32_bf16 v[110:113], v[70:73], v[182:185], v[110:113]
	v_mfma_f32_16x16x32_bf16 v[106:109], v[78:81], v[182:185], v[106:109]
	v_mfma_f32_16x16x32_bf16 v[102:105], v[70:73], v[190:193], v[102:105]
	v_mfma_f32_16x16x32_bf16 v[98:101], v[78:81], v[190:193], v[98:101]
	v_mfma_f32_16x16x32_bf16 v[134:137], v[194:197], v[152:155], v[134:137]
	v_mfma_f32_16x16x32_bf16 v[130:133], v[202:205], v[152:155], v[130:133]
	v_mfma_f32_16x16x32_bf16 v[118:121], v[194:197], v[170:173], v[118:121]
	v_mfma_f32_16x16x32_bf16 v[114:117], v[202:205], v[170:173], v[114:117]
	v_mfma_f32_16x16x32_bf16 v[94:97], v[194:197], v[178:181], v[94:97]
	v_mfma_f32_16x16x32_bf16 v[90:93], v[202:205], v[178:181], v[90:93]
	v_mfma_f32_16x16x32_bf16 v[86:89], v[194:197], v[186:189], v[86:89]
	v_mfma_f32_16x16x32_bf16 v[82:85], v[202:205], v[186:189], v[82:85]
	v_mfma_f32_16x16x32_bf16 v[134:137], v[198:201], v[166:169], v[134:137]
	v_mfma_f32_16x16x32_bf16 v[130:133], v[210:213], v[166:169], v[130:133]
	v_mfma_f32_16x16x32_bf16 v[118:121], v[198:201], v[174:177], v[118:121]
	v_mfma_f32_16x16x32_bf16 v[114:117], v[210:213], v[174:177], v[114:117]
	v_mfma_f32_16x16x32_bf16 v[94:97], v[198:201], v[182:185], v[94:97]
	v_mfma_f32_16x16x32_bf16 v[90:93], v[210:213], v[182:185], v[90:93]
	v_mfma_f32_16x16x32_bf16 v[86:89], v[198:201], v[190:193], v[86:89]
	v_mfma_f32_16x16x32_bf16 v[82:85], v[210:213], v[190:193], v[82:85]
	s_barrier
; #define PG8_STAGE(bufoff, gbase, voff) do { _Pragma("unroll") for (int _i = 0; _i < 2; ++_i) \
;         __builtin_amdgcn_global_load_lds((const unsigned*)((const char*)(gbase) + (voff)[_i]), (LAS unsigned*)(lds + (bufoff) + ldsw + _i * 8192), 16, 0, 0); } while (0)
; #define PG8_LDA(dst, b, h) do { _Pragma("unroll") for (int m = 0; m < 4; ++m) _Pragma("unroll") for (int k = 0; k < 2; ++k) dst[m][k] = *(const LAS bf16x8*)(lds + PG8_SA(b, h) + aoff + m * 2048 + k * 1024); } while (0)
; #define PG8_LDB(dst, b, h) do { _Pragma("unroll") for (int n = 0; n < 2; ++n) _Pragma("unroll") for (int k = 0; k < 2; ++k) dst[n][k] = *(const LAS bf16x8*)(lds + PG8_SB(b, h) + boff + n * 2048 + k * 1024); } while (0)
; #define PG8_MMA(ai, bj, At, Bt) do { __builtin_amdgcn_s_setprio(1); _Pragma("unroll") for (int m = 0; m < 4; ++m) _Pragma("unroll") for (int n = 0; n < 2; ++n) _Pragma("unroll") for (int k = 0; k < 2; ++k) \
;         acc[ai][bj][m][n] = __builtin_amdgcn_mfma_f32_16x16x32_bf16(Bt[n][k], At[m][k], acc[ai][bj][m][n], 0, 0, 0); __builtin_amdgcn_s_setprio(0); } while (0)
; #define PG8_WAIT_V(n) asm volatile("s_waitcnt vmcnt(" #n ")" ::: "memory")
; #define PG8_WAIT_L(n) asm volatile("s_waitcnt lgkmcnt(" #n ")" ::: "memory")
; #define PG8_BAR __builtin_amdgcn_s_barrier()
; #define PG8_SCHED __builtin_amdgcn_sched_barrier(0)
; template <class Epi, class Sched>
; __device__ __forceinline__ void gemm_phase(LAS unsigned char* lds, const Gemm g, const Sched& S, const Epi& E) {
;     ...
;             PG8_LDB(B0, 1, 0); PG8_SCHED; PG8_LDA(At, 1, 0); PG8_STAGE(PG8_SA(0, 1), a2 + hstep, voffA);
;             PG8_WAIT_L(8); PG8_BAR; PG8_WAIT_L(0); PG8_MMA(0, 0, At, B0); PG8_BAR; PG8_SCHED;
;             PG8_LDB(B1, 1, 1); PG8_STAGE(PG8_SB(1, 0), b3, voffB);
;             PG8_BAR; PG8_WAIT_L(0); PG8_MMA(0, 1, At, B1); PG8_BAR;
;             PG8_LDA(At, 1, 1); PG8_STAGE(PG8_SA(1, 0), a3, voffA);
;             PG8_BAR; PG8_WAIT_L(0); PG8_MMA(1, 0, At, B0); PG8_BAR; PG8_SCHED;
;             PG8_STAGE(PG8_SB(1, 1), b3 + hstep, voffB);
;             PG8_WAIT_V(6); PG8_BAR; PG8_MMA(1, 1, At, B1); PG8_BAR;
	s_add_i32 s28, s38, s60
	v_lshl_add_u64 v[156:157], v[156:157], 0, s[36:37]
	s_mov_b32 m0, s28
	s_nop 0
	global_load_lds_dwordx4 v[156:157], off
	v_lshl_add_u64 v[156:157], v[160:161], 0, s[36:37]
	s_add_i32 m0, s28, 0x2000
	s_nop 0
	global_load_lds_dwordx4 v[156:157], off
	s_mov_b32 m0, s66
	v_lshl_add_u64 v[156:157], v[206:207], 0, s[36:37]
	global_load_lds_dwordx4 v[156:157], off
	v_lshl_add_u64 v[156:157], v[214:215], 0, s[36:37]
	s_mov_b32 m0, s67
	s_nop 0
	global_load_lds_dwordx4 v[156:157], off
	ds_read_b128 v[152:155], v165 offset:49152
	ds_read_b128 v[166:169], v165 offset:50176
	ds_read_b128 v[170:173], v165 offset:51200
	ds_read_b128 v[174:177], v165 offset:52224
	ds_read_b128 v[178:181], v165 offset:53248
	ds_read_b128 v[182:185], v165 offset:54272
	ds_read_b128 v[186:189], v165 offset:55296
	ds_read_b128 v[190:193], v165 offset:56320
	s_waitcnt vmcnt(4)
	s_waitcnt lgkmcnt(0)
	s_barrier
	v_mfma_f32_16x16x32_bf16 v[62:65], v[66:69], v[152:155], v[62:65]
	v_mfma_f32_16x16x32_bf16 v[58:61], v[74:77], v[152:155], v[58:61]
	v_mfma_f32_16x16x32_bf16 v[46:49], v[66:69], v[170:173], v[46:49]
	v_mfma_f32_16x16x32_bf16 v[42:45], v[74:77], v[170:173], v[42:45]
	v_mfma_f32_16x16x32_bf16 v[30:33], v[66:69], v[178:181], v[30:33]
	v_mfma_f32_16x16x32_bf16 v[26:29], v[74:77], v[178:181], v[26:29]
	v_mfma_f32_16x16x32_bf16 v[22:25], v[66:69], v[186:189], v[22:25]
	v_mfma_f32_16x16x32_bf16 v[14:17], v[74:77], v[186:189], v[14:17]
	v_mfma_f32_16x16x32_bf16 v[62:65], v[70:73], v[166:169], v[62:65]
	v_mfma_f32_16x16x32_bf16 v[58:61], v[78:81], v[166:169], v[58:61]
	v_mfma_f32_16x16x32_bf16 v[46:49], v[70:73], v[174:177], v[46:49]
	v_mfma_f32_16x16x32_bf16 v[42:45], v[78:81], v[174:177], v[42:45]
	v_mfma_f32_16x16x32_bf16 v[30:33], v[70:73], v[182:185], v[30:33]
	v_mfma_f32_16x16x32_bf16 v[26:29], v[78:81], v[182:185], v[26:29]
	v_mfma_f32_16x16x32_bf16 v[22:25], v[70:73], v[190:193], v[22:25]
	v_mfma_f32_16x16x32_bf16 v[14:17], v[78:81], v[190:193], v[14:17]
	s_add_u32 s28, s52, 0x200080
	s_addc_u32 s29, s53, 0
	s_add_i32 s38, s39, s60
	v_lshl_add_u64 v[66:67], s[28:29], 0, v[0:1]
	s_mov_b32 m0, s38
	s_nop 0
	global_load_lds_dwordx4 v[66:67], off
	v_lshl_add_u64 v[66:67], s[28:29], 0, v[146:147]
	s_add_i32 m0, s38, 0x2000
	s_nop 0
	global_load_lds_dwordx4 v[66:67], off
	v_mfma_f32_16x16x32_bf16 v[54:57], v[194:197], v[152:155], v[54:57]
	v_mfma_f32_16x16x32_bf16 v[50:53], v[202:205], v[152:155], v[50:53]
	v_mfma_f32_16x16x32_bf16 v[38:41], v[194:197], v[170:173], v[38:41]
	v_mfma_f32_16x16x32_bf16 v[34:37], v[202:205], v[170:173], v[34:37]
	v_mfma_f32_16x16x32_bf16 v[18:21], v[194:197], v[178:181], v[18:21]
	v_mfma_f32_16x16x32_bf16 v[10:13], v[202:205], v[178:181], v[10:13]
	v_mfma_f32_16x16x32_bf16 v[6:9], v[194:197], v[186:189], v[6:9]
	v_mfma_f32_16x16x32_bf16 v[2:5], v[202:205], v[186:189], v[2:5]
	v_mfma_f32_16x16x32_bf16 v[54:57], v[198:201], v[166:169], v[54:57]
	v_mfma_f32_16x16x32_bf16 v[50:53], v[210:213], v[166:169], v[50:53]
	v_mfma_f32_16x16x32_bf16 v[38:41], v[198:201], v[174:177], v[38:41]
	v_mfma_f32_16x16x32_bf16 v[34:37], v[210:213], v[174:177], v[34:37]
	v_mfma_f32_16x16x32_bf16 v[18:21], v[198:201], v[182:185], v[18:21]
	v_mfma_f32_16x16x32_bf16 v[10:13], v[210:213], v[182:185], v[10:13]
	v_mfma_f32_16x16x32_bf16 v[6:9], v[198:201], v[190:193], v[6:9]
	v_mfma_f32_16x16x32_bf16 v[2:5], v[210:213], v[190:193], v[2:5]
	s_add_i32 s75, s75, 2
	s_add_u32 s73, s73, 0x100
	s_addc_u32 s74, s74, 0
	s_cmpk_gt_u32 s75, 0x7d
	s_mov_b64 s[28:29], s[50:51]
	s_barrier
	s_cbranch_scc0 .LBB0_44
	s_cmp_lt_i32 s8, 64
	s_cselect_b64 s[50:51], -1, 0
	s_cmp_gt_i32 s8, 63
	s_cbranch_scc0 .LBB0_35
	s_mov_b64 s[52:53], 0x18000
	s_mov_b64 s[28:29], s[46:47]
	s_branch .LBB0_36

; #define PG8_STAGE(bufoff, gbase, voff) do { _Pragma("unroll") for (int _i = 0; _i < 2; ++_i) \
;         __builtin_amdgcn_global_load_lds((const unsigned*)((const char*)(gbase) + (voff)[_i]), (LAS unsigned*)(lds + (bufoff) + ldsw + _i * 8192), 16, 0, 0); } while (0)
; #define PG8_LDA(dst, b, h) do { _Pragma("unroll") for (int m = 0; m < 4; ++m) _Pragma("unroll") for (int k = 0; k < 2; ++k) dst[m][k] = *(const LAS bf16x8*)(lds + PG8_SA(b, h) + aoff + m * 2048 + k * 1024); } while (0)
; #define PG8_LDB(dst, b, h) do { _Pragma("unroll") for (int n = 0; n < 2; ++n) _Pragma("unroll") for (int k = 0; k < 2; ++k) dst[n][k] = *(const LAS bf16x8*)(lds + PG8_SB(b, h) + boff + n * 2048 + k * 1024); } while (0)
; #define PG8_MMA(ai, bj, At, Bt) do { __builtin_amdgcn_s_setprio(1); _Pragma("unroll") for (int m = 0; m < 4; ++m) _Pragma("unroll") for (int n = 0; n < 2; ++n) _Pragma("unroll") for (int k = 0; k < 2; ++k) \
;         acc[ai][bj][m][n] = __builtin_amdgcn_mfma_f32_16x16x32_bf16(Bt[n][k], At[m][k], acc[ai][bj][m][n], 0, 0, 0); __builtin_amdgcn_s_setprio(0); } while (0)
; #define PG8_WAIT_L(n) asm volatile("s_waitcnt lgkmcnt(" #n ")" ::: "memory")
; #define PG8_BAR __builtin_amdgcn_s_barrier()
; #define PG8_SCHED __builtin_amdgcn_sched_barrier(0)
; template <class Epi, class Sched>
; __device__ __forceinline__ void gemm_phase(LAS unsigned char* lds, const Gemm g, const Sched& S, const Epi& E) {
;     ...
;         for (int t = 0; t < nt; t += 2) {
;             const bool last = (t == nt - 2);
;             const char* a1 = cA + (size_t)(t + 1) * kstep;
;             const char* a2 = last ? nA : cA + (size_t)(t + 2) * kstep; const char* b2 = last ? nB : cB + (size_t)(t + 2) * kstep;
;             const char* a3 = a2 + kstep; const char* b3 = b2 + kstep;
;             PG8_LDB(B0, 0, 0); PG8_SCHED; PG8_LDA(At, 0, 0); PG8_STAGE(PG8_SA(1, 1), a1 + hstep, voffA);
;             PG8_WAIT_L(8); PG8_BAR; PG8_WAIT_L(0); PG8_MMA(0, 0, At, B0); PG8_BAR; PG8_SCHED;
;             PG8_LDB(B1, 0, 1); PG8_STAGE(PG8_SB(0, 0), b2, voffB);
;             PG8_BAR; PG8_WAIT_L(0); PG8_MMA(0, 1, At, B1); PG8_BAR;
;             PG8_LDA(At, 0, 1); PG8_STAGE(PG8_SA(0, 0), a2, voffA);
;             PG8_BAR; PG8_WAIT_L(0); PG8_MMA(1, 0, At, B0); PG8_BAR; PG8_SCHED;
.LBB0_58:
	s_add_u32 s52, s50, 0x100
	s_addc_u32 s53, s51, 0
	s_cmp_eq_u32 s71, 28
	s_cselect_b32 s57, s11, s53
	s_cselect_b32 s56, s29, s52
	s_cselect_b32 s55, s41, s70
	s_cselect_b32 s54, s43, s69
	v_lshl_add_u64 v[156:157], s[50:51], 0, v[134:135]
	s_add_i32 m0, s25, 0xc000
	s_nop 0
	global_load_lds_dwordx4 v[156:157], off
	v_lshl_add_u64 v[156:157], s[50:51], 0, v[132:133]
	s_add_i32 m0, s25, 0xe000
	s_nop 0
	global_load_lds_dwordx4 v[156:157], off
	s_add_i32 s38, 0, 0x10000
	v_add_u32_e32 v152, s38, v137
	ds_read_b128 v[140:143], v152
	ds_read_b128 v[144:147], v152 offset:1024
	ds_read_b128 v[148:151], v152 offset:2048
	ds_read_b128 v[152:155], v152 offset:3072
	ds_read_b128 v[160:163], v139
	ds_read_b128 v[164:167], v139 offset:1024
	ds_read_b128 v[168:171], v139 offset:2048
	ds_read_b128 v[172:175], v139 offset:3072
	ds_read_b128 v[176:179], v139 offset:4096
	ds_read_b128 v[180:183], v139 offset:5120
	ds_read_b128 v[184:187], v139 offset:6144
	ds_read_b128 v[188:191], v139 offset:7168
	s_add_i32 s50, 0, 0x14000
	v_add_u32_e32 v156, s50, v137
	ds_read_b128 v[192:195], v156
	ds_read_b128 v[196:199], v156 offset:1024
	ds_read_b128 v[200:203], v156 offset:2048
	ds_read_b128 v[204:207], v156 offset:3072
	s_waitcnt lgkmcnt(4)
	s_barrier
	s_waitcnt lgkmcnt(0)
	v_mfma_f32_16x16x32_bf16 v[126:129], v[140:143], v[160:163], v[126:129]
	v_mfma_f32_16x16x32_bf16 v[122:125], v[148:151], v[160:163], v[122:125]
	v_mfma_f32_16x16x32_bf16 v[118:121], v[140:143], v[168:171], v[118:121]
	v_mfma_f32_16x16x32_bf16 v[114:117], v[148:151], v[168:171], v[114:117]
	v_mfma_f32_16x16x32_bf16 v[106:109], v[140:143], v[176:179], v[106:109]
	v_mfma_f32_16x16x32_bf16 v[98:101], v[148:151], v[176:179], v[98:101]
	v_mfma_f32_16x16x32_bf16 v[90:93], v[140:143], v[184:187], v[90:93]
	v_mfma_f32_16x16x32_bf16 v[82:85], v[148:151], v[184:187], v[82:85]
	v_mfma_f32_16x16x32_bf16 v[126:129], v[144:147], v[164:167], v[126:129]
	v_mfma_f32_16x16x32_bf16 v[122:125], v[152:155], v[164:167], v[122:125]
	v_mfma_f32_16x16x32_bf16 v[118:121], v[144:147], v[172:175], v[118:121]
	v_mfma_f32_16x16x32_bf16 v[114:117], v[152:155], v[172:175], v[114:117]
	v_mfma_f32_16x16x32_bf16 v[106:109], v[144:147], v[180:183], v[106:109]
	v_mfma_f32_16x16x32_bf16 v[98:101], v[152:155], v[180:183], v[98:101]
	v_mfma_f32_16x16x32_bf16 v[90:93], v[144:147], v[188:191], v[90:93]
	v_mfma_f32_16x16x32_bf16 v[82:85], v[152:155], v[188:191], v[82:85]
	v_mfma_f32_16x16x32_bf16 v[110:113], v[192:195], v[160:163], v[110:113]
	v_mfma_f32_16x16x32_bf16 v[102:105], v[200:203], v[160:163], v[102:105]
	v_mfma_f32_16x16x32_bf16 v[94:97], v[192:195], v[168:171], v[94:97]
	v_mfma_f32_16x16x32_bf16 v[86:89], v[200:203], v[168:171], v[86:89]
	v_mfma_f32_16x16x32_bf16 v[78:81], v[192:195], v[176:179], v[78:81]
	v_mfma_f32_16x16x32_bf16 v[74:77], v[200:203], v[176:179], v[74:77]
	v_mfma_f32_16x16x32_bf16 v[70:73], v[192:195], v[184:187], v[70:73]
	v_mfma_f32_16x16x32_bf16 v[66:69], v[200:203], v[184:187], v[66:69]
	v_mfma_f32_16x16x32_bf16 v[110:113], v[196:199], v[164:167], v[110:113]
	v_mfma_f32_16x16x32_bf16 v[102:105], v[204:207], v[164:167], v[102:105]
	v_mfma_f32_16x16x32_bf16 v[94:97], v[196:199], v[172:175], v[94:97]
	v_mfma_f32_16x16x32_bf16 v[86:89], v[204:207], v[172:175], v[86:89]
	v_mfma_f32_16x16x32_bf16 v[78:81], v[196:199], v[180:183], v[78:81]
	v_mfma_f32_16x16x32_bf16 v[74:77], v[204:207], v[180:183], v[74:77]
	v_mfma_f32_16x16x32_bf16 v[70:73], v[196:199], v[188:191], v[70:73]
	v_mfma_f32_16x16x32_bf16 v[66:69], v[204:207], v[188:191], v[66:69]
	s_barrier
	s_add_i32 s38, s38, s63
	v_lshl_add_u64 v[156:157], s[54:55], 0, v[0:1]
	s_mov_b32 m0, s38
	v_lshl_add_u64 v[210:211], s[54:55], 0, v[130:131]
	global_load_lds_dwordx4 v[156:157], off
	s_add_i32 m0, s38, 0x2000
	s_nop 0
	global_load_lds_dwordx4 v[210:211], off
	s_mov_b32 m0, s25
	v_lshl_add_u64 v[212:213], s[56:57], 0, v[0:1]
	global_load_lds_dwordx4 v[212:213], off
	v_lshl_add_u64 v[214:215], s[56:57], 0, v[130:131]
	s_mov_b32 m0, s27
	s_nop 0
	global_load_lds_dwordx4 v[214:215], off
	ds_read_b128 v[160:163], v139 offset:16384
	ds_read_b128 v[164:167], v139 offset:17408
	ds_read_b128 v[168:171], v139 offset:18432
	ds_read_b128 v[172:175], v139 offset:19456
	ds_read_b128 v[176:179], v139 offset:20480
	ds_read_b128 v[180:183], v139 offset:21504
	ds_read_b128 v[184:187], v139 offset:22528
	ds_read_b128 v[188:191], v139 offset:23552
	s_waitcnt vmcnt(4)
	s_waitcnt lgkmcnt(0)
	s_barrier
	v_mfma_f32_16x16x32_bf16 v[62:65], v[140:143], v[160:163], v[62:65]
	v_mfma_f32_16x16x32_bf16 v[58:61], v[148:151], v[160:163], v[58:61]
	v_mfma_f32_16x16x32_bf16 v[54:57], v[140:143], v[168:171], v[54:57]
	v_mfma_f32_16x16x32_bf16 v[50:53], v[148:151], v[168:171], v[50:53]
	v_mfma_f32_16x16x32_bf16 v[38:41], v[140:143], v[176:179], v[38:41]
	v_mfma_f32_16x16x32_bf16 v[34:37], v[148:151], v[176:179], v[34:37]
	v_mfma_f32_16x16x32_bf16 v[22:25], v[140:143], v[184:187], v[22:25]
	v_mfma_f32_16x16x32_bf16 v[18:21], v[148:151], v[184:187], v[18:21]
	v_mfma_f32_16x16x32_bf16 v[62:65], v[144:147], v[164:167], v[62:65]
	v_mfma_f32_16x16x32_bf16 v[58:61], v[152:155], v[164:167], v[58:61]
	v_mfma_f32_16x16x32_bf16 v[54:57], v[144:147], v[172:175], v[54:57]
	v_mfma_f32_16x16x32_bf16 v[50:53], v[152:155], v[172:175], v[50:53]
	v_mfma_f32_16x16x32_bf16 v[38:41], v[144:147], v[180:183], v[38:41]
	v_mfma_f32_16x16x32_bf16 v[34:37], v[152:155], v[180:183], v[34:37]
	v_mfma_f32_16x16x32_bf16 v[22:25], v[144:147], v[188:191], v[22:25]
	v_mfma_f32_16x16x32_bf16 v[18:21], v[152:155], v[188:191], v[18:21]
	v_mfma_f32_16x16x32_bf16 v[46:49], v[192:195], v[160:163], v[46:49]
	v_mfma_f32_16x16x32_bf16 v[42:45], v[200:203], v[160:163], v[42:45]
	v_mfma_f32_16x16x32_bf16 v[30:33], v[192:195], v[168:171], v[30:33]
	v_mfma_f32_16x16x32_bf16 v[26:29], v[200:203], v[168:171], v[26:29]
	v_mfma_f32_16x16x32_bf16 v[14:17], v[192:195], v[176:179], v[14:17]
	v_mfma_f32_16x16x32_bf16 v[10:13], v[200:203], v[176:179], v[10:13]
	v_mfma_f32_16x16x32_bf16 v[6:9], v[192:195], v[184:187], v[6:9]
	v_mfma_f32_16x16x32_bf16 v[2:5], v[200:203], v[184:187], v[2:5]
	v_mfma_f32_16x16x32_bf16 v[46:49], v[196:199], v[164:167], v[46:49]
	v_mfma_f32_16x16x32_bf16 v[42:45], v[204:207], v[164:167], v[42:45]
	v_mfma_f32_16x16x32_bf16 v[30:33], v[196:199], v[172:175], v[30:33]
	v_mfma_f32_16x16x32_bf16 v[26:29], v[204:207], v[172:175], v[26:29]
	v_mfma_f32_16x16x32_bf16 v[14:17], v[196:199], v[180:183], v[14:17]
	v_mfma_f32_16x16x32_bf16 v[10:13], v[204:207], v[180:183], v[10:13]
	v_mfma_f32_16x16x32_bf16 v[6:9], v[196:199], v[188:191], v[6:9]
	v_mfma_f32_16x16x32_bf16 v[2:5], v[204:207], v[188:191], v[2:5]
	s_barrier
; #define PG8_STAGE(bufoff, gbase, voff) do { _Pragma("unroll") for (int _i = 0; _i < 2; ++_i) \
;         __builtin_amdgcn_global_load_lds((const unsigned*)((const char*)(gbase) + (voff)[_i]), (LAS unsigned*)(lds + (bufoff) + ldsw + _i * 8192), 16, 0, 0); } while (0)
; #define PG8_LDA(dst, b, h) do { _Pragma("unroll") for (int m = 0; m < 4; ++m) _Pragma("unroll") for (int k = 0; k < 2; ++k) dst[m][k] = *(const LAS bf16x8*)(lds + PG8_SA(b, h) + aoff + m * 2048 + k * 1024); } while (0)
; #define PG8_LDB(dst, b, h) do { _Pragma("unroll") for (int n = 0; n < 2; ++n) _Pragma("unroll") for (int k = 0; k < 2; ++k) dst[n][k] = *(const LAS bf16x8*)(lds + PG8_SB(b, h) + boff + n * 2048 + k * 1024); } while (0)
; #define PG8_MMA(ai, bj, At, Bt) do { __builtin_amdgcn_s_setprio(1); _Pragma("unroll") for (int m = 0; m < 4; ++m) _Pragma("unroll") for (int n = 0; n < 2; ++n) _Pragma("unroll") for (int k = 0; k < 2; ++k) \
;         acc[ai][bj][m][n] = __builtin_amdgcn_mfma_f32_16x16x32_bf16(Bt[n][k], At[m][k], acc[ai][bj][m][n], 0, 0, 0); __builtin_amdgcn_s_setprio(0); } while (0)
; #define PG8_WAIT_V(n) asm volatile("s_waitcnt vmcnt(" #n ")" ::: "memory")
; #define PG8_WAIT_L(n) asm volatile("s_waitcnt lgkmcnt(" #n ")" ::: "memory")
; #define PG8_BAR __builtin_amdgcn_s_barrier()
; #define PG8_SCHED __builtin_amdgcn_sched_barrier(0)
; template <class Epi, class Sched>
; __device__ __forceinline__ void gemm_phase(LAS unsigned char* lds, const Gemm g, const Sched& S, const Epi& E) {
;     ...
;             PG8_STAGE(PG8_SB(0, 1), b2 + hstep, voffB);
;             PG8_WAIT_V(6); PG8_BAR; PG8_MMA(1, 1, At, B1); PG8_BAR;
;             PG8_LDB(B0, 1, 0); PG8_SCHED; PG8_LDA(At, 1, 0); PG8_STAGE(PG8_SA(0, 1), a2 + hstep, voffA);
;             PG8_WAIT_L(8); PG8_BAR; PG8_WAIT_L(0); PG8_MMA(0, 0, At, B0); PG8_BAR; PG8_SCHED;
	s_add_u32 s38, s54, 0x200000
	s_addc_u32 s39, s55, 0
	s_add_i32 s50, s50, s63
	v_lshl_add_u64 v[140:141], s[38:39], 0, v[0:1]
	s_mov_b32 m0, s50
	s_nop 0
	global_load_lds_dwordx4 v[140:141], off
	v_lshl_add_u64 v[140:141], s[38:39], 0, v[130:131]
	s_add_i32 m0, s50, 0x2000
	s_nop 0
	global_load_lds_dwordx4 v[140:141], off
	s_add_u32 s38, s56, 0x200000
	s_addc_u32 s39, s57, 0
	s_mov_b32 m0, s64
	v_lshl_add_u64 v[192:193], s[38:39], 0, v[0:1]
	global_load_lds_dwordx4 v[192:193], off
	v_lshl_add_u64 v[192:193], s[38:39], 0, v[130:131]
	s_mov_b32 m0, s65
	s_nop 0
	global_load_lds_dwordx4 v[192:193], off
	s_add_i32 s50, 0, 0x18000
	v_add_u32_e32 v152, s50, v137
	ds_read_b128 v[140:143], v152
	ds_read_b128 v[144:147], v152 offset:1024
	ds_read_b128 v[148:151], v152 offset:2048
	ds_read_b128 v[152:155], v152 offset:3072
	ds_read_b128 v[160:163], v139 offset:32768
	ds_read_b128 v[164:167], v139 offset:33792
	ds_read_b128 v[168:171], v139 offset:34816
	ds_read_b128 v[172:175], v139 offset:35840
	ds_read_b128 v[176:179], v139 offset:36864
	ds_read_b128 v[180:183], v139 offset:37888
	ds_read_b128 v[184:187], v139 offset:38912
	ds_read_b128 v[188:191], v139 offset:39936
	s_add_i32 s51, 0, 0x1c000
	v_add_u32_e32 v204, s51, v137
	ds_read_b128 v[192:195], v204
	ds_read_b128 v[196:199], v204 offset:1024
	ds_read_b128 v[200:203], v204 offset:2048
	ds_read_b128 v[204:207], v204 offset:3072
	s_waitcnt lgkmcnt(4)
	s_barrier
	s_waitcnt lgkmcnt(0)
	v_mfma_f32_16x16x32_bf16 v[126:129], v[140:143], v[160:163], v[126:129]
	v_mfma_f32_16x16x32_bf16 v[122:125], v[148:151], v[160:163], v[122:125]
	v_mfma_f32_16x16x32_bf16 v[118:121], v[140:143], v[168:171], v[118:121]
	v_mfma_f32_16x16x32_bf16 v[114:117], v[148:151], v[168:171], v[114:117]
	v_mfma_f32_16x16x32_bf16 v[106:109], v[140:143], v[176:179], v[106:109]
	v_mfma_f32_16x16x32_bf16 v[98:101], v[148:151], v[176:179], v[98:101]
	v_mfma_f32_16x16x32_bf16 v[90:93], v[140:143], v[184:187], v[90:93]
	v_mfma_f32_16x16x32_bf16 v[82:85], v[148:151], v[184:187], v[82:85]
	v_mfma_f32_16x16x32_bf16 v[126:129], v[144:147], v[164:167], v[126:129]
	v_mfma_f32_16x16x32_bf16 v[122:125], v[152:155], v[164:167], v[122:125]
	v_mfma_f32_16x16x32_bf16 v[118:121], v[144:147], v[172:175], v[118:121]
	v_mfma_f32_16x16x32_bf16 v[114:117], v[152:155], v[172:175], v[114:117]
	v_mfma_f32_16x16x32_bf16 v[106:109], v[144:147], v[180:183], v[106:109]
	v_mfma_f32_16x16x32_bf16 v[98:101], v[152:155], v[180:183], v[98:101]
	v_mfma_f32_16x16x32_bf16 v[90:93], v[144:147], v[188:191], v[90:93]
	v_mfma_f32_16x16x32_bf16 v[82:85], v[152:155], v[188:191], v[82:85]
	v_mfma_f32_16x16x32_bf16 v[110:113], v[192:195], v[160:163], v[110:113]
	v_mfma_f32_16x16x32_bf16 v[102:105], v[200:203], v[160:163], v[102:105]
	v_mfma_f32_16x16x32_bf16 v[94:97], v[192:195], v[168:171], v[94:97]
	v_mfma_f32_16x16x32_bf16 v[86:89], v[200:203], v[168:171], v[86:89]
	v_mfma_f32_16x16x32_bf16 v[78:81], v[192:195], v[176:179], v[78:81]
	v_mfma_f32_16x16x32_bf16 v[74:77], v[200:203], v[176:179], v[74:77]
	v_mfma_f32_16x16x32_bf16 v[70:73], v[192:195], v[184:187], v[70:73]
	v_mfma_f32_16x16x32_bf16 v[66:69], v[200:203], v[184:187], v[66:69]
	v_mfma_f32_16x16x32_bf16 v[110:113], v[196:199], v[164:167], v[110:113]
	v_mfma_f32_16x16x32_bf16 v[102:105], v[204:207], v[164:167], v[102:105]
	v_mfma_f32_16x16x32_bf16 v[94:97], v[196:199], v[172:175], v[94:97]
	v_mfma_f32_16x16x32_bf16 v[86:89], v[204:207], v[172:175], v[86:89]
	v_mfma_f32_16x16x32_bf16 v[78:81], v[196:199], v[180:183], v[78:81]
	v_mfma_f32_16x16x32_bf16 v[74:77], v[204:207], v[180:183], v[74:77]
	v_mfma_f32_16x16x32_bf16 v[70:73], v[196:199], v[188:191], v[70:73]
	v_mfma_f32_16x16x32_bf16 v[66:69], v[204:207], v[188:191], v[66:69]
	s_barrier
	s_add_i32 s38, s50, s63
	v_lshl_add_u64 v[156:157], v[156:157], 0, s[36:37]
	s_mov_b32 m0, s38
	s_nop 0
	global_load_lds_dwordx4 v[156:157], off
	v_lshl_add_u64 v[156:157], v[210:211], 0, s[36:37]
	s_add_i32 m0, s38, 0x2000
	s_nop 0
	global_load_lds_dwordx4 v[156:157], off
	s_mov_b32 m0, s66
	v_lshl_add_u64 v[156:157], v[212:213], 0, s[36:37]
	global_load_lds_dwordx4 v[156:157], off
	v_lshl_add_u64 v[156:157], v[214:215], 0, s[36:37]
	s_mov_b32 m0, s67
	s_nop 0
	global_load_lds_dwordx4 v[156:157], off
	ds_read_b128 v[160:163], v139 offset:49152
	ds_read_b128 v[164:167], v139 offset:50176
	ds_read_b128 v[168:171], v139 offset:51200
	ds_read_b128 v[172:175], v139 offset:52224
	ds_read_b128 v[176:179], v139 offset:53248
	ds_read_b128 v[180:183], v139 offset:54272
	ds_read_b128 v[184:187], v139 offset:55296
	ds_read_b128 v[188:191], v139 offset:56320
	s_waitcnt vmcnt(4)
	s_waitcnt lgkmcnt(0)
	s_barrier
; #define PG8_STAGE(bufoff, gbase, voff) do { _Pragma("unroll") for (int _i = 0; _i < 2; ++_i) \
;         __builtin_amdgcn_global_load_lds((const unsigned*)((const char*)(gbase) + (voff)[_i]), (LAS unsigned*)(lds + (bufoff) + ldsw + _i * 8192), 16, 0, 0); } while (0)
; #define PG8_LDA(dst, b, h) do { _Pragma("unroll") for (int m = 0; m < 4; ++m) _Pragma("unroll") for (int k = 0; k < 2; ++k) dst[m][k] = *(const LAS bf16x8*)(lds + PG8_SA(b, h) + aoff + m * 2048 + k * 1024); } while (0)
; #define PG8_LDB(dst, b, h) do { _Pragma("unroll") for (int n = 0; n < 2; ++n) _Pragma("unroll") for (int k = 0; k < 2; ++k) dst[n][k] = *(const LAS bf16x8*)(lds + PG8_SB(b, h) + boff + n * 2048 + k * 1024); } while (0)
; #define PG8_MMA(ai, bj, At, Bt) do { __builtin_amdgcn_s_setprio(1); _Pragma("unroll") for (int m = 0; m < 4; ++m) _Pragma("unroll") for (int n = 0; n < 2; ++n) _Pragma("unroll") for (int k = 0; k < 2; ++k) \
;         acc[ai][bj][m][n] = __builtin_amdgcn_mfma_f32_16x16x32_bf16(Bt[n][k], At[m][k], acc[ai][bj][m][n], 0, 0, 0); __builtin_amdgcn_s_setprio(0); } while (0)
; #define PG8_BAR __builtin_amdgcn_s_barrier()
;     __device__ __forceinline__ void operator()(const f32x4 (&acc)[2][2][4][2], const Unit& u, int wr, int wc, int fr, int fq) const {
;         const int row0 = u.pm * BM + wr * 64 + fr, col0 = u.pn * BM + wc * 32 + 4 * fq;
;         float* base = part + (size_t)u.ks * Mp * ldc;
; #pragma unroll
;         for (int ai = 0; ai < 2; ++ai)
; #pragma unroll
;             for (int m = 0; m < 4; ++m) { float* rowp = base + (size_t)(row0 + ai * HALF + m * 16) * ldc + col0;
; #pragma unroll
;                 for (int bj = 0; bj < 2; ++bj)
; #pragma unroll
;                     for (int n = 0; n < 2; ++n) *(f32x4*)(rowp + bj * HALF + n * 16) = acc[ai][bj][m][n]; }
;     }
; template <class Epi, class Sched>
; __device__ __forceinline__ void gemm_phase(LAS unsigned char* lds, const Gemm g, const Sched& S, const Epi& E) {
;     ...
;             PG8_LDB(B1, 1, 1); PG8_STAGE(PG8_SB(1, 0), b3, voffB);
;             PG8_BAR; PG8_WAIT_L(0); PG8_MMA(0, 1, At, B1); PG8_BAR;
;             PG8_LDA(At, 1, 1); PG8_STAGE(PG8_SA(1, 0), a3, voffA);
;             PG8_BAR; PG8_WAIT_L(0); PG8_MMA(1, 0, At, B0); PG8_BAR; PG8_SCHED;
;             PG8_STAGE(PG8_SB(1, 1), b3 + hstep, voffB);
;             PG8_WAIT_V(6); PG8_BAR; PG8_MMA(1, 1, At, B1); PG8_BAR;
	v_mfma_f32_16x16x32_bf16 v[62:65], v[140:143], v[160:163], v[62:65]
	v_mfma_f32_16x16x32_bf16 v[58:61], v[148:151], v[160:163], v[58:61]
	v_mfma_f32_16x16x32_bf16 v[54:57], v[140:143], v[168:171], v[54:57]
	v_mfma_f32_16x16x32_bf16 v[50:53], v[148:151], v[168:171], v[50:53]
	v_mfma_f32_16x16x32_bf16 v[38:41], v[140:143], v[176:179], v[38:41]
	v_mfma_f32_16x16x32_bf16 v[34:37], v[148:151], v[176:179], v[34:37]
	v_mfma_f32_16x16x32_bf16 v[22:25], v[140:143], v[184:187], v[22:25]
	v_mfma_f32_16x16x32_bf16 v[18:21], v[148:151], v[184:187], v[18:21]
	v_mfma_f32_16x16x32_bf16 v[62:65], v[144:147], v[164:167], v[62:65]
	v_mfma_f32_16x16x32_bf16 v[58:61], v[152:155], v[164:167], v[58:61]
	v_mfma_f32_16x16x32_bf16 v[54:57], v[144:147], v[172:175], v[54:57]
	v_mfma_f32_16x16x32_bf16 v[50:53], v[152:155], v[172:175], v[50:53]
	v_mfma_f32_16x16x32_bf16 v[38:41], v[144:147], v[180:183], v[38:41]
	v_mfma_f32_16x16x32_bf16 v[34:37], v[152:155], v[180:183], v[34:37]
	v_mfma_f32_16x16x32_bf16 v[22:25], v[144:147], v[188:191], v[22:25]
	v_mfma_f32_16x16x32_bf16 v[18:21], v[152:155], v[188:191], v[18:21]
	s_add_u32 s38, s54, 0x200080
	s_addc_u32 s39, s55, 0
	s_add_i32 s50, s51, s63
	v_lshl_add_u64 v[140:141], s[38:39], 0, v[0:1]
	s_mov_b32 m0, s50
	s_nop 0
	global_load_lds_dwordx4 v[140:141], off
	v_lshl_add_u64 v[140:141], s[38:39], 0, v[130:131]
	s_add_i32 m0, s50, 0x2000
	s_nop 0
	global_load_lds_dwordx4 v[140:141], off
	v_mfma_f32_16x16x32_bf16 v[46:49], v[192:195], v[160:163], v[46:49]
	v_mfma_f32_16x16x32_bf16 v[42:45], v[200:203], v[160:163], v[42:45]
	v_mfma_f32_16x16x32_bf16 v[30:33], v[192:195], v[168:171], v[30:33]
	v_mfma_f32_16x16x32_bf16 v[26:29], v[200:203], v[168:171], v[26:29]
	v_mfma_f32_16x16x32_bf16 v[14:17], v[192:195], v[176:179], v[14:17]
	v_mfma_f32_16x16x32_bf16 v[10:13], v[200:203], v[176:179], v[10:13]
	v_mfma_f32_16x16x32_bf16 v[6:9], v[192:195], v[184:187], v[6:9]
	v_mfma_f32_16x16x32_bf16 v[2:5], v[200:203], v[184:187], v[2:5]
	v_mfma_f32_16x16x32_bf16 v[46:49], v[196:199], v[164:167], v[46:49]
	v_mfma_f32_16x16x32_bf16 v[42:45], v[204:207], v[164:167], v[42:45]
	v_mfma_f32_16x16x32_bf16 v[30:33], v[196:199], v[172:175], v[30:33]
	v_mfma_f32_16x16x32_bf16 v[26:29], v[204:207], v[172:175], v[26:29]
	v_mfma_f32_16x16x32_bf16 v[14:17], v[196:199], v[180:183], v[14:17]
	v_mfma_f32_16x16x32_bf16 v[10:13], v[204:207], v[180:183], v[10:13]
	v_mfma_f32_16x16x32_bf16 v[6:9], v[196:199], v[188:191], v[6:9]
	v_mfma_f32_16x16x32_bf16 v[2:5], v[204:207], v[188:191], v[2:5]
	s_add_i32 s71, s71, 2
	s_add_u32 s69, s69, 0x100
	s_addc_u32 s70, s70, 0
	s_cmp_gt_u32 s71, 29
	s_mov_b64 s[50:51], s[52:53]
	s_barrier
	s_cbranch_scc0 .LBB0_58
	s_ashr_i32 s11, s10, 31
	s_lshl_b64 s[10:11], s[10:11], 24
	v_lshl_or_b32 v140, s26, 8, v138
	s_add_u32 s10, s8, s10
	v_lshl_add_u32 v142, s24, 8, v136
	s_addc_u32 s11, s9, s11
	v_ashrrev_i32_e32 v141, 31, v140
	v_ashrrev_i32_e32 v143, 31, v142
	v_lshl_add_u64 v[140:141], v[140:141], 2, s[10:11]
	v_lshlrev_b64 v[144:145], 13, v[142:143]
	v_lshl_add_u64 v[144:145], v[140:141], 0, v[144:145]
	global_store_dwordx4 v[144:145], v[126:129], off
	global_store_dwordx4 v[144:145], v[122:125], off offset:64
	global_store_dwordx4 v[144:145], v[110:113], off offset:512
	global_store_dwordx4 v[144:145], v[102:105], off offset:576
	s_mov_b64 s[10:11], 0x100000
	s_mov_b32 s26, s40
	v_or_b32_e32 v102, 16, v142
	v_ashrrev_i32_e32 v103, 31, v102
	v_lshlrev_b64 v[102:103], 13, v[102:103]
	v_lshl_add_u64 v[102:103], v[140:141], 0, v[102:103]
	global_store_dwordx4 v[102:103], v[118:121], off
	global_store_dwordx4 v[102:103], v[114:117], off offset:64
	global_store_dwordx4 v[102:103], v[94:97], off offset:512
	global_store_dwordx4 v[102:103], v[86:89], off offset:576
	s_mov_b32 s24, s42
	s_mov_b64 s[52:53], s[48:49]
	v_or_b32_e32 v86, 32, v142
	v_ashrrev_i32_e32 v87, 31, v86
	v_lshlrev_b64 v[86:87], 13, v[86:87]
	v_lshl_add_u64 v[86:87], v[140:141], 0, v[86:87]
	global_store_dwordx4 v[86:87], v[106:109], off
	global_store_dwordx4 v[86:87], v[98:101], off offset:64
	global_store_dwordx4 v[86:87], v[78:81], off offset:512
	global_store_dwordx4 v[86:87], v[74:77], off offset:576
	s_mov_b64 s[50:51], s[46:47]
	s_nop 0
	v_or_b32_e32 v74, 48, v142
	v_ashrrev_i32_e32 v75, 31, v74
	v_lshlrev_b64 v[74:75], 13, v[74:75]
	v_lshl_add_u64 v[74:75], v[140:141], 0, v[74:75]
	global_store_dwordx4 v[74:75], v[90:93], off
	global_store_dwordx4 v[74:75], v[82:85], off offset:64
	global_store_dwordx4 v[74:75], v[70:73], off offset:512
	global_store_dwordx4 v[74:75], v[66:69], off offset:576
	s_nop 1
	v_add_co_u32_e32 v68, vcc, s93, v144
	v_lshl_add_u64 v[66:67], v[144:145], 0, s[10:11]
	s_nop 0
	v_addc_co_u32_e32 v69, vcc, 0, v145, vcc
	s_mov_b64 s[10:11], 0x120000
	global_store_dwordx4 v[68:69], v[62:65], off
	global_store_dwordx4 v[66:67], v[58:61], off offset:64
	global_store_dwordx4 v[66:67], v[46:49], off offset:512
	global_store_dwordx4 v[66:67], v[42:45], off offset:576
	s_nop 1
	v_lshl_add_u64 v[42:43], v[144:145], 0, s[10:11]
	s_mov_b32 s10, 0x120000
	v_add_co_u32_e32 v44, vcc, s10, v144
	s_mov_b64 s[10:11], 0x140000
	s_nop 0
	v_addc_co_u32_e32 v45, vcc, 0, v145, vcc
	global_store_dwordx4 v[44:45], v[54:57], off
	global_store_dwordx4 v[42:43], v[50:53], off offset:64
	global_store_dwordx4 v[42:43], v[30:33], off offset:512
	global_store_dwordx4 v[42:43], v[26:29], off offset:576
	s_nop 1
	v_lshl_add_u64 v[26:27], v[144:145], 0, s[10:11]
	s_mov_b32 s10, 0x140000
	v_add_co_u32_e32 v28, vcc, s10, v144
	s_mov_b64 s[10:11], 0x160000
	s_nop 0
	v_addc_co_u32_e32 v29, vcc, 0, v145, vcc
	global_store_dwordx4 v[28:29], v[38:41], off
	global_store_dwordx4 v[26:27], v[34:37], off offset:64
	global_store_dwordx4 v[26:27], v[14:17], off offset:512
	global_store_dwordx4 v[26:27], v[10:13], off offset:576
	s_nop 1
	v_add_co_u32_e32 v12, vcc, 0x160000, v144
	v_lshl_add_u64 v[10:11], v[144:145], 0, s[10:11]
	s_nop 0
	v_addc_co_u32_e32 v13, vcc, 0, v145, vcc
	s_and_b64 vcc, exec, s[44:45]
	s_mov_b32 s10, s28
	global_store_dwordx4 v[12:13], v[22:25], off
	global_store_dwordx4 v[10:11], v[18:21], off offset:64
	global_store_dwordx4 v[10:11], v[6:9], off offset:512
	global_store_dwordx4 v[10:11], v[2:5], off offset:576
	s_cbranch_vccz .LBB0_55
	s_waitcnt vmcnt(0)
	s_cmpk_gt_u32 s60, 0xff
	s_cbranch_scc1 .LBB0_62
	s_barrier

; #define PG8_STAGE(bufoff, gbase, voff) do { _Pragma("unroll") for (int _i = 0; _i < 2; ++_i) \
;         __builtin_amdgcn_global_load_lds((const unsigned*)((const char*)(gbase) + (voff)[_i]), (LAS unsigned*)(lds + (bufoff) + ldsw + _i * 8192), 16, 0, 0); } while (0)
; #define PG8_LDA(dst, b, h) do { _Pragma("unroll") for (int m = 0; m < 4; ++m) _Pragma("unroll") for (int k = 0; k < 2; ++k) dst[m][k] = *(const LAS bf16x8*)(lds + PG8_SA(b, h) + aoff + m * 2048 + k * 1024); } while (0)
; #define PG8_LDB(dst, b, h) do { _Pragma("unroll") for (int n = 0; n < 2; ++n) _Pragma("unroll") for (int k = 0; k < 2; ++k) dst[n][k] = *(const LAS bf16x8*)(lds + PG8_SB(b, h) + boff + n * 2048 + k * 1024); } while (0)
; #define PG8_MMA(ai, bj, At, Bt) do { __builtin_amdgcn_s_setprio(1); _Pragma("unroll") for (int m = 0; m < 4; ++m) _Pragma("unroll") for (int n = 0; n < 2; ++n) _Pragma("unroll") for (int k = 0; k < 2; ++k) \
;         acc[ai][bj][m][n] = __builtin_amdgcn_mfma_f32_16x16x32_bf16(Bt[n][k], At[m][k], acc[ai][bj][m][n], 0, 0, 0); __builtin_amdgcn_s_setprio(0); } while (0)
; #define PG8_WAIT_L(n) asm volatile("s_waitcnt lgkmcnt(" #n ")" ::: "memory")
; #define PG8_BAR __builtin_amdgcn_s_barrier()
; #define PG8_SCHED __builtin_amdgcn_sched_barrier(0)
; template <class Epi, class Sched>
; __device__ __forceinline__ void gemm_phase(LAS unsigned char* lds, const Gemm g, const Sched& S, const Epi& E) {
;     ...
;         for (int t = 0; t < nt; t += 2) {
;             const bool last = (t == nt - 2);
;             const char* a1 = cA + (size_t)(t + 1) * kstep;
;             const char* a2 = last ? nA : cA + (size_t)(t + 2) * kstep; const char* b2 = last ? nB : cB + (size_t)(t + 2) * kstep;
;             const char* a3 = a2 + kstep; const char* b3 = b2 + kstep;
;             PG8_LDB(B0, 0, 0); PG8_SCHED; PG8_LDA(At, 0, 0); PG8_STAGE(PG8_SA(1, 1), a1 + hstep, voffA);
;             PG8_WAIT_L(8); PG8_BAR; PG8_WAIT_L(0); PG8_MMA(0, 0, At, B0); PG8_BAR; PG8_SCHED;
;             PG8_LDB(B1, 0, 1); PG8_STAGE(PG8_SB(0, 0), b2, voffB);
;             PG8_BAR; PG8_WAIT_L(0); PG8_MMA(0, 1, At, B1); PG8_BAR;
;             PG8_LDA(At, 0, 1); PG8_STAGE(PG8_SA(0, 0), a2, voffA);
;             PG8_BAR; PG8_WAIT_L(0); PG8_MMA(1, 0, At, B0); PG8_BAR; PG8_SCHED;
.LBB0_73:
	s_add_u32 s38, s46, 0xfff80080
	s_addc_u32 s39, s47, -1
	s_cmp_eq_u32 s73, 28
	s_cselect_b32 s51, s29, s39
	s_cselect_b32 s50, s69, s38
	s_cselect_b32 s49, s27, s72
	s_cselect_b32 s48, s70, s71
	v_lshl_add_u64 v[140:141], s[46:47], 0, v[138:139]
	s_add_i32 m0, s9, 0xc000
	s_nop 0
	global_load_lds_dwordx4 v[140:141], off
	v_lshl_add_u64 v[140:141], s[46:47], 0, v[136:137]
	s_add_i32 m0, s9, 0xe000
	s_nop 0
	global_load_lds_dwordx4 v[140:141], off
	s_add_i32 s74, 0, 0x10000
	v_add_u32_e32 v140, s74, v143
	ds_read_b128 v[146:149], v140
	ds_read_b128 v[150:153], v140 offset:1024
	ds_read_b128 v[154:157], v140 offset:2048
	ds_read_b128 v[160:163], v140 offset:3072
	ds_read_b128 v[164:167], v145
	ds_read_b128 v[168:171], v145 offset:1024
	ds_read_b128 v[172:175], v145 offset:2048
	ds_read_b128 v[176:179], v145 offset:3072
	ds_read_b128 v[180:183], v145 offset:4096
	ds_read_b128 v[184:187], v145 offset:5120
	ds_read_b128 v[188:191], v145 offset:6144
	ds_read_b128 v[192:195], v145 offset:7168
	s_add_i32 s75, 0, 0x14000
	v_add_u32_e32 v140, s75, v143
	ds_read_b128 v[196:199], v140
	ds_read_b128 v[200:203], v140 offset:1024
	ds_read_b128 v[204:207], v140 offset:2048
	ds_read_b128 v[210:213], v140 offset:3072
	s_waitcnt lgkmcnt(4)
	s_barrier
	s_waitcnt lgkmcnt(0)
	v_mfma_f32_16x16x32_bf16 v[126:129], v[146:149], v[164:167], v[126:129]
	v_mfma_f32_16x16x32_bf16 v[122:125], v[154:157], v[164:167], v[122:125]
	v_mfma_f32_16x16x32_bf16 v[110:113], v[146:149], v[172:175], v[110:113]
	v_mfma_f32_16x16x32_bf16 v[106:109], v[154:157], v[172:175], v[106:109]
	v_mfma_f32_16x16x32_bf16 v[94:97], v[146:149], v[180:183], v[94:97]
	v_mfma_f32_16x16x32_bf16 v[90:93], v[154:157], v[180:183], v[90:93]
	v_mfma_f32_16x16x32_bf16 v[78:81], v[146:149], v[188:191], v[78:81]
	v_mfma_f32_16x16x32_bf16 v[74:77], v[154:157], v[188:191], v[74:77]
	v_mfma_f32_16x16x32_bf16 v[126:129], v[150:153], v[168:171], v[126:129]
	v_mfma_f32_16x16x32_bf16 v[122:125], v[160:163], v[168:171], v[122:125]
	v_mfma_f32_16x16x32_bf16 v[110:113], v[150:153], v[176:179], v[110:113]
	v_mfma_f32_16x16x32_bf16 v[106:109], v[160:163], v[176:179], v[106:109]
	v_mfma_f32_16x16x32_bf16 v[94:97], v[150:153], v[184:187], v[94:97]
	v_mfma_f32_16x16x32_bf16 v[90:93], v[160:163], v[184:187], v[90:93]
	v_mfma_f32_16x16x32_bf16 v[78:81], v[150:153], v[192:195], v[78:81]
	v_mfma_f32_16x16x32_bf16 v[74:77], v[160:163], v[192:195], v[74:77]
	v_mfma_f32_16x16x32_bf16 v[118:121], v[196:199], v[164:167], v[118:121]
	v_mfma_f32_16x16x32_bf16 v[114:117], v[204:207], v[164:167], v[114:117]
	v_mfma_f32_16x16x32_bf16 v[102:105], v[196:199], v[172:175], v[102:105]
	v_mfma_f32_16x16x32_bf16 v[98:101], v[204:207], v[172:175], v[98:101]
	v_mfma_f32_16x16x32_bf16 v[86:89], v[196:199], v[180:183], v[86:89]
	v_mfma_f32_16x16x32_bf16 v[82:85], v[204:207], v[180:183], v[82:85]
	v_mfma_f32_16x16x32_bf16 v[70:73], v[196:199], v[188:191], v[70:73]
	v_mfma_f32_16x16x32_bf16 v[66:69], v[204:207], v[188:191], v[66:69]
	v_mfma_f32_16x16x32_bf16 v[118:121], v[200:203], v[168:171], v[118:121]
	v_mfma_f32_16x16x32_bf16 v[114:117], v[210:213], v[168:171], v[114:117]
	v_mfma_f32_16x16x32_bf16 v[102:105], v[200:203], v[176:179], v[102:105]
	v_mfma_f32_16x16x32_bf16 v[98:101], v[210:213], v[176:179], v[98:101]
	v_mfma_f32_16x16x32_bf16 v[86:89], v[200:203], v[184:187], v[86:89]
	v_mfma_f32_16x16x32_bf16 v[82:85], v[210:213], v[184:187], v[82:85]
	v_mfma_f32_16x16x32_bf16 v[70:73], v[200:203], v[192:195], v[70:73]
	v_mfma_f32_16x16x32_bf16 v[66:69], v[210:213], v[192:195], v[66:69]
	s_barrier
	s_add_i32 s38, s74, s56
	v_lshl_add_u64 v[140:141], s[48:49], 0, v[0:1]
	s_mov_b32 m0, s38
	v_lshl_add_u64 v[214:215], s[48:49], 0, v[130:131]
	global_load_lds_dwordx4 v[140:141], off
	s_add_i32 m0, s38, 0x2000
	s_nop 0
	global_load_lds_dwordx4 v[214:215], off
	s_mov_b32 m0, s9
	v_lshl_add_u64 v[216:217], s[50:51], 0, v[134:135]
	global_load_lds_dwordx4 v[216:217], off
	v_lshl_add_u64 v[224:225], s[50:51], 0, v[132:133]
	s_mov_b32 m0, s60
	s_nop 0
	global_load_lds_dwordx4 v[224:225], off
	ds_read_b128 v[164:167], v145 offset:16384
	ds_read_b128 v[168:171], v145 offset:17408
	ds_read_b128 v[172:175], v145 offset:18432
	ds_read_b128 v[176:179], v145 offset:19456
	ds_read_b128 v[180:183], v145 offset:20480
	ds_read_b128 v[184:187], v145 offset:21504
	ds_read_b128 v[188:191], v145 offset:22528
	ds_read_b128 v[192:195], v145 offset:23552
	s_waitcnt vmcnt(4)
	s_waitcnt lgkmcnt(0)
	s_barrier
	v_mfma_f32_16x16x32_bf16 v[62:65], v[146:149], v[164:167], v[62:65]
	v_mfma_f32_16x16x32_bf16 v[58:61], v[154:157], v[164:167], v[58:61]
	v_mfma_f32_16x16x32_bf16 v[46:49], v[146:149], v[172:175], v[46:49]
	v_mfma_f32_16x16x32_bf16 v[42:45], v[154:157], v[172:175], v[42:45]
	v_mfma_f32_16x16x32_bf16 v[30:33], v[146:149], v[180:183], v[30:33]
	v_mfma_f32_16x16x32_bf16 v[26:29], v[154:157], v[180:183], v[26:29]
	v_mfma_f32_16x16x32_bf16 v[14:17], v[146:149], v[188:191], v[14:17]
	v_mfma_f32_16x16x32_bf16 v[10:13], v[154:157], v[188:191], v[10:13]
	v_mfma_f32_16x16x32_bf16 v[62:65], v[150:153], v[168:171], v[62:65]
	v_mfma_f32_16x16x32_bf16 v[58:61], v[160:163], v[168:171], v[58:61]
	v_mfma_f32_16x16x32_bf16 v[46:49], v[150:153], v[176:179], v[46:49]
	v_mfma_f32_16x16x32_bf16 v[42:45], v[160:163], v[176:179], v[42:45]
	v_mfma_f32_16x16x32_bf16 v[30:33], v[150:153], v[184:187], v[30:33]
	v_mfma_f32_16x16x32_bf16 v[26:29], v[160:163], v[184:187], v[26:29]
	v_mfma_f32_16x16x32_bf16 v[14:17], v[150:153], v[192:195], v[14:17]
	v_mfma_f32_16x16x32_bf16 v[10:13], v[160:163], v[192:195], v[10:13]
	v_mfma_f32_16x16x32_bf16 v[54:57], v[196:199], v[164:167], v[54:57]
	v_mfma_f32_16x16x32_bf16 v[50:53], v[204:207], v[164:167], v[50:53]
	v_mfma_f32_16x16x32_bf16 v[38:41], v[196:199], v[172:175], v[38:41]
	v_mfma_f32_16x16x32_bf16 v[34:37], v[204:207], v[172:175], v[34:37]
	v_mfma_f32_16x16x32_bf16 v[22:25], v[196:199], v[180:183], v[22:25]
	v_mfma_f32_16x16x32_bf16 v[18:21], v[204:207], v[180:183], v[18:21]
	v_mfma_f32_16x16x32_bf16 v[6:9], v[196:199], v[188:191], v[6:9]
	v_mfma_f32_16x16x32_bf16 v[2:5], v[204:207], v[188:191], v[2:5]
	v_mfma_f32_16x16x32_bf16 v[54:57], v[200:203], v[168:171], v[54:57]
	v_mfma_f32_16x16x32_bf16 v[50:53], v[210:213], v[168:171], v[50:53]
	v_mfma_f32_16x16x32_bf16 v[38:41], v[200:203], v[176:179], v[38:41]
	v_mfma_f32_16x16x32_bf16 v[34:37], v[210:213], v[176:179], v[34:37]
	v_mfma_f32_16x16x32_bf16 v[22:25], v[200:203], v[184:187], v[22:25]
	v_mfma_f32_16x16x32_bf16 v[18:21], v[210:213], v[184:187], v[18:21]
	v_mfma_f32_16x16x32_bf16 v[6:9], v[200:203], v[192:195], v[6:9]
	v_mfma_f32_16x16x32_bf16 v[2:5], v[210:213], v[192:195], v[2:5]
	s_barrier
; #define PG8_STAGE(bufoff, gbase, voff) do { _Pragma("unroll") for (int _i = 0; _i < 2; ++_i) \
;         __builtin_amdgcn_global_load_lds((const unsigned*)((const char*)(gbase) + (voff)[_i]), (LAS unsigned*)(lds + (bufoff) + ldsw + _i * 8192), 16, 0, 0); } while (0)
; #define PG8_LDA(dst, b, h) do { _Pragma("unroll") for (int m = 0; m < 4; ++m) _Pragma("unroll") for (int k = 0; k < 2; ++k) dst[m][k] = *(const LAS bf16x8*)(lds + PG8_SA(b, h) + aoff + m * 2048 + k * 1024); } while (0)
; #define PG8_LDB(dst, b, h) do { _Pragma("unroll") for (int n = 0; n < 2; ++n) _Pragma("unroll") for (int k = 0; k < 2; ++k) dst[n][k] = *(const LAS bf16x8*)(lds + PG8_SB(b, h) + boff + n * 2048 + k * 1024); } while (0)
; #define PG8_MMA(ai, bj, At, Bt) do { __builtin_amdgcn_s_setprio(1); _Pragma("unroll") for (int m = 0; m < 4; ++m) _Pragma("unroll") for (int n = 0; n < 2; ++n) _Pragma("unroll") for (int k = 0; k < 2; ++k) \
;         acc[ai][bj][m][n] = __builtin_amdgcn_mfma_f32_16x16x32_bf16(Bt[n][k], At[m][k], acc[ai][bj][m][n], 0, 0, 0); __builtin_amdgcn_s_setprio(0); } while (0)
; #define PG8_WAIT_V(n) asm volatile("s_waitcnt vmcnt(" #n ")" ::: "memory")
; #define PG8_WAIT_L(n) asm volatile("s_waitcnt lgkmcnt(" #n ")" ::: "memory")
; #define PG8_BAR __builtin_amdgcn_s_barrier()
; #define PG8_SCHED __builtin_amdgcn_sched_barrier(0)
; template <class Epi, class Sched>
; __device__ __forceinline__ void gemm_phase(LAS unsigned char* lds, const Gemm g, const Sched& S, const Epi& E) {
;     ...
;             PG8_STAGE(PG8_SB(0, 1), b2 + hstep, voffB);
;             PG8_WAIT_V(6); PG8_BAR; PG8_MMA(1, 1, At, B1); PG8_BAR;
;             PG8_LDB(B0, 1, 0); PG8_SCHED; PG8_LDA(At, 1, 0); PG8_STAGE(PG8_SA(0, 1), a2 + hstep, voffA);
;             PG8_WAIT_L(8); PG8_BAR; PG8_WAIT_L(0); PG8_MMA(0, 0, At, B0); PG8_BAR; PG8_SCHED;
	s_add_u32 s38, s48, 0x80000
	s_addc_u32 s39, s49, 0
	s_add_i32 s74, s75, s56
	v_lshl_add_u64 v[146:147], s[38:39], 0, v[0:1]
	s_mov_b32 m0, s74
	s_nop 0
	global_load_lds_dwordx4 v[146:147], off
	v_lshl_add_u64 v[146:147], s[38:39], 0, v[130:131]
	s_add_i32 m0, s74, 0x2000
	s_nop 0
	global_load_lds_dwordx4 v[146:147], off
	s_add_u32 s38, s50, 0x80000
	s_addc_u32 s39, s51, 0
	s_mov_b32 m0, s61
	v_lshl_add_u64 v[196:197], s[38:39], 0, v[134:135]
	global_load_lds_dwordx4 v[196:197], off
	v_lshl_add_u64 v[196:197], s[38:39], 0, v[132:133]
	s_mov_b32 m0, s62
	s_nop 0
	global_load_lds_dwordx4 v[196:197], off
	s_add_i32 s74, 0, 0x18000
	v_add_u32_e32 v160, s74, v143
	ds_read_b128 v[146:149], v160
	ds_read_b128 v[150:153], v160 offset:1024
	ds_read_b128 v[154:157], v160 offset:2048
	ds_read_b128 v[160:163], v160 offset:3072
	ds_read_b128 v[164:167], v145 offset:32768
	ds_read_b128 v[168:171], v145 offset:33792
	ds_read_b128 v[172:175], v145 offset:34816
	ds_read_b128 v[176:179], v145 offset:35840
	ds_read_b128 v[180:183], v145 offset:36864
	ds_read_b128 v[184:187], v145 offset:37888
	ds_read_b128 v[188:191], v145 offset:38912
	ds_read_b128 v[192:195], v145 offset:39936
	s_add_i32 s50, 0, 0x1c000
	v_add_u32_e32 v210, s50, v143
	ds_read_b128 v[196:199], v210
	ds_read_b128 v[200:203], v210 offset:1024
	ds_read_b128 v[204:207], v210 offset:2048
	ds_read_b128 v[210:213], v210 offset:3072
	s_waitcnt lgkmcnt(4)
	s_barrier
	s_waitcnt lgkmcnt(0)
	v_mfma_f32_16x16x32_bf16 v[126:129], v[146:149], v[164:167], v[126:129]
	v_mfma_f32_16x16x32_bf16 v[122:125], v[154:157], v[164:167], v[122:125]
	v_mfma_f32_16x16x32_bf16 v[110:113], v[146:149], v[172:175], v[110:113]
	v_mfma_f32_16x16x32_bf16 v[106:109], v[154:157], v[172:175], v[106:109]
	v_mfma_f32_16x16x32_bf16 v[94:97], v[146:149], v[180:183], v[94:97]
	v_mfma_f32_16x16x32_bf16 v[90:93], v[154:157], v[180:183], v[90:93]
	v_mfma_f32_16x16x32_bf16 v[78:81], v[146:149], v[188:191], v[78:81]
	v_mfma_f32_16x16x32_bf16 v[74:77], v[154:157], v[188:191], v[74:77]
	v_mfma_f32_16x16x32_bf16 v[126:129], v[150:153], v[168:171], v[126:129]
	v_mfma_f32_16x16x32_bf16 v[122:125], v[160:163], v[168:171], v[122:125]
	v_mfma_f32_16x16x32_bf16 v[110:113], v[150:153], v[176:179], v[110:113]
	v_mfma_f32_16x16x32_bf16 v[106:109], v[160:163], v[176:179], v[106:109]
	v_mfma_f32_16x16x32_bf16 v[94:97], v[150:153], v[184:187], v[94:97]
	v_mfma_f32_16x16x32_bf16 v[90:93], v[160:163], v[184:187], v[90:93]
	v_mfma_f32_16x16x32_bf16 v[78:81], v[150:153], v[192:195], v[78:81]
	v_mfma_f32_16x16x32_bf16 v[74:77], v[160:163], v[192:195], v[74:77]
	v_mfma_f32_16x16x32_bf16 v[118:121], v[196:199], v[164:167], v[118:121]
	v_mfma_f32_16x16x32_bf16 v[114:117], v[204:207], v[164:167], v[114:117]
	v_mfma_f32_16x16x32_bf16 v[102:105], v[196:199], v[172:175], v[102:105]
	v_mfma_f32_16x16x32_bf16 v[98:101], v[204:207], v[172:175], v[98:101]
	v_mfma_f32_16x16x32_bf16 v[86:89], v[196:199], v[180:183], v[86:89]
	v_mfma_f32_16x16x32_bf16 v[82:85], v[204:207], v[180:183], v[82:85]
	v_mfma_f32_16x16x32_bf16 v[70:73], v[196:199], v[188:191], v[70:73]
	v_mfma_f32_16x16x32_bf16 v[66:69], v[204:207], v[188:191], v[66:69]
	v_mfma_f32_16x16x32_bf16 v[118:121], v[200:203], v[168:171], v[118:121]
	v_mfma_f32_16x16x32_bf16 v[114:117], v[210:213], v[168:171], v[114:117]
	v_mfma_f32_16x16x32_bf16 v[102:105], v[200:203], v[176:179], v[102:105]
	v_mfma_f32_16x16x32_bf16 v[98:101], v[210:213], v[176:179], v[98:101]
	v_mfma_f32_16x16x32_bf16 v[86:89], v[200:203], v[184:187], v[86:89]
	v_mfma_f32_16x16x32_bf16 v[82:85], v[210:213], v[184:187], v[82:85]
	v_mfma_f32_16x16x32_bf16 v[70:73], v[200:203], v[192:195], v[70:73]
	v_mfma_f32_16x16x32_bf16 v[66:69], v[210:213], v[192:195], v[66:69]
	s_barrier
	s_add_i32 s38, s74, s56
	v_lshl_add_u64 v[140:141], v[140:141], 0, s[36:37]
	s_mov_b32 m0, s38
	s_nop 0
	global_load_lds_dwordx4 v[140:141], off
	v_lshl_add_u64 v[140:141], v[214:215], 0, s[36:37]
	s_add_i32 m0, s38, 0x2000
	s_nop 0
	global_load_lds_dwordx4 v[140:141], off
	s_mov_b32 m0, s64
	v_lshl_add_u64 v[140:141], v[216:217], 0, s[36:37]
	global_load_lds_dwordx4 v[140:141], off
	v_lshl_add_u64 v[140:141], v[224:225], 0, s[36:37]
	s_mov_b32 m0, s65
	s_nop 0
	global_load_lds_dwordx4 v[140:141], off
	ds_read_b128 v[164:167], v145 offset:49152
	ds_read_b128 v[168:171], v145 offset:50176
	ds_read_b128 v[172:175], v145 offset:51200
	ds_read_b128 v[176:179], v145 offset:52224
	ds_read_b128 v[180:183], v145 offset:53248
	ds_read_b128 v[184:187], v145 offset:54272
	ds_read_b128 v[188:191], v145 offset:55296
	ds_read_b128 v[192:195], v145 offset:56320
	s_waitcnt vmcnt(4)
	s_waitcnt lgkmcnt(0)
	s_barrier
; __device__ __forceinline__ unsigned cvt_pk_bf16(float lo, float hi) { unsigned r; asm("v_cvt_pk_bf16_f32 %0, %1, %2" : "=v"(r) : "v"(lo), "v"(hi)); return r; }
; #define PG8_STAGE(bufoff, gbase, voff) do { _Pragma("unroll") for (int _i = 0; _i < 2; ++_i) \
;         __builtin_amdgcn_global_load_lds((const unsigned*)((const char*)(gbase) + (voff)[_i]), (LAS unsigned*)(lds + (bufoff) + ldsw + _i * 8192), 16, 0, 0); } while (0)
; #define PG8_LDA(dst, b, h) do { _Pragma("unroll") for (int m = 0; m < 4; ++m) _Pragma("unroll") for (int k = 0; k < 2; ++k) dst[m][k] = *(const LAS bf16x8*)(lds + PG8_SA(b, h) + aoff + m * 2048 + k * 1024); } while (0)
; #define PG8_WAIT_V(n) asm volatile("s_waitcnt vmcnt(" #n ")" ::: "memory")
; #define PG8_BAR __builtin_amdgcn_s_barrier()
;     __device__ __forceinline__ void operator()(const f32x4 (&acc)[2][2][4][2], const Unit& u, int wr, int wc, int fr, int fq) const {
;         const int row0 = u.pm * BM + wr * 64 + fr, col0 = u.pn * BM + wc * 32 + 8 * fq;
; #pragma unroll
;         for (int ai = 0; ai < 2; ++ai)
; #pragma unroll
;             for (int m = 0; m < 4; ++m) { bf16_t* rowp = O + (size_t)(row0 + ai * HALF + m * 16) * ldc + col0;
; #pragma unroll
;                 for (int bj = 0; bj < 2; ++bj) { f32x4 v0 = acc[ai][bj][m][0], v1 = acc[ai][bj][m][1];
;                     if (ACT == 1) {
; #pragma unroll
;                         for (int j = 0; j < 4; ++j) { float a = fmaxf(v0[j], 0.f), b = fmaxf(v1[j], 0.f); v0[j] = a * a; v1[j] = b * b; } }
;                     u32x4 w; w.x = cvt_pk_bf16(v0[0], v0[1]); w.y = cvt_pk_bf16(v0[2], v0[3]); w.z = cvt_pk_bf16(v1[0], v1[1]); w.w = cvt_pk_bf16(v1[2], v1[3]);
;                     if (ACT == 1) __builtin_nontemporal_store(w, (u32x4*)(rowp + bj * HALF));
;                     else *(u32x4*)(rowp + bj * HALF) = w; } }
; template <class Epi, class Sched>
; __device__ __forceinline__ void gemm_phase(LAS unsigned char* lds, const Gemm g, const Sched& S, const Epi& E) {
;     ...
;             PG8_LDB(B1, 1, 1); PG8_STAGE(PG8_SB(1, 0), b3, voffB);
;             PG8_BAR; PG8_WAIT_L(0); PG8_MMA(0, 1, At, B1); PG8_BAR;
;             PG8_LDA(At, 1, 1); PG8_STAGE(PG8_SA(1, 0), a3, voffA);
;             PG8_BAR; PG8_WAIT_L(0); PG8_MMA(1, 0, At, B0); PG8_BAR; PG8_SCHED;
;             PG8_STAGE(PG8_SB(1, 1), b3 + hstep, voffB);
;             PG8_WAIT_V(6); PG8_BAR; PG8_MMA(1, 1, At, B1); PG8_BAR;
	v_mfma_f32_16x16x32_bf16 v[62:65], v[146:149], v[164:167], v[62:65]
	v_mfma_f32_16x16x32_bf16 v[58:61], v[154:157], v[164:167], v[58:61]
	v_mfma_f32_16x16x32_bf16 v[46:49], v[146:149], v[172:175], v[46:49]
	v_mfma_f32_16x16x32_bf16 v[42:45], v[154:157], v[172:175], v[42:45]
	v_mfma_f32_16x16x32_bf16 v[30:33], v[146:149], v[180:183], v[30:33]
	v_mfma_f32_16x16x32_bf16 v[26:29], v[154:157], v[180:183], v[26:29]
	v_mfma_f32_16x16x32_bf16 v[14:17], v[146:149], v[188:191], v[14:17]
	v_mfma_f32_16x16x32_bf16 v[10:13], v[154:157], v[188:191], v[10:13]
	v_mfma_f32_16x16x32_bf16 v[62:65], v[150:153], v[168:171], v[62:65]
	v_mfma_f32_16x16x32_bf16 v[58:61], v[160:163], v[168:171], v[58:61]
	v_mfma_f32_16x16x32_bf16 v[46:49], v[150:153], v[176:179], v[46:49]
	v_mfma_f32_16x16x32_bf16 v[42:45], v[160:163], v[176:179], v[42:45]
	v_mfma_f32_16x16x32_bf16 v[30:33], v[150:153], v[184:187], v[30:33]
	v_mfma_f32_16x16x32_bf16 v[26:29], v[160:163], v[184:187], v[26:29]
	v_mfma_f32_16x16x32_bf16 v[14:17], v[150:153], v[192:195], v[14:17]
	v_mfma_f32_16x16x32_bf16 v[10:13], v[160:163], v[192:195], v[10:13]
	s_add_u32 s38, s48, 0x80080
	s_addc_u32 s39, s49, 0
	s_add_i32 s48, s50, s56
	v_lshl_add_u64 v[140:141], s[38:39], 0, v[0:1]
	s_mov_b32 m0, s48
	s_nop 0
	global_load_lds_dwordx4 v[140:141], off
	v_lshl_add_u64 v[140:141], s[38:39], 0, v[130:131]
	s_add_i32 m0, s48, 0x2000
	s_nop 0
	global_load_lds_dwordx4 v[140:141], off
	v_mfma_f32_16x16x32_bf16 v[54:57], v[196:199], v[164:167], v[54:57]
	v_mfma_f32_16x16x32_bf16 v[50:53], v[204:207], v[164:167], v[50:53]
	v_mfma_f32_16x16x32_bf16 v[38:41], v[196:199], v[172:175], v[38:41]
	v_mfma_f32_16x16x32_bf16 v[34:37], v[204:207], v[172:175], v[34:37]
	v_mfma_f32_16x16x32_bf16 v[22:25], v[196:199], v[180:183], v[22:25]
	v_mfma_f32_16x16x32_bf16 v[18:21], v[204:207], v[180:183], v[18:21]
	v_mfma_f32_16x16x32_bf16 v[6:9], v[196:199], v[188:191], v[6:9]
	v_mfma_f32_16x16x32_bf16 v[2:5], v[204:207], v[188:191], v[2:5]
	v_mfma_f32_16x16x32_bf16 v[54:57], v[200:203], v[168:171], v[54:57]
	v_mfma_f32_16x16x32_bf16 v[50:53], v[210:213], v[168:171], v[50:53]
	v_mfma_f32_16x16x32_bf16 v[38:41], v[200:203], v[176:179], v[38:41]
	v_mfma_f32_16x16x32_bf16 v[34:37], v[210:213], v[176:179], v[34:37]
	v_mfma_f32_16x16x32_bf16 v[22:25], v[200:203], v[184:187], v[22:25]
	v_mfma_f32_16x16x32_bf16 v[18:21], v[210:213], v[184:187], v[18:21]
	v_mfma_f32_16x16x32_bf16 v[6:9], v[200:203], v[192:195], v[6:9]
	v_mfma_f32_16x16x32_bf16 v[2:5], v[210:213], v[192:195], v[2:5]
	s_add_i32 s73, s73, 2
	s_add_u32 s71, s71, 0x100
	s_addc_u32 s72, s72, 0
	s_add_u32 s46, s46, 0x100
	s_addc_u32 s47, s47, 0
	s_cmp_gt_u32 s73, 29
	s_barrier
	s_cbranch_scc0 .LBB0_73
	v_lshl_add_u32 v146, s8, 8, v142
	v_max_f32_e32 v122, v122, v122
	v_ashrrev_i32_e32 v147, 31, v146
	v_max_f32_e32 v122, 0, v122
	v_max_f32_e32 v123, v123, v123
	v_max_f32_e32 v124, v124, v124
	v_lshl_or_b32 v140, s68, 8, v144
	v_lshlrev_b64 v[148:149], 14, v[146:147]
	v_mul_f32_e32 v147, v122, v122
	v_max_f32_e32 v122, v127, v127
	v_max_f32_e32 v123, 0, v123
	v_max_f32_e32 v124, 0, v124
	v_ashrrev_i32_e32 v141, 31, v140
	v_max_f32_e32 v126, v126, v126
	v_max_f32_e32 v122, 0, v122
	v_mul_f32_e32 v127, v123, v123
	v_max_f32_e32 v123, v128, v128
	v_mul_f32_e32 v128, v124, v124
	v_max_f32_e32 v124, v129, v129
	v_max_f32_e32 v125, v125, v125
	v_lshl_add_u64 v[148:149], s[24:25], 0, v[148:149]
	v_lshlrev_b64 v[150:151], 1, v[140:141]
	v_max_f32_e32 v126, 0, v126
	v_mul_f32_e32 v122, v122, v122
	v_max_f32_e32 v123, 0, v123
	v_max_f32_e32 v124, 0, v124
	v_max_f32_e32 v125, 0, v125
	v_max_f32_e32 v114, v114, v114
	v_lshl_add_u64 v[140:141], v[148:149], 0, v[150:151]
	v_mul_f32_e32 v126, v126, v126
	v_mul_f32_e32 v123, v123, v123
	v_mul_f32_e32 v124, v124, v124
	v_mul_f32_e32 v125, v125, v125
	v_cvt_pk_bf16_f32 v122, v126, v122
	v_max_f32_e32 v114, 0, v114
	v_max_f32_e32 v115, v115, v115
	v_max_f32_e32 v116, v116, v116
	v_cvt_pk_bf16_f32 v123, v123, v124
	v_cvt_pk_bf16_f32 v124, v147, v127
	v_cvt_pk_bf16_f32 v125, v128, v125
	global_store_dwordx4 v[140:141], v[122:125], off nt
	v_max_f32_e32 v115, 0, v115
	v_max_f32_e32 v116, 0, v116
	v_mul_f32_e32 v122, v114, v114
	v_max_f32_e32 v114, v119, v119
	v_max_f32_e32 v118, v118, v118
	v_max_f32_e32 v114, 0, v114
	v_mul_f32_e32 v119, v115, v115
	v_max_f32_e32 v115, v120, v120
	v_mul_f32_e32 v120, v116, v116
	v_max_f32_e32 v116, v121, v121
	v_max_f32_e32 v117, v117, v117
	v_max_f32_e32 v118, 0, v118
	v_mul_f32_e32 v114, v114, v114
	v_max_f32_e32 v115, 0, v115
	v_max_f32_e32 v116, 0, v116
	v_max_f32_e32 v117, 0, v117
	v_mul_f32_e32 v118, v118, v118
	v_mul_f32_e32 v115, v115, v115
	v_mul_f32_e32 v116, v116, v116
	v_mul_f32_e32 v117, v117, v117
	v_cvt_pk_bf16_f32 v114, v118, v114
	v_max_f32_e32 v106, v106, v106
	v_cvt_pk_bf16_f32 v115, v115, v116
	v_cvt_pk_bf16_f32 v116, v122, v119
	v_cvt_pk_bf16_f32 v117, v120, v117
	global_store_dwordx4 v[140:141], v[114:117], off offset:256 nt
	v_max_f32_e32 v106, 0, v106
	v_max_f32_e32 v107, v107, v107
	v_or_b32_e32 v114, 16, v146
	v_max_f32_e32 v108, v108, v108
	v_ashrrev_i32_e32 v115, 31, v114
	v_mul_f32_e32 v116, v106, v106
	v_max_f32_e32 v106, v111, v111
	v_max_f32_e32 v107, 0, v107
	v_max_f32_e32 v108, 0, v108
	v_lshlrev_b64 v[114:115], 14, v[114:115]
	v_max_f32_e32 v110, v110, v110
	v_max_f32_e32 v106, 0, v106
	v_mul_f32_e32 v111, v107, v107
	v_max_f32_e32 v107, v112, v112
	v_mul_f32_e32 v112, v108, v108
	v_max_f32_e32 v108, v113, v113
	v_max_f32_e32 v109, v109, v109
	v_lshl_add_u64 v[114:115], s[24:25], 0, v[114:115]
	v_max_f32_e32 v110, 0, v110
	v_mul_f32_e32 v106, v106, v106
	v_max_f32_e32 v107, 0, v107
; __device__ __forceinline__ unsigned cvt_pk_bf16(float lo, float hi) { unsigned r; asm("v_cvt_pk_bf16_f32 %0, %1, %2" : "=v"(r) : "v"(lo), "v"(hi)); return r; }
;     __device__ __forceinline__ void operator()(const f32x4 (&acc)[2][2][4][2], const Unit& u, int wr, int wc, int fr, int fq) const {
;     ...
;             for (int m = 0; m < 4; ++m) { bf16_t* rowp = O + (size_t)(row0 + ai * HALF + m * 16) * ldc + col0;
; #pragma unroll
;                 for (int bj = 0; bj < 2; ++bj) { f32x4 v0 = acc[ai][bj][m][0], v1 = acc[ai][bj][m][1];
;                     if (ACT == 1) {
; #pragma unroll
;                         for (int j = 0; j < 4; ++j) { float a = fmaxf(v0[j], 0.f), b = fmaxf(v1[j], 0.f); v0[j] = a * a; v1[j] = b * b; } }
;                     u32x4 w; w.x = cvt_pk_bf16(v0[0], v0[1]); w.y = cvt_pk_bf16(v0[2], v0[3]); w.z = cvt_pk_bf16(v1[0], v1[1]); w.w = cvt_pk_bf16(v1[2], v1[3]);
;                     if (ACT == 1) __builtin_nontemporal_store(w, (u32x4*)(rowp + bj * HALF));
;                     else *(u32x4*)(rowp + bj * HALF) = w; } }
	v_max_f32_e32 v108, 0, v108
	v_max_f32_e32 v109, 0, v109
	v_max_f32_e32 v98, v98, v98
	v_lshl_add_u64 v[114:115], v[114:115], 0, v[150:151]
	v_mul_f32_e32 v110, v110, v110
	v_mul_f32_e32 v107, v107, v107
	v_mul_f32_e32 v108, v108, v108
	v_mul_f32_e32 v109, v109, v109
	v_cvt_pk_bf16_f32 v106, v110, v106
	v_max_f32_e32 v98, 0, v98
	v_max_f32_e32 v99, v99, v99
	v_max_f32_e32 v100, v100, v100
	v_cvt_pk_bf16_f32 v107, v107, v108
	v_cvt_pk_bf16_f32 v108, v116, v111
	v_cvt_pk_bf16_f32 v109, v112, v109
	global_store_dwordx4 v[114:115], v[106:109], off nt
	v_max_f32_e32 v99, 0, v99
	v_max_f32_e32 v100, 0, v100
	v_mul_f32_e32 v106, v98, v98
	v_max_f32_e32 v98, v103, v103
	v_max_f32_e32 v102, v102, v102
	v_max_f32_e32 v98, 0, v98
	v_mul_f32_e32 v103, v99, v99
	v_max_f32_e32 v99, v104, v104
	v_mul_f32_e32 v104, v100, v100
	v_max_f32_e32 v100, v105, v105
	v_max_f32_e32 v101, v101, v101
	v_max_f32_e32 v102, 0, v102
	v_mul_f32_e32 v98, v98, v98
	v_max_f32_e32 v99, 0, v99
	v_max_f32_e32 v100, 0, v100
	v_max_f32_e32 v101, 0, v101
	v_mul_f32_e32 v102, v102, v102
	v_mul_f32_e32 v99, v99, v99
	v_mul_f32_e32 v100, v100, v100
	v_mul_f32_e32 v101, v101, v101
	v_cvt_pk_bf16_f32 v98, v102, v98
	v_max_f32_e32 v90, v90, v90
	v_cvt_pk_bf16_f32 v99, v99, v100
	v_cvt_pk_bf16_f32 v100, v106, v103
	v_cvt_pk_bf16_f32 v101, v104, v101
	global_store_dwordx4 v[114:115], v[98:101], off offset:256 nt
	v_max_f32_e32 v90, 0, v90
	v_max_f32_e32 v91, v91, v91
	v_or_b32_e32 v98, 32, v146
	v_max_f32_e32 v92, v92, v92
	v_ashrrev_i32_e32 v99, 31, v98
	v_mul_f32_e32 v100, v90, v90
	v_max_f32_e32 v90, v95, v95
	v_max_f32_e32 v91, 0, v91
	v_max_f32_e32 v92, 0, v92
	v_lshlrev_b64 v[98:99], 14, v[98:99]
	v_max_f32_e32 v94, v94, v94
	v_max_f32_e32 v90, 0, v90
	v_mul_f32_e32 v95, v91, v91
	v_max_f32_e32 v91, v96, v96
	v_mul_f32_e32 v96, v92, v92
	v_max_f32_e32 v92, v97, v97
	v_max_f32_e32 v93, v93, v93
	v_lshl_add_u64 v[98:99], s[24:25], 0, v[98:99]
	v_max_f32_e32 v94, 0, v94
	v_mul_f32_e32 v90, v90, v90
	v_max_f32_e32 v91, 0, v91
	v_max_f32_e32 v92, 0, v92
	v_max_f32_e32 v93, 0, v93
	v_max_f32_e32 v82, v82, v82
	v_lshl_add_u64 v[98:99], v[98:99], 0, v[150:151]
	v_mul_f32_e32 v94, v94, v94
	v_mul_f32_e32 v91, v91, v91
	v_mul_f32_e32 v92, v92, v92
	v_mul_f32_e32 v93, v93, v93
	v_cvt_pk_bf16_f32 v90, v94, v90
	v_max_f32_e32 v82, 0, v82
	v_max_f32_e32 v83, v83, v83
	v_max_f32_e32 v84, v84, v84
	v_cvt_pk_bf16_f32 v91, v91, v92
	v_cvt_pk_bf16_f32 v92, v100, v95
	v_cvt_pk_bf16_f32 v93, v96, v93
	global_store_dwordx4 v[98:99], v[90:93], off nt
	v_max_f32_e32 v83, 0, v83
	v_max_f32_e32 v84, 0, v84
	v_mul_f32_e32 v90, v82, v82
	v_max_f32_e32 v82, v87, v87
	v_max_f32_e32 v86, v86, v86
	v_max_f32_e32 v82, 0, v82
	v_mul_f32_e32 v87, v83, v83
	v_max_f32_e32 v83, v88, v88
	v_mul_f32_e32 v88, v84, v84
	v_max_f32_e32 v84, v89, v89
	v_max_f32_e32 v85, v85, v85
	v_max_f32_e32 v86, 0, v86
	v_mul_f32_e32 v82, v82, v82
	v_max_f32_e32 v83, 0, v83
	v_max_f32_e32 v84, 0, v84
	v_max_f32_e32 v85, 0, v85
	v_mul_f32_e32 v86, v86, v86
	v_mul_f32_e32 v83, v83, v83
	v_mul_f32_e32 v84, v84, v84
	v_mul_f32_e32 v85, v85, v85
	v_cvt_pk_bf16_f32 v82, v86, v82
	v_max_f32_e32 v74, v74, v74
	v_cvt_pk_bf16_f32 v83, v83, v84
	v_cvt_pk_bf16_f32 v84, v90, v87
	v_cvt_pk_bf16_f32 v85, v88, v85
	global_store_dwordx4 v[98:99], v[82:85], off offset:256 nt
	v_max_f32_e32 v74, 0, v74
	v_max_f32_e32 v75, v75, v75
	v_or_b32_e32 v82, 48, v146
	v_max_f32_e32 v76, v76, v76
	v_ashrrev_i32_e32 v83, 31, v82
	v_mul_f32_e32 v84, v74, v74
	v_max_f32_e32 v74, v79, v79
	v_max_f32_e32 v75, 0, v75
	v_max_f32_e32 v76, 0, v76
	v_lshlrev_b64 v[82:83], 14, v[82:83]
	v_max_f32_e32 v78, v78, v78
	v_max_f32_e32 v74, 0, v74
	v_mul_f32_e32 v79, v75, v75
	v_max_f32_e32 v75, v80, v80
	v_mul_f32_e32 v80, v76, v76
	v_max_f32_e32 v76, v81, v81
	v_max_f32_e32 v77, v77, v77
	v_lshl_add_u64 v[82:83], s[24:25], 0, v[82:83]
	v_max_f32_e32 v78, 0, v78
	v_mul_f32_e32 v74, v74, v74
	v_max_f32_e32 v75, 0, v75
	v_max_f32_e32 v76, 0, v76
	v_max_f32_e32 v77, 0, v77
	v_max_f32_e32 v66, v66, v66
	v_max_f32_e32 v67, v67, v67
	v_max_f32_e32 v68, v68, v68
	v_lshl_add_u64 v[82:83], v[82:83], 0, v[150:151]
	v_mul_f32_e32 v78, v78, v78
	v_mul_f32_e32 v75, v75, v75
	v_mul_f32_e32 v76, v76, v76
	v_mul_f32_e32 v77, v77, v77
	v_cvt_pk_bf16_f32 v74, v78, v74
	v_max_f32_e32 v66, 0, v66
	v_max_f32_e32 v67, 0, v67
	v_max_f32_e32 v68, 0, v68
	v_cvt_pk_bf16_f32 v75, v75, v76
	v_cvt_pk_bf16_f32 v76, v84, v79
	v_cvt_pk_bf16_f32 v77, v80, v77
	global_store_dwordx4 v[82:83], v[74:77], off nt
	v_max_f32_e32 v69, v69, v69
	v_max_f32_e32 v70, v70, v70
	v_mul_f32_e32 v74, v66, v66
	v_max_f32_e32 v66, v71, v71
	v_mul_f32_e32 v71, v67, v67
	v_max_f32_e32 v67, v72, v72
	v_mul_f32_e32 v72, v68, v68
	v_max_f32_e32 v68, v73, v73
	v_max_f32_e32 v67, 0, v67
	v_max_f32_e32 v68, 0, v68
	v_max_f32_e32 v66, 0, v66
	v_mul_f32_e32 v67, v67, v67
	v_max_f32_e32 v69, 0, v69
	v_mul_f32_e32 v68, v68, v68
	v_max_f32_e32 v58, v58, v58
	v_max_f32_e32 v70, 0, v70
	v_mul_f32_e32 v66, v66, v66
	v_mul_f32_e32 v69, v69, v69
	v_cvt_pk_bf16_f32 v67, v67, v68
	v_cvt_pk_bf16_f32 v68, v74, v71
	v_max_f32_e32 v58, 0, v58
	v_max_f32_e32 v59, v59, v59
	v_max_f32_e32 v60, v60, v60
	v_mul_f32_e32 v70, v70, v70
	v_cvt_pk_bf16_f32 v66, v70, v66
	v_cvt_pk_bf16_f32 v69, v72, v69
	global_store_dwordx4 v[82:83], v[66:69], off offset:256 nt
	v_max_f32_e32 v62, v62, v62
	v_max_f32_e32 v59, 0, v59
	v_mul_f32_e32 v68, v58, v58
	v_max_f32_e32 v58, v63, v63
	v_max_f32_e32 v60, 0, v60
	v_max_f32_e32 v62, 0, v62
	v_max_f32_e32 v58, 0, v58
	v_mul_f32_e32 v63, v59, v59
	v_max_f32_e32 v59, v64, v64
	v_mul_f32_e32 v64, v60, v60
	v_max_f32_e32 v60, v65, v65
; __device__ __forceinline__ unsigned cvt_pk_bf16(float lo, float hi) { unsigned r; asm("v_cvt_pk_bf16_f32 %0, %1, %2" : "=v"(r) : "v"(lo), "v"(hi)); return r; }
;     __device__ __forceinline__ void operator()(const f32x4 (&acc)[2][2][4][2], const Unit& u, int wr, int wc, int fr, int fq) const {
;     ...
;             for (int m = 0; m < 4; ++m) { bf16_t* rowp = O + (size_t)(row0 + ai * HALF + m * 16) * ldc + col0;
; #pragma unroll
;                 for (int bj = 0; bj < 2; ++bj) { f32x4 v0 = acc[ai][bj][m][0], v1 = acc[ai][bj][m][1];
;                     if (ACT == 1) {
; #pragma unroll
;                         for (int j = 0; j < 4; ++j) { float a = fmaxf(v0[j], 0.f), b = fmaxf(v1[j], 0.f); v0[j] = a * a; v1[j] = b * b; } }
;                     u32x4 w; w.x = cvt_pk_bf16(v0[0], v0[1]); w.y = cvt_pk_bf16(v0[2], v0[3]); w.z = cvt_pk_bf16(v1[0], v1[1]); w.w = cvt_pk_bf16(v1[2], v1[3]);
;                     if (ACT == 1) __builtin_nontemporal_store(w, (u32x4*)(rowp + bj * HALF));
;                     else *(u32x4*)(rowp + bj * HALF) = w; } }
	v_mul_f32_e32 v62, v62, v62
	v_mul_f32_e32 v58, v58, v58
	v_max_f32_e32 v59, 0, v59
	v_max_f32_e32 v60, 0, v60
	v_max_f32_e32 v61, v61, v61
	s_mov_b32 s8, 0x200000
	v_mul_f32_e32 v59, v59, v59
	v_max_f32_e32 v61, 0, v61
	v_mul_f32_e32 v60, v60, v60
	v_cvt_pk_bf16_f32 v58, v62, v58
	v_add_co_u32_e32 v62, vcc, s8, v140
	v_max_f32_e32 v50, v50, v50
	v_max_f32_e32 v51, v51, v51
	v_max_f32_e32 v52, v52, v52
	v_mul_f32_e32 v61, v61, v61
	v_cvt_pk_bf16_f32 v59, v59, v60
	v_cvt_pk_bf16_f32 v60, v68, v63
	v_addc_co_u32_e32 v63, vcc, 0, v141, vcc
	v_max_f32_e32 v50, 0, v50
	v_max_f32_e32 v51, 0, v51
	v_max_f32_e32 v52, 0, v52
	v_cvt_pk_bf16_f32 v61, v64, v61
	global_store_dwordx4 v[62:63], v[58:61], off nt
	v_max_f32_e32 v53, v53, v53
	s_mov_b64 s[38:39], 0x200000
	v_mul_f32_e32 v58, v50, v50
	v_max_f32_e32 v50, v55, v55
	v_mul_f32_e32 v55, v51, v51
	v_max_f32_e32 v51, v56, v56
	v_mul_f32_e32 v56, v52, v52
	v_max_f32_e32 v52, v57, v57
	v_max_f32_e32 v51, 0, v51
	v_max_f32_e32 v52, 0, v52
	v_max_f32_e32 v54, v54, v54
	v_max_f32_e32 v50, 0, v50
	v_mul_f32_e32 v51, v51, v51
	v_max_f32_e32 v53, 0, v53
	v_mul_f32_e32 v52, v52, v52
	v_max_f32_e32 v42, v42, v42
	v_lshl_add_u64 v[66:67], v[140:141], 0, s[38:39]
	v_max_f32_e32 v54, 0, v54
	v_mul_f32_e32 v50, v50, v50
	v_mul_f32_e32 v53, v53, v53
	v_cvt_pk_bf16_f32 v51, v51, v52
	v_cvt_pk_bf16_f32 v52, v58, v55
	v_max_f32_e32 v42, 0, v42
	v_max_f32_e32 v43, v43, v43
	v_max_f32_e32 v44, v44, v44
	v_mul_f32_e32 v54, v54, v54
	v_cvt_pk_bf16_f32 v50, v54, v50
	v_cvt_pk_bf16_f32 v53, v56, v53
	global_store_dwordx4 v[66:67], v[50:53], off offset:256 nt
	v_max_f32_e32 v46, v46, v46
	v_max_f32_e32 v43, 0, v43
	v_mul_f32_e32 v52, v42, v42
	v_max_f32_e32 v42, v47, v47
	v_max_f32_e32 v44, 0, v44
	v_max_f32_e32 v46, 0, v46
	v_max_f32_e32 v42, 0, v42
	v_mul_f32_e32 v47, v43, v43
	v_max_f32_e32 v43, v48, v48
	v_mul_f32_e32 v48, v44, v44
	v_max_f32_e32 v44, v49, v49
	v_mul_f32_e32 v46, v46, v46
	v_mul_f32_e32 v42, v42, v42
	v_max_f32_e32 v43, 0, v43
	v_max_f32_e32 v44, 0, v44
	v_max_f32_e32 v45, v45, v45
	s_mov_b32 s8, 0x240000
	v_mul_f32_e32 v43, v43, v43
	v_max_f32_e32 v45, 0, v45
	v_mul_f32_e32 v44, v44, v44
	v_cvt_pk_bf16_f32 v42, v46, v42
	v_add_co_u32_e32 v46, vcc, s8, v140
	v_max_f32_e32 v34, v34, v34
	v_max_f32_e32 v35, v35, v35
	v_max_f32_e32 v36, v36, v36
	v_mul_f32_e32 v45, v45, v45
	v_cvt_pk_bf16_f32 v43, v43, v44
	v_cvt_pk_bf16_f32 v44, v52, v47
	v_addc_co_u32_e32 v47, vcc, 0, v141, vcc
	v_max_f32_e32 v34, 0, v34
	v_max_f32_e32 v35, 0, v35
	v_max_f32_e32 v36, 0, v36
	v_cvt_pk_bf16_f32 v45, v48, v45
	global_store_dwordx4 v[46:47], v[42:45], off nt
	v_max_f32_e32 v37, v37, v37
	s_mov_b64 s[38:39], 0x240000
	v_mul_f32_e32 v42, v34, v34
	v_max_f32_e32 v34, v39, v39
	v_mul_f32_e32 v39, v35, v35
	v_max_f32_e32 v35, v40, v40
	v_mul_f32_e32 v40, v36, v36
	v_max_f32_e32 v36, v41, v41
	v_max_f32_e32 v35, 0, v35
	v_max_f32_e32 v36, 0, v36
	v_max_f32_e32 v38, v38, v38
	v_max_f32_e32 v34, 0, v34
	v_mul_f32_e32 v35, v35, v35
	v_max_f32_e32 v37, 0, v37
	v_mul_f32_e32 v36, v36, v36
	v_max_f32_e32 v26, v26, v26
	v_lshl_add_u64 v[50:51], v[140:141], 0, s[38:39]
	v_max_f32_e32 v38, 0, v38
	v_mul_f32_e32 v34, v34, v34
	v_mul_f32_e32 v37, v37, v37
	v_cvt_pk_bf16_f32 v35, v35, v36
	v_cvt_pk_bf16_f32 v36, v42, v39
	v_max_f32_e32 v26, 0, v26
	v_max_f32_e32 v27, v27, v27
	v_max_f32_e32 v28, v28, v28
	v_mul_f32_e32 v38, v38, v38
	v_cvt_pk_bf16_f32 v34, v38, v34
	v_cvt_pk_bf16_f32 v37, v40, v37
	global_store_dwordx4 v[50:51], v[34:37], off offset:256 nt
	v_max_f32_e32 v30, v30, v30
	v_max_f32_e32 v27, 0, v27
	v_mul_f32_e32 v36, v26, v26
	v_max_f32_e32 v26, v31, v31
	v_max_f32_e32 v28, 0, v28
	v_max_f32_e32 v30, 0, v30
; __device__ __forceinline__ unsigned cvt_pk_bf16(float lo, float hi) { unsigned r; asm("v_cvt_pk_bf16_f32 %0, %1, %2" : "=v"(r) : "v"(lo), "v"(hi)); return r; }
;     __device__ __forceinline__ void operator()(const f32x4 (&acc)[2][2][4][2], const Unit& u, int wr, int wc, int fr, int fq) const {
;     ...
;             for (int m = 0; m < 4; ++m) { bf16_t* rowp = O + (size_t)(row0 + ai * HALF + m * 16) * ldc + col0;
; #pragma unroll
;                 for (int bj = 0; bj < 2; ++bj) { f32x4 v0 = acc[ai][bj][m][0], v1 = acc[ai][bj][m][1];
;                     if (ACT == 1) {
; #pragma unroll
;                         for (int j = 0; j < 4; ++j) { float a = fmaxf(v0[j], 0.f), b = fmaxf(v1[j], 0.f); v0[j] = a * a; v1[j] = b * b; } }
;                     u32x4 w; w.x = cvt_pk_bf16(v0[0], v0[1]); w.y = cvt_pk_bf16(v0[2], v0[3]); w.z = cvt_pk_bf16(v1[0], v1[1]); w.w = cvt_pk_bf16(v1[2], v1[3]);
;                     if (ACT == 1) __builtin_nontemporal_store(w, (u32x4*)(rowp + bj * HALF));
;                     else *(u32x4*)(rowp + bj * HALF) = w; } }
	v_max_f32_e32 v26, 0, v26
	v_mul_f32_e32 v31, v27, v27
	v_max_f32_e32 v27, v32, v32
	v_mul_f32_e32 v32, v28, v28
	v_max_f32_e32 v28, v33, v33
	v_mul_f32_e32 v30, v30, v30
	v_mul_f32_e32 v26, v26, v26
	v_max_f32_e32 v27, 0, v27
	v_max_f32_e32 v28, 0, v28
	v_max_f32_e32 v29, v29, v29
	s_mov_b32 s8, 0x280000
	v_mul_f32_e32 v27, v27, v27
	v_max_f32_e32 v29, 0, v29
	v_mul_f32_e32 v28, v28, v28
	v_cvt_pk_bf16_f32 v26, v30, v26
	v_add_co_u32_e32 v30, vcc, s8, v140
	v_max_f32_e32 v18, v18, v18
	v_max_f32_e32 v19, v19, v19
	v_max_f32_e32 v20, v20, v20
	v_mul_f32_e32 v29, v29, v29
	v_cvt_pk_bf16_f32 v27, v27, v28
	v_cvt_pk_bf16_f32 v28, v36, v31
	v_addc_co_u32_e32 v31, vcc, 0, v141, vcc
	v_max_f32_e32 v18, 0, v18
	v_max_f32_e32 v19, 0, v19
	v_max_f32_e32 v20, 0, v20
	v_cvt_pk_bf16_f32 v29, v32, v29
	global_store_dwordx4 v[30:31], v[26:29], off nt
	v_max_f32_e32 v21, v21, v21
	s_mov_b64 s[38:39], 0x280000
	v_mul_f32_e32 v26, v18, v18
	v_max_f32_e32 v18, v23, v23
	v_mul_f32_e32 v23, v19, v19
	v_max_f32_e32 v19, v24, v24
	v_mul_f32_e32 v24, v20, v20
	v_max_f32_e32 v20, v25, v25
	v_max_f32_e32 v19, 0, v19
	v_max_f32_e32 v20, 0, v20
	v_max_f32_e32 v22, v22, v22
	v_max_f32_e32 v18, 0, v18
	v_mul_f32_e32 v19, v19, v19
	v_max_f32_e32 v21, 0, v21
	v_mul_f32_e32 v20, v20, v20
	v_max_f32_e32 v10, v10, v10
	v_lshl_add_u64 v[34:35], v[140:141], 0, s[38:39]
	v_max_f32_e32 v22, 0, v22
	v_mul_f32_e32 v18, v18, v18
	v_mul_f32_e32 v21, v21, v21
	v_cvt_pk_bf16_f32 v19, v19, v20
	v_cvt_pk_bf16_f32 v20, v26, v23
	v_max_f32_e32 v10, 0, v10
	v_max_f32_e32 v11, v11, v11
	v_max_f32_e32 v12, v12, v12
	v_mul_f32_e32 v22, v22, v22
	v_cvt_pk_bf16_f32 v18, v22, v18
	v_cvt_pk_bf16_f32 v21, v24, v21
	global_store_dwordx4 v[34:35], v[18:21], off offset:256 nt
	v_max_f32_e32 v14, v14, v14
	v_max_f32_e32 v11, 0, v11
	v_mul_f32_e32 v20, v10, v10
	v_max_f32_e32 v10, v15, v15
	v_max_f32_e32 v12, 0, v12
	v_max_f32_e32 v14, 0, v14
	v_max_f32_e32 v10, 0, v10
	v_mul_f32_e32 v15, v11, v11
	v_max_f32_e32 v11, v16, v16
	v_mul_f32_e32 v16, v12, v12
	v_max_f32_e32 v12, v17, v17
	v_mul_f32_e32 v14, v14, v14
	v_mul_f32_e32 v10, v10, v10
	v_max_f32_e32 v11, 0, v11
	v_max_f32_e32 v12, 0, v12
	v_max_f32_e32 v13, v13, v13
	s_mov_b32 s8, 0x2c0000
	v_mul_f32_e32 v11, v11, v11
	v_max_f32_e32 v13, 0, v13
	v_mul_f32_e32 v12, v12, v12
	v_cvt_pk_bf16_f32 v10, v14, v10
	v_add_co_u32_e32 v14, vcc, s8, v140
	v_max_f32_e32 v2, v2, v2
	v_max_f32_e32 v3, v3, v3
	v_max_f32_e32 v4, v4, v4
	v_mul_f32_e32 v13, v13, v13
	v_cvt_pk_bf16_f32 v11, v11, v12
	v_cvt_pk_bf16_f32 v12, v20, v15
	v_addc_co_u32_e32 v15, vcc, 0, v141, vcc
	v_max_f32_e32 v2, 0, v2
	v_max_f32_e32 v3, 0, v3
	v_max_f32_e32 v4, 0, v4
	v_cvt_pk_bf16_f32 v13, v16, v13
	global_store_dwordx4 v[14:15], v[10:13], off nt
	v_max_f32_e32 v5, v5, v5
	s_mov_b64 s[38:39], 0x2c0000
	v_mul_f32_e32 v10, v2, v2
	v_max_f32_e32 v2, v7, v7
	v_mul_f32_e32 v7, v3, v3
	v_max_f32_e32 v3, v8, v8
	v_mul_f32_e32 v8, v4, v4
	v_max_f32_e32 v4, v9, v9
	v_max_f32_e32 v6, v6, v6
	v_max_f32_e32 v2, 0, v2
	v_max_f32_e32 v3, 0, v3
	v_max_f32_e32 v4, 0, v4
	v_max_f32_e32 v5, 0, v5
	v_lshl_add_u64 v[18:19], v[140:141], 0, s[38:39]
	v_max_f32_e32 v6, 0, v6
	v_mul_f32_e32 v2, v2, v2
	v_mul_f32_e32 v3, v3, v3
	v_mul_f32_e32 v4, v4, v4
	v_mul_f32_e32 v5, v5, v5
	s_and_b64 vcc, exec, s[40:41]
	s_mov_b32 s68, s26
	s_mov_b32 s8, s28
	s_mov_b64 s[46:47], s[44:45]
	s_mov_b64 s[48:49], s[42:43]
	v_mul_f32_e32 v6, v6, v6
	v_cvt_pk_bf16_f32 v2, v6, v2
	v_cvt_pk_bf16_f32 v3, v3, v4
	v_cvt_pk_bf16_f32 v4, v10, v7
	v_cvt_pk_bf16_f32 v5, v8, v5
	global_store_dwordx4 v[18:19], v[2:5], off offset:256 nt
	s_cbranch_vccz .LBB0_70
	s_waitcnt vmcnt(0)
	s_cmpk_gt_u32 s52, 0xff
	s_cbranch_scc1 .LBB0_77
	s_barrier

; #define PG8_STAGE(bufoff, gbase, voff) do { _Pragma("unroll") for (int _i = 0; _i < 2; ++_i) \
;         __builtin_amdgcn_global_load_lds((const unsigned*)((const char*)(gbase) + (voff)[_i]), (LAS unsigned*)(lds + (bufoff) + ldsw + _i * 8192), 16, 0, 0); } while (0)
; #define PG8_LDA(dst, b, h) do { _Pragma("unroll") for (int m = 0; m < 4; ++m) _Pragma("unroll") for (int k = 0; k < 2; ++k) dst[m][k] = *(const LAS bf16x8*)(lds + PG8_SA(b, h) + aoff + m * 2048 + k * 1024); } while (0)
; #define PG8_LDB(dst, b, h) do { _Pragma("unroll") for (int n = 0; n < 2; ++n) _Pragma("unroll") for (int k = 0; k < 2; ++k) dst[n][k] = *(const LAS bf16x8*)(lds + PG8_SB(b, h) + boff + n * 2048 + k * 1024); } while (0)
; #define PG8_MMA(ai, bj, At, Bt) do { __builtin_amdgcn_s_setprio(1); _Pragma("unroll") for (int m = 0; m < 4; ++m) _Pragma("unroll") for (int n = 0; n < 2; ++n) _Pragma("unroll") for (int k = 0; k < 2; ++k) \
;         acc[ai][bj][m][n] = __builtin_amdgcn_mfma_f32_16x16x32_bf16(Bt[n][k], At[m][k], acc[ai][bj][m][n], 0, 0, 0); __builtin_amdgcn_s_setprio(0); } while (0)
; #define PG8_WAIT_L(n) asm volatile("s_waitcnt lgkmcnt(" #n ")" ::: "memory")
; #define PG8_BAR __builtin_amdgcn_s_barrier()
; #define PG8_SCHED __builtin_amdgcn_sched_barrier(0)
; template <class Epi, class Sched>
; __device__ __forceinline__ void gemm_phase(LAS unsigned char* lds, const Gemm g, const Sched& S, const Epi& E) {
;     ...
;         for (int t = 0; t < nt; t += 2) {
;             const bool last = (t == nt - 2);
;             const char* a1 = cA + (size_t)(t + 1) * kstep;
;             const char* a2 = last ? nA : cA + (size_t)(t + 2) * kstep; const char* b2 = last ? nB : cB + (size_t)(t + 2) * kstep;
;             const char* a3 = a2 + kstep; const char* b3 = b2 + kstep;
;             PG8_LDB(B0, 0, 0); PG8_SCHED; PG8_LDA(At, 0, 0); PG8_STAGE(PG8_SA(1, 1), a1 + hstep, voffA);
;             PG8_WAIT_L(8); PG8_BAR; PG8_WAIT_L(0); PG8_MMA(0, 0, At, B0); PG8_BAR; PG8_SCHED;
;             PG8_LDB(B1, 0, 1); PG8_STAGE(PG8_SB(0, 0), b2, voffB);
;             PG8_BAR; PG8_WAIT_L(0); PG8_MMA(0, 1, At, B1); PG8_BAR;
;             PG8_LDA(At, 0, 1); PG8_STAGE(PG8_SA(0, 0), a2, voffA);
;             PG8_BAR; PG8_WAIT_L(0); PG8_MMA(1, 0, At, B0); PG8_BAR; PG8_SCHED;
.LBB0_99:
	s_add_u32 s56, s28, 0x100
	s_addc_u32 s57, s29, 0
	s_cmp_eq_u32 s81, 28
	s_cselect_b32 s61, s51, s57
	s_cselect_b32 s60, s77, s56
	s_cselect_b32 s59, s49, s80
	s_cselect_b32 s58, s78, s79
	v_lshl_add_u64 v[156:157], s[28:29], 0, v[150:151]
	s_add_i32 m0, s9, 0xc000
	s_nop 0
	global_load_lds_dwordx4 v[156:157], off
	v_lshl_add_u64 v[156:157], s[28:29], 0, v[148:149]
	s_add_i32 m0, s9, 0xe000
	s_nop 0
	global_load_lds_dwordx4 v[156:157], off
	s_add_i32 s38, 0, 0x10000
	v_add_u32_e32 v110, s38, v169
	ds_read_b128 v[98:101], v110
	ds_read_b128 v[102:105], v110 offset:1024
	ds_read_b128 v[106:109], v110 offset:2048
	ds_read_b128 v[110:113], v110 offset:3072
	ds_read_b128 v[152:155], v171
	ds_read_b128 v[160:163], v171 offset:1024
	ds_read_b128 v[164:167], v171 offset:2048
	ds_read_b128 v[172:175], v171 offset:3072
	ds_read_b128 v[176:179], v171 offset:4096
	ds_read_b128 v[180:183], v171 offset:5120
	ds_read_b128 v[184:187], v171 offset:6144
	ds_read_b128 v[188:191], v171 offset:7168
	s_add_i32 s39, 0, 0x14000
	v_add_u32_e32 v156, s39, v169
	ds_read_b128 v[192:195], v156
	ds_read_b128 v[196:199], v156 offset:1024
	ds_read_b128 v[200:203], v156 offset:2048
	ds_read_b128 v[204:207], v156 offset:3072
	s_waitcnt lgkmcnt(4)
	s_barrier
	s_waitcnt lgkmcnt(0)
	v_mfma_f32_16x16x32_bf16 v[142:145], v[98:101], v[152:155], v[142:145]
	v_mfma_f32_16x16x32_bf16 v[138:141], v[106:109], v[152:155], v[138:141]
	v_mfma_f32_16x16x32_bf16 v[126:129], v[98:101], v[164:167], v[126:129]
	v_mfma_f32_16x16x32_bf16 v[122:125], v[106:109], v[164:167], v[122:125]
	v_mfma_f32_16x16x32_bf16 v[94:97], v[98:101], v[176:179], v[94:97]
	v_mfma_f32_16x16x32_bf16 v[90:93], v[106:109], v[176:179], v[90:93]
	v_mfma_f32_16x16x32_bf16 v[86:89], v[98:101], v[184:187], v[86:89]
	v_mfma_f32_16x16x32_bf16 v[82:85], v[106:109], v[184:187], v[82:85]
	v_mfma_f32_16x16x32_bf16 v[142:145], v[102:105], v[160:163], v[142:145]
	v_mfma_f32_16x16x32_bf16 v[138:141], v[110:113], v[160:163], v[138:141]
	v_mfma_f32_16x16x32_bf16 v[126:129], v[102:105], v[172:175], v[126:129]
	v_mfma_f32_16x16x32_bf16 v[122:125], v[110:113], v[172:175], v[122:125]
	v_mfma_f32_16x16x32_bf16 v[94:97], v[102:105], v[180:183], v[94:97]
	v_mfma_f32_16x16x32_bf16 v[90:93], v[110:113], v[180:183], v[90:93]
	v_mfma_f32_16x16x32_bf16 v[86:89], v[102:105], v[188:191], v[86:89]
	v_mfma_f32_16x16x32_bf16 v[82:85], v[110:113], v[188:191], v[82:85]
	v_mfma_f32_16x16x32_bf16 v[134:137], v[192:195], v[152:155], v[134:137]
	v_mfma_f32_16x16x32_bf16 v[130:133], v[200:203], v[152:155], v[130:133]
	v_mfma_f32_16x16x32_bf16 v[118:121], v[192:195], v[164:167], v[118:121]
	v_mfma_f32_16x16x32_bf16 v[114:117], v[200:203], v[164:167], v[114:117]
	v_mfma_f32_16x16x32_bf16 v[78:81], v[192:195], v[176:179], v[78:81]
	v_mfma_f32_16x16x32_bf16 v[74:77], v[200:203], v[176:179], v[74:77]
	v_mfma_f32_16x16x32_bf16 v[70:73], v[192:195], v[184:187], v[70:73]
	v_mfma_f32_16x16x32_bf16 v[66:69], v[200:203], v[184:187], v[66:69]
	v_mfma_f32_16x16x32_bf16 v[134:137], v[196:199], v[160:163], v[134:137]
	v_mfma_f32_16x16x32_bf16 v[130:133], v[204:207], v[160:163], v[130:133]
	v_mfma_f32_16x16x32_bf16 v[118:121], v[196:199], v[172:175], v[118:121]
	v_mfma_f32_16x16x32_bf16 v[114:117], v[204:207], v[172:175], v[114:117]
	v_mfma_f32_16x16x32_bf16 v[78:81], v[196:199], v[180:183], v[78:81]
	v_mfma_f32_16x16x32_bf16 v[74:77], v[204:207], v[180:183], v[74:77]
	v_mfma_f32_16x16x32_bf16 v[70:73], v[196:199], v[188:191], v[70:73]
	v_mfma_f32_16x16x32_bf16 v[66:69], v[204:207], v[188:191], v[66:69]
	s_barrier
	s_add_i32 s28, s38, s67
	v_lshl_add_u64 v[156:157], s[58:59], 0, v[0:1]
	s_mov_b32 m0, s28
	v_lshl_add_u64 v[210:211], s[58:59], 0, v[146:147]
	global_load_lds_dwordx4 v[156:157], off
	s_add_i32 m0, s28, 0x2000
	s_nop 0
	global_load_lds_dwordx4 v[210:211], off
	s_mov_b32 m0, s9
	v_lshl_add_u64 v[212:213], s[60:61], 0, v[0:1]
	global_load_lds_dwordx4 v[212:213], off
	v_lshl_add_u64 v[214:215], s[60:61], 0, v[146:147]
	s_mov_b32 m0, s68
	s_nop 0
	global_load_lds_dwordx4 v[214:215], off
	ds_read_b128 v[152:155], v171 offset:16384
	ds_read_b128 v[160:163], v171 offset:17408
	ds_read_b128 v[164:167], v171 offset:18432
	ds_read_b128 v[172:175], v171 offset:19456
	ds_read_b128 v[176:179], v171 offset:20480
	ds_read_b128 v[180:183], v171 offset:21504
	ds_read_b128 v[184:187], v171 offset:22528
	ds_read_b128 v[188:191], v171 offset:23552
	s_waitcnt vmcnt(4)
	s_waitcnt lgkmcnt(0)
	s_barrier
	v_mfma_f32_16x16x32_bf16 v[62:65], v[98:101], v[152:155], v[62:65]
	v_mfma_f32_16x16x32_bf16 v[58:61], v[106:109], v[152:155], v[58:61]
	v_mfma_f32_16x16x32_bf16 v[46:49], v[98:101], v[164:167], v[46:49]
	v_mfma_f32_16x16x32_bf16 v[42:45], v[106:109], v[164:167], v[42:45]
	v_mfma_f32_16x16x32_bf16 v[30:33], v[98:101], v[176:179], v[30:33]
	v_mfma_f32_16x16x32_bf16 v[26:29], v[106:109], v[176:179], v[26:29]
	v_mfma_f32_16x16x32_bf16 v[22:25], v[98:101], v[184:187], v[22:25]
	v_mfma_f32_16x16x32_bf16 v[18:21], v[106:109], v[184:187], v[18:21]
	v_mfma_f32_16x16x32_bf16 v[62:65], v[102:105], v[160:163], v[62:65]
	v_mfma_f32_16x16x32_bf16 v[58:61], v[110:113], v[160:163], v[58:61]
	v_mfma_f32_16x16x32_bf16 v[46:49], v[102:105], v[172:175], v[46:49]
	v_mfma_f32_16x16x32_bf16 v[42:45], v[110:113], v[172:175], v[42:45]
	v_mfma_f32_16x16x32_bf16 v[30:33], v[102:105], v[180:183], v[30:33]
	v_mfma_f32_16x16x32_bf16 v[26:29], v[110:113], v[180:183], v[26:29]
	v_mfma_f32_16x16x32_bf16 v[22:25], v[102:105], v[188:191], v[22:25]
	v_mfma_f32_16x16x32_bf16 v[18:21], v[110:113], v[188:191], v[18:21]
	v_mfma_f32_16x16x32_bf16 v[54:57], v[192:195], v[152:155], v[54:57]
	v_mfma_f32_16x16x32_bf16 v[50:53], v[200:203], v[152:155], v[50:53]
	v_mfma_f32_16x16x32_bf16 v[38:41], v[192:195], v[164:167], v[38:41]
	v_mfma_f32_16x16x32_bf16 v[34:37], v[200:203], v[164:167], v[34:37]
	v_mfma_f32_16x16x32_bf16 v[14:17], v[192:195], v[176:179], v[14:17]
	v_mfma_f32_16x16x32_bf16 v[10:13], v[200:203], v[176:179], v[10:13]
	v_mfma_f32_16x16x32_bf16 v[6:9], v[192:195], v[184:187], v[6:9]
	v_mfma_f32_16x16x32_bf16 v[2:5], v[200:203], v[184:187], v[2:5]
	v_mfma_f32_16x16x32_bf16 v[54:57], v[196:199], v[160:163], v[54:57]
	v_mfma_f32_16x16x32_bf16 v[50:53], v[204:207], v[160:163], v[50:53]
	v_mfma_f32_16x16x32_bf16 v[38:41], v[196:199], v[172:175], v[38:41]
	v_mfma_f32_16x16x32_bf16 v[34:37], v[204:207], v[172:175], v[34:37]
	v_mfma_f32_16x16x32_bf16 v[14:17], v[196:199], v[180:183], v[14:17]
	v_mfma_f32_16x16x32_bf16 v[10:13], v[204:207], v[180:183], v[10:13]
	v_mfma_f32_16x16x32_bf16 v[6:9], v[196:199], v[188:191], v[6:9]
	v_mfma_f32_16x16x32_bf16 v[2:5], v[204:207], v[188:191], v[2:5]
	s_barrier
; #define PG8_STAGE(bufoff, gbase, voff) do { _Pragma("unroll") for (int _i = 0; _i < 2; ++_i) \
;         __builtin_amdgcn_global_load_lds((const unsigned*)((const char*)(gbase) + (voff)[_i]), (LAS unsigned*)(lds + (bufoff) + ldsw + _i * 8192), 16, 0, 0); } while (0)
; #define PG8_LDA(dst, b, h) do { _Pragma("unroll") for (int m = 0; m < 4; ++m) _Pragma("unroll") for (int k = 0; k < 2; ++k) dst[m][k] = *(const LAS bf16x8*)(lds + PG8_SA(b, h) + aoff + m * 2048 + k * 1024); } while (0)
; #define PG8_LDB(dst, b, h) do { _Pragma("unroll") for (int n = 0; n < 2; ++n) _Pragma("unroll") for (int k = 0; k < 2; ++k) dst[n][k] = *(const LAS bf16x8*)(lds + PG8_SB(b, h) + boff + n * 2048 + k * 1024); } while (0)
; #define PG8_MMA(ai, bj, At, Bt) do { __builtin_amdgcn_s_setprio(1); _Pragma("unroll") for (int m = 0; m < 4; ++m) _Pragma("unroll") for (int n = 0; n < 2; ++n) _Pragma("unroll") for (int k = 0; k < 2; ++k) \
;         acc[ai][bj][m][n] = __builtin_amdgcn_mfma_f32_16x16x32_bf16(Bt[n][k], At[m][k], acc[ai][bj][m][n], 0, 0, 0); __builtin_amdgcn_s_setprio(0); } while (0)
; #define PG8_WAIT_V(n) asm volatile("s_waitcnt vmcnt(" #n ")" ::: "memory")
; #define PG8_WAIT_L(n) asm volatile("s_waitcnt lgkmcnt(" #n ")" ::: "memory")
; #define PG8_BAR __builtin_amdgcn_s_barrier()
; #define PG8_SCHED __builtin_amdgcn_sched_barrier(0)
; template <class Epi, class Sched>
; __device__ __forceinline__ void gemm_phase(LAS unsigned char* lds, const Gemm g, const Sched& S, const Epi& E) {
;     ...
;             PG8_STAGE(PG8_SB(0, 1), b2 + hstep, voffB);
;             PG8_WAIT_V(6); PG8_BAR; PG8_MMA(1, 1, At, B1); PG8_BAR;
;             PG8_LDB(B0, 1, 0); PG8_SCHED; PG8_LDA(At, 1, 0); PG8_STAGE(PG8_SA(0, 1), a2 + hstep, voffA);
;             PG8_WAIT_L(8); PG8_BAR; PG8_WAIT_L(0); PG8_MMA(0, 0, At, B0); PG8_BAR; PG8_SCHED;
	s_add_u32 s28, s58, 0x80000
	s_addc_u32 s29, s59, 0
	s_add_i32 s38, s39, s67
	v_lshl_add_u64 v[98:99], s[28:29], 0, v[0:1]
	s_mov_b32 m0, s38
	s_nop 0
	global_load_lds_dwordx4 v[98:99], off
	v_lshl_add_u64 v[98:99], s[28:29], 0, v[146:147]
	s_add_i32 m0, s38, 0x2000
	s_nop 0
	global_load_lds_dwordx4 v[98:99], off
	s_add_u32 s28, s60, 0x80000
	s_addc_u32 s29, s61, 0
	s_mov_b32 m0, s69
	v_lshl_add_u64 v[192:193], s[28:29], 0, v[0:1]
	global_load_lds_dwordx4 v[192:193], off
	v_lshl_add_u64 v[192:193], s[28:29], 0, v[146:147]
	s_mov_b32 m0, s70
	s_nop 0
	global_load_lds_dwordx4 v[192:193], off
	s_add_i32 s38, 0, 0x18000
	v_add_u32_e32 v110, s38, v169
	ds_read_b128 v[98:101], v110
	ds_read_b128 v[102:105], v110 offset:1024
	ds_read_b128 v[106:109], v110 offset:2048
	ds_read_b128 v[110:113], v110 offset:3072
	ds_read_b128 v[152:155], v171 offset:32768
	ds_read_b128 v[160:163], v171 offset:33792
	ds_read_b128 v[164:167], v171 offset:34816
	ds_read_b128 v[172:175], v171 offset:35840
	ds_read_b128 v[176:179], v171 offset:36864
	ds_read_b128 v[180:183], v171 offset:37888
	ds_read_b128 v[184:187], v171 offset:38912
	ds_read_b128 v[188:191], v171 offset:39936
	s_add_i32 s39, 0, 0x1c000
	v_add_u32_e32 v204, s39, v169
	ds_read_b128 v[192:195], v204
	ds_read_b128 v[196:199], v204 offset:1024
	ds_read_b128 v[200:203], v204 offset:2048
	ds_read_b128 v[204:207], v204 offset:3072
	s_waitcnt lgkmcnt(4)
	s_barrier
	s_waitcnt lgkmcnt(0)
	v_mfma_f32_16x16x32_bf16 v[142:145], v[98:101], v[152:155], v[142:145]
	v_mfma_f32_16x16x32_bf16 v[138:141], v[106:109], v[152:155], v[138:141]
	v_mfma_f32_16x16x32_bf16 v[126:129], v[98:101], v[164:167], v[126:129]
	v_mfma_f32_16x16x32_bf16 v[122:125], v[106:109], v[164:167], v[122:125]
	v_mfma_f32_16x16x32_bf16 v[94:97], v[98:101], v[176:179], v[94:97]
	v_mfma_f32_16x16x32_bf16 v[90:93], v[106:109], v[176:179], v[90:93]
	v_mfma_f32_16x16x32_bf16 v[86:89], v[98:101], v[184:187], v[86:89]
	v_mfma_f32_16x16x32_bf16 v[82:85], v[106:109], v[184:187], v[82:85]
	v_mfma_f32_16x16x32_bf16 v[142:145], v[102:105], v[160:163], v[142:145]
	v_mfma_f32_16x16x32_bf16 v[138:141], v[110:113], v[160:163], v[138:141]
	v_mfma_f32_16x16x32_bf16 v[126:129], v[102:105], v[172:175], v[126:129]
	v_mfma_f32_16x16x32_bf16 v[122:125], v[110:113], v[172:175], v[122:125]
	v_mfma_f32_16x16x32_bf16 v[94:97], v[102:105], v[180:183], v[94:97]
	v_mfma_f32_16x16x32_bf16 v[90:93], v[110:113], v[180:183], v[90:93]
	v_mfma_f32_16x16x32_bf16 v[86:89], v[102:105], v[188:191], v[86:89]
	v_mfma_f32_16x16x32_bf16 v[82:85], v[110:113], v[188:191], v[82:85]
	v_mfma_f32_16x16x32_bf16 v[134:137], v[192:195], v[152:155], v[134:137]
	v_mfma_f32_16x16x32_bf16 v[130:133], v[200:203], v[152:155], v[130:133]
	v_mfma_f32_16x16x32_bf16 v[118:121], v[192:195], v[164:167], v[118:121]
	v_mfma_f32_16x16x32_bf16 v[114:117], v[200:203], v[164:167], v[114:117]
	v_mfma_f32_16x16x32_bf16 v[78:81], v[192:195], v[176:179], v[78:81]
	v_mfma_f32_16x16x32_bf16 v[74:77], v[200:203], v[176:179], v[74:77]
	v_mfma_f32_16x16x32_bf16 v[70:73], v[192:195], v[184:187], v[70:73]
	v_mfma_f32_16x16x32_bf16 v[66:69], v[200:203], v[184:187], v[66:69]
	v_mfma_f32_16x16x32_bf16 v[134:137], v[196:199], v[160:163], v[134:137]
	v_mfma_f32_16x16x32_bf16 v[130:133], v[204:207], v[160:163], v[130:133]
	v_mfma_f32_16x16x32_bf16 v[118:121], v[196:199], v[172:175], v[118:121]
	v_mfma_f32_16x16x32_bf16 v[114:117], v[204:207], v[172:175], v[114:117]
	v_mfma_f32_16x16x32_bf16 v[78:81], v[196:199], v[180:183], v[78:81]
	v_mfma_f32_16x16x32_bf16 v[74:77], v[204:207], v[180:183], v[74:77]
	v_mfma_f32_16x16x32_bf16 v[70:73], v[196:199], v[188:191], v[70:73]
	v_mfma_f32_16x16x32_bf16 v[66:69], v[204:207], v[188:191], v[66:69]
	s_barrier
; #define PG8_STAGE(bufoff, gbase, voff) do { _Pragma("unroll") for (int _i = 0; _i < 2; ++_i) \
;         __builtin_amdgcn_global_load_lds((const unsigned*)((const char*)(gbase) + (voff)[_i]), (LAS unsigned*)(lds + (bufoff) + ldsw + _i * 8192), 16, 0, 0); } while (0)
; #define PG8_LDA(dst, b, h) do { _Pragma("unroll") for (int m = 0; m < 4; ++m) _Pragma("unroll") for (int k = 0; k < 2; ++k) dst[m][k] = *(const LAS bf16x8*)(lds + PG8_SA(b, h) + aoff + m * 2048 + k * 1024); } while (0)
; #define PG8_LDB(dst, b, h) do { _Pragma("unroll") for (int n = 0; n < 2; ++n) _Pragma("unroll") for (int k = 0; k < 2; ++k) dst[n][k] = *(const LAS bf16x8*)(lds + PG8_SB(b, h) + boff + n * 2048 + k * 1024); } while (0)
; #define PG8_MMA(ai, bj, At, Bt) do { __builtin_amdgcn_s_setprio(1); _Pragma("unroll") for (int m = 0; m < 4; ++m) _Pragma("unroll") for (int n = 0; n < 2; ++n) _Pragma("unroll") for (int k = 0; k < 2; ++k) \
;         acc[ai][bj][m][n] = __builtin_amdgcn_mfma_f32_16x16x32_bf16(Bt[n][k], At[m][k], acc[ai][bj][m][n], 0, 0, 0); __builtin_amdgcn_s_setprio(0); } while (0)
; #define PG8_WAIT_V(n) asm volatile("s_waitcnt vmcnt(" #n ")" ::: "memory")
; #define PG8_WAIT_L(n) asm volatile("s_waitcnt lgkmcnt(" #n ")" ::: "memory")
; #define PG8_BAR __builtin_amdgcn_s_barrier()
; #define PG8_SCHED __builtin_amdgcn_sched_barrier(0)
; template <class Epi, class Sched>
; __device__ __forceinline__ void gemm_phase(LAS unsigned char* lds, const Gemm g, const Sched& S, const Epi& E) {
;     ...
;             PG8_LDB(B0, 1, 0); PG8_SCHED; PG8_LDA(At, 1, 0); PG8_STAGE(PG8_SA(0, 1), a2 + hstep, voffA);
;             PG8_WAIT_L(8); PG8_BAR; PG8_WAIT_L(0); PG8_MMA(0, 0, At, B0); PG8_BAR; PG8_SCHED;
;             PG8_LDB(B1, 1, 1); PG8_STAGE(PG8_SB(1, 0), b3, voffB);
;             PG8_BAR; PG8_WAIT_L(0); PG8_MMA(0, 1, At, B1); PG8_BAR;
;             PG8_LDA(At, 1, 1); PG8_STAGE(PG8_SA(1, 0), a3, voffA);
;             PG8_BAR; PG8_WAIT_L(0); PG8_MMA(1, 0, At, B0); PG8_BAR; PG8_SCHED;
;             PG8_STAGE(PG8_SB(1, 1), b3 + hstep, voffB);
;             PG8_WAIT_V(6); PG8_BAR; PG8_MMA(1, 1, At, B1); PG8_BAR;
	s_add_i32 s28, s38, s67
	v_lshl_add_u64 v[156:157], v[156:157], 0, s[36:37]
	s_mov_b32 m0, s28
	s_nop 0
	global_load_lds_dwordx4 v[156:157], off
	v_lshl_add_u64 v[156:157], v[210:211], 0, s[36:37]
	s_add_i32 m0, s28, 0x2000
	s_nop 0
	global_load_lds_dwordx4 v[156:157], off
	s_mov_b32 m0, s72
	v_lshl_add_u64 v[156:157], v[212:213], 0, s[36:37]
	global_load_lds_dwordx4 v[156:157], off
	v_lshl_add_u64 v[156:157], v[214:215], 0, s[36:37]
	s_mov_b32 m0, s73
	s_nop 0
	global_load_lds_dwordx4 v[156:157], off
	ds_read_b128 v[152:155], v171 offset:49152
	ds_read_b128 v[160:163], v171 offset:50176
	ds_read_b128 v[164:167], v171 offset:51200
	ds_read_b128 v[172:175], v171 offset:52224
	ds_read_b128 v[176:179], v171 offset:53248
	ds_read_b128 v[180:183], v171 offset:54272
	ds_read_b128 v[184:187], v171 offset:55296
	ds_read_b128 v[188:191], v171 offset:56320
	s_waitcnt vmcnt(4)
	s_waitcnt lgkmcnt(0)
	s_barrier
	v_mfma_f32_16x16x32_bf16 v[62:65], v[98:101], v[152:155], v[62:65]
	v_mfma_f32_16x16x32_bf16 v[58:61], v[106:109], v[152:155], v[58:61]
	v_mfma_f32_16x16x32_bf16 v[46:49], v[98:101], v[164:167], v[46:49]
	v_mfma_f32_16x16x32_bf16 v[42:45], v[106:109], v[164:167], v[42:45]
	v_mfma_f32_16x16x32_bf16 v[30:33], v[98:101], v[176:179], v[30:33]
	v_mfma_f32_16x16x32_bf16 v[26:29], v[106:109], v[176:179], v[26:29]
	v_mfma_f32_16x16x32_bf16 v[22:25], v[98:101], v[184:187], v[22:25]
	v_mfma_f32_16x16x32_bf16 v[18:21], v[106:109], v[184:187], v[18:21]
	v_mfma_f32_16x16x32_bf16 v[62:65], v[102:105], v[160:163], v[62:65]
	v_mfma_f32_16x16x32_bf16 v[58:61], v[110:113], v[160:163], v[58:61]
	v_mfma_f32_16x16x32_bf16 v[46:49], v[102:105], v[172:175], v[46:49]
	v_mfma_f32_16x16x32_bf16 v[42:45], v[110:113], v[172:175], v[42:45]
	v_mfma_f32_16x16x32_bf16 v[30:33], v[102:105], v[180:183], v[30:33]
	v_mfma_f32_16x16x32_bf16 v[26:29], v[110:113], v[180:183], v[26:29]
	v_mfma_f32_16x16x32_bf16 v[22:25], v[102:105], v[188:191], v[22:25]
	v_mfma_f32_16x16x32_bf16 v[18:21], v[110:113], v[188:191], v[18:21]
	s_add_u32 s28, s58, 0x80080
	s_addc_u32 s29, s59, 0
	s_add_i32 s38, s39, s67
	v_lshl_add_u64 v[98:99], s[28:29], 0, v[0:1]
	s_mov_b32 m0, s38
	s_nop 0
	global_load_lds_dwordx4 v[98:99], off
	v_lshl_add_u64 v[98:99], s[28:29], 0, v[146:147]
	s_add_i32 m0, s38, 0x2000
	s_nop 0
	global_load_lds_dwordx4 v[98:99], off
	v_mfma_f32_16x16x32_bf16 v[54:57], v[192:195], v[152:155], v[54:57]
	v_mfma_f32_16x16x32_bf16 v[50:53], v[200:203], v[152:155], v[50:53]
	v_mfma_f32_16x16x32_bf16 v[38:41], v[192:195], v[164:167], v[38:41]
	v_mfma_f32_16x16x32_bf16 v[34:37], v[200:203], v[164:167], v[34:37]
	v_mfma_f32_16x16x32_bf16 v[14:17], v[192:195], v[176:179], v[14:17]
	v_mfma_f32_16x16x32_bf16 v[10:13], v[200:203], v[176:179], v[10:13]
	v_mfma_f32_16x16x32_bf16 v[6:9], v[192:195], v[184:187], v[6:9]
	v_mfma_f32_16x16x32_bf16 v[2:5], v[200:203], v[184:187], v[2:5]
	v_mfma_f32_16x16x32_bf16 v[54:57], v[196:199], v[160:163], v[54:57]
	v_mfma_f32_16x16x32_bf16 v[50:53], v[204:207], v[160:163], v[50:53]
	v_mfma_f32_16x16x32_bf16 v[38:41], v[196:199], v[172:175], v[38:41]
	v_mfma_f32_16x16x32_bf16 v[34:37], v[204:207], v[172:175], v[34:37]
	v_mfma_f32_16x16x32_bf16 v[14:17], v[196:199], v[180:183], v[14:17]
	v_mfma_f32_16x16x32_bf16 v[10:13], v[204:207], v[180:183], v[10:13]
	v_mfma_f32_16x16x32_bf16 v[6:9], v[196:199], v[188:191], v[6:9]
	v_mfma_f32_16x16x32_bf16 v[2:5], v[204:207], v[188:191], v[2:5]
	s_add_i32 s81, s81, 2
	s_add_u32 s79, s79, 0x100
	s_addc_u32 s80, s80, 0
	s_cmp_gt_u32 s81, 29
	s_mov_b64 s[28:29], s[56:57]
	s_barrier
	s_cbranch_scc0 .LBB0_99
	s_cmp_lt_i32 s8, 64
	s_cselect_b64 s[58:59], -1, 0
	s_cmp_gt_i32 s8, 63
	s_cbranch_scc0 .LBB0_90
	s_mov_b64 s[60:61], 0x18000
	s_mov_b64 s[28:29], s[46:47]
	s_mov_b64 s[56:57], s[24:25]
	s_branch .LBB0_91

; #define PG8_STAGE(bufoff, gbase, voff) do { _Pragma("unroll") for (int _i = 0; _i < 2; ++_i) \
;         __builtin_amdgcn_global_load_lds((const unsigned*)((const char*)(gbase) + (voff)[_i]), (LAS unsigned*)(lds + (bufoff) + ldsw + _i * 8192), 16, 0, 0); } while (0)
; #define PG8_LDA(dst, b, h) do { _Pragma("unroll") for (int m = 0; m < 4; ++m) _Pragma("unroll") for (int k = 0; k < 2; ++k) dst[m][k] = *(const LAS bf16x8*)(lds + PG8_SA(b, h) + aoff + m * 2048 + k * 1024); } while (0)
; #define PG8_LDB(dst, b, h) do { _Pragma("unroll") for (int n = 0; n < 2; ++n) _Pragma("unroll") for (int k = 0; k < 2; ++k) dst[n][k] = *(const LAS bf16x8*)(lds + PG8_SB(b, h) + boff + n * 2048 + k * 1024); } while (0)
; #define PG8_MMA(ai, bj, At, Bt) do { __builtin_amdgcn_s_setprio(1); _Pragma("unroll") for (int m = 0; m < 4; ++m) _Pragma("unroll") for (int n = 0; n < 2; ++n) _Pragma("unroll") for (int k = 0; k < 2; ++k) \
;         acc[ai][bj][m][n] = __builtin_amdgcn_mfma_f32_16x16x32_bf16(Bt[n][k], At[m][k], acc[ai][bj][m][n], 0, 0, 0); __builtin_amdgcn_s_setprio(0); } while (0)
; #define PG8_WAIT_L(n) asm volatile("s_waitcnt lgkmcnt(" #n ")" ::: "memory")
; #define PG8_BAR __builtin_amdgcn_s_barrier()
; #define PG8_SCHED __builtin_amdgcn_sched_barrier(0)
; template <class Epi, class Sched>
; __device__ __forceinline__ void gemm_phase(LAS unsigned char* lds, const Gemm g, const Sched& S, const Epi& E) {
;     ...
;         for (int t = 0; t < nt; t += 2) {
;             const bool last = (t == nt - 2);
;             const char* a1 = cA + (size_t)(t + 1) * kstep;
;             const char* a2 = last ? nA : cA + (size_t)(t + 2) * kstep; const char* b2 = last ? nB : cB + (size_t)(t + 2) * kstep;
;             const char* a3 = a2 + kstep; const char* b3 = b2 + kstep;
;             PG8_LDB(B0, 0, 0); PG8_SCHED; PG8_LDA(At, 0, 0); PG8_STAGE(PG8_SA(1, 1), a1 + hstep, voffA);
;             PG8_WAIT_L(8); PG8_BAR; PG8_WAIT_L(0); PG8_MMA(0, 0, At, B0); PG8_BAR; PG8_SCHED;
;             PG8_LDB(B1, 0, 1); PG8_STAGE(PG8_SB(0, 0), b2, voffB);
;             PG8_BAR; PG8_WAIT_L(0); PG8_MMA(0, 1, At, B1); PG8_BAR;
;             PG8_LDA(At, 0, 1); PG8_STAGE(PG8_SA(0, 0), a2, voffA);
;             PG8_BAR; PG8_WAIT_L(0); PG8_MMA(1, 0, At, B0); PG8_BAR; PG8_SCHED;
.LBB0_113:
	s_add_u32 s54, s52, 0x100
	s_addc_u32 s55, s53, 0
	s_cmp_eq_u32 s73, 4
	s_cselect_b32 s59, s11, s55
	s_cselect_b32 s58, s29, s54
	s_cselect_b32 s57, s41, s72
	s_cselect_b32 s56, s45, s71
	v_lshl_add_u64 v[156:157], s[52:53], 0, v[134:135]
	s_add_i32 m0, s25, 0xc000
	s_nop 0
	global_load_lds_dwordx4 v[156:157], off
	v_lshl_add_u64 v[156:157], s[52:53], 0, v[132:133]
	s_add_i32 m0, s25, 0xe000
	s_nop 0
	global_load_lds_dwordx4 v[156:157], off
	s_add_i32 s38, 0, 0x10000
	v_add_u32_e32 v152, s38, v137
	ds_read_b128 v[140:143], v152
	ds_read_b128 v[144:147], v152 offset:1024
	ds_read_b128 v[148:151], v152 offset:2048
	ds_read_b128 v[152:155], v152 offset:3072
	ds_read_b128 v[160:163], v139
	ds_read_b128 v[164:167], v139 offset:1024
	ds_read_b128 v[168:171], v139 offset:2048
	ds_read_b128 v[172:175], v139 offset:3072
	ds_read_b128 v[176:179], v139 offset:4096
	ds_read_b128 v[180:183], v139 offset:5120
	ds_read_b128 v[184:187], v139 offset:6144
	ds_read_b128 v[188:191], v139 offset:7168
	s_add_i32 s52, 0, 0x14000
	v_add_u32_e32 v156, s52, v137
	ds_read_b128 v[192:195], v156
	ds_read_b128 v[196:199], v156 offset:1024
	ds_read_b128 v[200:203], v156 offset:2048
	ds_read_b128 v[204:207], v156 offset:3072
	s_waitcnt lgkmcnt(4)
	s_barrier
	s_waitcnt lgkmcnt(0)
	v_mfma_f32_16x16x32_bf16 v[126:129], v[140:143], v[160:163], v[126:129]
	v_mfma_f32_16x16x32_bf16 v[122:125], v[148:151], v[160:163], v[122:125]
	v_mfma_f32_16x16x32_bf16 v[118:121], v[140:143], v[168:171], v[118:121]
	v_mfma_f32_16x16x32_bf16 v[114:117], v[148:151], v[168:171], v[114:117]
	v_mfma_f32_16x16x32_bf16 v[106:109], v[140:143], v[176:179], v[106:109]
	v_mfma_f32_16x16x32_bf16 v[98:101], v[148:151], v[176:179], v[98:101]
	v_mfma_f32_16x16x32_bf16 v[90:93], v[140:143], v[184:187], v[90:93]
	v_mfma_f32_16x16x32_bf16 v[82:85], v[148:151], v[184:187], v[82:85]
	v_mfma_f32_16x16x32_bf16 v[126:129], v[144:147], v[164:167], v[126:129]
	v_mfma_f32_16x16x32_bf16 v[122:125], v[152:155], v[164:167], v[122:125]
	v_mfma_f32_16x16x32_bf16 v[118:121], v[144:147], v[172:175], v[118:121]
	v_mfma_f32_16x16x32_bf16 v[114:117], v[152:155], v[172:175], v[114:117]
	v_mfma_f32_16x16x32_bf16 v[106:109], v[144:147], v[180:183], v[106:109]
	v_mfma_f32_16x16x32_bf16 v[98:101], v[152:155], v[180:183], v[98:101]
	v_mfma_f32_16x16x32_bf16 v[90:93], v[144:147], v[188:191], v[90:93]
	v_mfma_f32_16x16x32_bf16 v[82:85], v[152:155], v[188:191], v[82:85]
	v_mfma_f32_16x16x32_bf16 v[110:113], v[192:195], v[160:163], v[110:113]
	v_mfma_f32_16x16x32_bf16 v[102:105], v[200:203], v[160:163], v[102:105]
	v_mfma_f32_16x16x32_bf16 v[94:97], v[192:195], v[168:171], v[94:97]
	v_mfma_f32_16x16x32_bf16 v[86:89], v[200:203], v[168:171], v[86:89]
	v_mfma_f32_16x16x32_bf16 v[78:81], v[192:195], v[176:179], v[78:81]
	v_mfma_f32_16x16x32_bf16 v[74:77], v[200:203], v[176:179], v[74:77]
	v_mfma_f32_16x16x32_bf16 v[70:73], v[192:195], v[184:187], v[70:73]
	v_mfma_f32_16x16x32_bf16 v[66:69], v[200:203], v[184:187], v[66:69]
	v_mfma_f32_16x16x32_bf16 v[110:113], v[196:199], v[164:167], v[110:113]
	v_mfma_f32_16x16x32_bf16 v[102:105], v[204:207], v[164:167], v[102:105]
	v_mfma_f32_16x16x32_bf16 v[94:97], v[196:199], v[172:175], v[94:97]
	v_mfma_f32_16x16x32_bf16 v[86:89], v[204:207], v[172:175], v[86:89]
	v_mfma_f32_16x16x32_bf16 v[78:81], v[196:199], v[180:183], v[78:81]
	v_mfma_f32_16x16x32_bf16 v[74:77], v[204:207], v[180:183], v[74:77]
	v_mfma_f32_16x16x32_bf16 v[70:73], v[196:199], v[188:191], v[70:73]
	v_mfma_f32_16x16x32_bf16 v[66:69], v[204:207], v[188:191], v[66:69]
	s_barrier
	s_add_i32 s38, s38, s65
	v_lshl_add_u64 v[156:157], s[56:57], 0, v[0:1]
	s_mov_b32 m0, s38
	v_lshl_add_u64 v[210:211], s[56:57], 0, v[130:131]
	global_load_lds_dwordx4 v[156:157], off
	s_add_i32 m0, s38, 0x2000
	s_nop 0
	global_load_lds_dwordx4 v[210:211], off
	s_mov_b32 m0, s25
	v_lshl_add_u64 v[212:213], s[58:59], 0, v[0:1]
	global_load_lds_dwordx4 v[212:213], off
	v_lshl_add_u64 v[214:215], s[58:59], 0, v[130:131]
	s_mov_b32 m0, s27
	s_nop 0
	global_load_lds_dwordx4 v[214:215], off
	ds_read_b128 v[160:163], v139 offset:16384
	ds_read_b128 v[164:167], v139 offset:17408
	ds_read_b128 v[168:171], v139 offset:18432
	ds_read_b128 v[172:175], v139 offset:19456
	ds_read_b128 v[176:179], v139 offset:20480
	ds_read_b128 v[180:183], v139 offset:21504
	ds_read_b128 v[184:187], v139 offset:22528
	ds_read_b128 v[188:191], v139 offset:23552
	s_waitcnt vmcnt(4)
	s_waitcnt lgkmcnt(0)
	s_barrier
	v_mfma_f32_16x16x32_bf16 v[62:65], v[140:143], v[160:163], v[62:65]
	v_mfma_f32_16x16x32_bf16 v[58:61], v[148:151], v[160:163], v[58:61]
	v_mfma_f32_16x16x32_bf16 v[54:57], v[140:143], v[168:171], v[54:57]
	v_mfma_f32_16x16x32_bf16 v[50:53], v[148:151], v[168:171], v[50:53]
	v_mfma_f32_16x16x32_bf16 v[38:41], v[140:143], v[176:179], v[38:41]
	v_mfma_f32_16x16x32_bf16 v[34:37], v[148:151], v[176:179], v[34:37]
	v_mfma_f32_16x16x32_bf16 v[22:25], v[140:143], v[184:187], v[22:25]
	v_mfma_f32_16x16x32_bf16 v[18:21], v[148:151], v[184:187], v[18:21]
	v_mfma_f32_16x16x32_bf16 v[62:65], v[144:147], v[164:167], v[62:65]
	v_mfma_f32_16x16x32_bf16 v[58:61], v[152:155], v[164:167], v[58:61]
	v_mfma_f32_16x16x32_bf16 v[54:57], v[144:147], v[172:175], v[54:57]
	v_mfma_f32_16x16x32_bf16 v[50:53], v[152:155], v[172:175], v[50:53]
	v_mfma_f32_16x16x32_bf16 v[38:41], v[144:147], v[180:183], v[38:41]
	v_mfma_f32_16x16x32_bf16 v[34:37], v[152:155], v[180:183], v[34:37]
	v_mfma_f32_16x16x32_bf16 v[22:25], v[144:147], v[188:191], v[22:25]
	v_mfma_f32_16x16x32_bf16 v[18:21], v[152:155], v[188:191], v[18:21]
	v_mfma_f32_16x16x32_bf16 v[46:49], v[192:195], v[160:163], v[46:49]
	v_mfma_f32_16x16x32_bf16 v[42:45], v[200:203], v[160:163], v[42:45]
	v_mfma_f32_16x16x32_bf16 v[30:33], v[192:195], v[168:171], v[30:33]
	v_mfma_f32_16x16x32_bf16 v[26:29], v[200:203], v[168:171], v[26:29]
	v_mfma_f32_16x16x32_bf16 v[14:17], v[192:195], v[176:179], v[14:17]
	v_mfma_f32_16x16x32_bf16 v[10:13], v[200:203], v[176:179], v[10:13]
	v_mfma_f32_16x16x32_bf16 v[6:9], v[192:195], v[184:187], v[6:9]
	v_mfma_f32_16x16x32_bf16 v[2:5], v[200:203], v[184:187], v[2:5]
	v_mfma_f32_16x16x32_bf16 v[46:49], v[196:199], v[164:167], v[46:49]
	v_mfma_f32_16x16x32_bf16 v[42:45], v[204:207], v[164:167], v[42:45]
	v_mfma_f32_16x16x32_bf16 v[30:33], v[196:199], v[172:175], v[30:33]
	v_mfma_f32_16x16x32_bf16 v[26:29], v[204:207], v[172:175], v[26:29]
	v_mfma_f32_16x16x32_bf16 v[14:17], v[196:199], v[180:183], v[14:17]
	v_mfma_f32_16x16x32_bf16 v[10:13], v[204:207], v[180:183], v[10:13]
	v_mfma_f32_16x16x32_bf16 v[6:9], v[196:199], v[188:191], v[6:9]
	v_mfma_f32_16x16x32_bf16 v[2:5], v[204:207], v[188:191], v[2:5]
	s_barrier
; #define PG8_STAGE(bufoff, gbase, voff) do { _Pragma("unroll") for (int _i = 0; _i < 2; ++_i) \
;         __builtin_amdgcn_global_load_lds((const unsigned*)((const char*)(gbase) + (voff)[_i]), (LAS unsigned*)(lds + (bufoff) + ldsw + _i * 8192), 16, 0, 0); } while (0)
; #define PG8_LDA(dst, b, h) do { _Pragma("unroll") for (int m = 0; m < 4; ++m) _Pragma("unroll") for (int k = 0; k < 2; ++k) dst[m][k] = *(const LAS bf16x8*)(lds + PG8_SA(b, h) + aoff + m * 2048 + k * 1024); } while (0)
; #define PG8_LDB(dst, b, h) do { _Pragma("unroll") for (int n = 0; n < 2; ++n) _Pragma("unroll") for (int k = 0; k < 2; ++k) dst[n][k] = *(const LAS bf16x8*)(lds + PG8_SB(b, h) + boff + n * 2048 + k * 1024); } while (0)
; #define PG8_MMA(ai, bj, At, Bt) do { __builtin_amdgcn_s_setprio(1); _Pragma("unroll") for (int m = 0; m < 4; ++m) _Pragma("unroll") for (int n = 0; n < 2; ++n) _Pragma("unroll") for (int k = 0; k < 2; ++k) \
;         acc[ai][bj][m][n] = __builtin_amdgcn_mfma_f32_16x16x32_bf16(Bt[n][k], At[m][k], acc[ai][bj][m][n], 0, 0, 0); __builtin_amdgcn_s_setprio(0); } while (0)
; #define PG8_WAIT_V(n) asm volatile("s_waitcnt vmcnt(" #n ")" ::: "memory")
; #define PG8_WAIT_L(n) asm volatile("s_waitcnt lgkmcnt(" #n ")" ::: "memory")
; #define PG8_BAR __builtin_amdgcn_s_barrier()
; #define PG8_SCHED __builtin_amdgcn_sched_barrier(0)
; template <class Epi, class Sched>
; __device__ __forceinline__ void gemm_phase(LAS unsigned char* lds, const Gemm g, const Sched& S, const Epi& E) {
;     ...
;             PG8_STAGE(PG8_SB(0, 1), b2 + hstep, voffB);
;             PG8_WAIT_V(6); PG8_BAR; PG8_MMA(1, 1, At, B1); PG8_BAR;
;             PG8_LDB(B0, 1, 0); PG8_SCHED; PG8_LDA(At, 1, 0); PG8_STAGE(PG8_SA(0, 1), a2 + hstep, voffA);
;             PG8_WAIT_L(8); PG8_BAR; PG8_WAIT_L(0); PG8_MMA(0, 0, At, B0); PG8_BAR; PG8_SCHED;
	s_add_u32 s38, s56, 0x80000
	s_addc_u32 s39, s57, 0
	s_add_i32 s52, s52, s65
	v_lshl_add_u64 v[140:141], s[38:39], 0, v[0:1]
	s_mov_b32 m0, s52
	s_nop 0
	global_load_lds_dwordx4 v[140:141], off
	v_lshl_add_u64 v[140:141], s[38:39], 0, v[130:131]
	s_add_i32 m0, s52, 0x2000
	s_nop 0
	global_load_lds_dwordx4 v[140:141], off
	s_add_u32 s38, s58, 0x80000
	s_addc_u32 s39, s59, 0
	s_mov_b32 m0, s66
	v_lshl_add_u64 v[192:193], s[38:39], 0, v[0:1]
	global_load_lds_dwordx4 v[192:193], off
	v_lshl_add_u64 v[192:193], s[38:39], 0, v[130:131]
	s_mov_b32 m0, s67
	s_nop 0
	global_load_lds_dwordx4 v[192:193], off
	s_add_i32 s52, 0, 0x18000
	v_add_u32_e32 v152, s52, v137
	ds_read_b128 v[140:143], v152
	ds_read_b128 v[144:147], v152 offset:1024
	ds_read_b128 v[148:151], v152 offset:2048
	ds_read_b128 v[152:155], v152 offset:3072
	ds_read_b128 v[160:163], v139 offset:32768
	ds_read_b128 v[164:167], v139 offset:33792
	ds_read_b128 v[168:171], v139 offset:34816
	ds_read_b128 v[172:175], v139 offset:35840
	ds_read_b128 v[176:179], v139 offset:36864
	ds_read_b128 v[180:183], v139 offset:37888
	ds_read_b128 v[184:187], v139 offset:38912
	ds_read_b128 v[188:191], v139 offset:39936
	s_add_i32 s53, 0, 0x1c000
	v_add_u32_e32 v204, s53, v137
	ds_read_b128 v[192:195], v204
	ds_read_b128 v[196:199], v204 offset:1024
	ds_read_b128 v[200:203], v204 offset:2048
	ds_read_b128 v[204:207], v204 offset:3072
	s_waitcnt lgkmcnt(4)
	s_barrier
	s_waitcnt lgkmcnt(0)
	v_mfma_f32_16x16x32_bf16 v[126:129], v[140:143], v[160:163], v[126:129]
	v_mfma_f32_16x16x32_bf16 v[122:125], v[148:151], v[160:163], v[122:125]
	v_mfma_f32_16x16x32_bf16 v[118:121], v[140:143], v[168:171], v[118:121]
	v_mfma_f32_16x16x32_bf16 v[114:117], v[148:151], v[168:171], v[114:117]
	v_mfma_f32_16x16x32_bf16 v[106:109], v[140:143], v[176:179], v[106:109]
	v_mfma_f32_16x16x32_bf16 v[98:101], v[148:151], v[176:179], v[98:101]
	v_mfma_f32_16x16x32_bf16 v[90:93], v[140:143], v[184:187], v[90:93]
	v_mfma_f32_16x16x32_bf16 v[82:85], v[148:151], v[184:187], v[82:85]
	v_mfma_f32_16x16x32_bf16 v[126:129], v[144:147], v[164:167], v[126:129]
	v_mfma_f32_16x16x32_bf16 v[122:125], v[152:155], v[164:167], v[122:125]
	v_mfma_f32_16x16x32_bf16 v[118:121], v[144:147], v[172:175], v[118:121]
	v_mfma_f32_16x16x32_bf16 v[114:117], v[152:155], v[172:175], v[114:117]
	v_mfma_f32_16x16x32_bf16 v[106:109], v[144:147], v[180:183], v[106:109]
	v_mfma_f32_16x16x32_bf16 v[98:101], v[152:155], v[180:183], v[98:101]
	v_mfma_f32_16x16x32_bf16 v[90:93], v[144:147], v[188:191], v[90:93]
	v_mfma_f32_16x16x32_bf16 v[82:85], v[152:155], v[188:191], v[82:85]
	v_mfma_f32_16x16x32_bf16 v[110:113], v[192:195], v[160:163], v[110:113]
	v_mfma_f32_16x16x32_bf16 v[102:105], v[200:203], v[160:163], v[102:105]
	v_mfma_f32_16x16x32_bf16 v[94:97], v[192:195], v[168:171], v[94:97]
	v_mfma_f32_16x16x32_bf16 v[86:89], v[200:203], v[168:171], v[86:89]
	v_mfma_f32_16x16x32_bf16 v[78:81], v[192:195], v[176:179], v[78:81]
	v_mfma_f32_16x16x32_bf16 v[74:77], v[200:203], v[176:179], v[74:77]
	v_mfma_f32_16x16x32_bf16 v[70:73], v[192:195], v[184:187], v[70:73]
	v_mfma_f32_16x16x32_bf16 v[66:69], v[200:203], v[184:187], v[66:69]
	v_mfma_f32_16x16x32_bf16 v[110:113], v[196:199], v[164:167], v[110:113]
	v_mfma_f32_16x16x32_bf16 v[102:105], v[204:207], v[164:167], v[102:105]
	v_mfma_f32_16x16x32_bf16 v[94:97], v[196:199], v[172:175], v[94:97]
	v_mfma_f32_16x16x32_bf16 v[86:89], v[204:207], v[172:175], v[86:89]
	v_mfma_f32_16x16x32_bf16 v[78:81], v[196:199], v[180:183], v[78:81]
	v_mfma_f32_16x16x32_bf16 v[74:77], v[204:207], v[180:183], v[74:77]
	v_mfma_f32_16x16x32_bf16 v[70:73], v[196:199], v[188:191], v[70:73]
	v_mfma_f32_16x16x32_bf16 v[66:69], v[204:207], v[188:191], v[66:69]
	s_barrier
	s_add_i32 s38, s52, s65
	v_lshl_add_u64 v[156:157], v[156:157], 0, s[36:37]
	s_mov_b32 m0, s38
	s_nop 0
	global_load_lds_dwordx4 v[156:157], off
	v_lshl_add_u64 v[156:157], v[210:211], 0, s[36:37]
	s_add_i32 m0, s38, 0x2000
	s_nop 0
	global_load_lds_dwordx4 v[156:157], off
	s_mov_b32 m0, s68
	v_lshl_add_u64 v[156:157], v[212:213], 0, s[36:37]
	global_load_lds_dwordx4 v[156:157], off
	v_lshl_add_u64 v[156:157], v[214:215], 0, s[36:37]
	s_mov_b32 m0, s69
	s_nop 0
	global_load_lds_dwordx4 v[156:157], off
	ds_read_b128 v[160:163], v139 offset:49152
	ds_read_b128 v[164:167], v139 offset:50176
	ds_read_b128 v[168:171], v139 offset:51200
	ds_read_b128 v[172:175], v139 offset:52224
	ds_read_b128 v[176:179], v139 offset:53248
	ds_read_b128 v[180:183], v139 offset:54272
	ds_read_b128 v[184:187], v139 offset:55296
	ds_read_b128 v[188:191], v139 offset:56320
	s_waitcnt vmcnt(4)
	s_waitcnt lgkmcnt(0)
	s_barrier
; #define PG8_STAGE(bufoff, gbase, voff) do { _Pragma("unroll") for (int _i = 0; _i < 2; ++_i) \
;         __builtin_amdgcn_global_load_lds((const unsigned*)((const char*)(gbase) + (voff)[_i]), (LAS unsigned*)(lds + (bufoff) + ldsw + _i * 8192), 16, 0, 0); } while (0)
; #define PG8_LDA(dst, b, h) do { _Pragma("unroll") for (int m = 0; m < 4; ++m) _Pragma("unroll") for (int k = 0; k < 2; ++k) dst[m][k] = *(const LAS bf16x8*)(lds + PG8_SA(b, h) + aoff + m * 2048 + k * 1024); } while (0)
; #define PG8_LDB(dst, b, h) do { _Pragma("unroll") for (int n = 0; n < 2; ++n) _Pragma("unroll") for (int k = 0; k < 2; ++k) dst[n][k] = *(const LAS bf16x8*)(lds + PG8_SB(b, h) + boff + n * 2048 + k * 1024); } while (0)
; #define PG8_MMA(ai, bj, At, Bt) do { __builtin_amdgcn_s_setprio(1); _Pragma("unroll") for (int m = 0; m < 4; ++m) _Pragma("unroll") for (int n = 0; n < 2; ++n) _Pragma("unroll") for (int k = 0; k < 2; ++k) \
;         acc[ai][bj][m][n] = __builtin_amdgcn_mfma_f32_16x16x32_bf16(Bt[n][k], At[m][k], acc[ai][bj][m][n], 0, 0, 0); __builtin_amdgcn_s_setprio(0); } while (0)
; #define PG8_BAR __builtin_amdgcn_s_barrier()
;     __device__ __forceinline__ void operator()(const f32x4 (&acc)[2][2][4][2], const Unit& u, int wr, int wc, int fr, int fq) const {
;         const int row0 = u.pm * BM + wr * 64 + fr, col0 = u.pn * BM + wc * 32 + 4 * fq;
;         float* base = part + (size_t)u.ks * Mp * ldc;
; #pragma unroll
;         for (int ai = 0; ai < 2; ++ai)
; #pragma unroll
;             for (int m = 0; m < 4; ++m) { float* rowp = base + (size_t)(row0 + ai * HALF + m * 16) * ldc + col0;
; #pragma unroll
;                 for (int bj = 0; bj < 2; ++bj)
; #pragma unroll
;                     for (int n = 0; n < 2; ++n) *(f32x4*)(rowp + bj * HALF + n * 16) = acc[ai][bj][m][n]; }
;     }
; template <class Epi, class Sched>
; __device__ __forceinline__ void gemm_phase(LAS unsigned char* lds, const Gemm g, const Sched& S, const Epi& E) {
;     ...
;             PG8_LDB(B1, 1, 1); PG8_STAGE(PG8_SB(1, 0), b3, voffB);
;             PG8_BAR; PG8_WAIT_L(0); PG8_MMA(0, 1, At, B1); PG8_BAR;
;             PG8_LDA(At, 1, 1); PG8_STAGE(PG8_SA(1, 0), a3, voffA);
;             PG8_BAR; PG8_WAIT_L(0); PG8_MMA(1, 0, At, B0); PG8_BAR; PG8_SCHED;
;             PG8_STAGE(PG8_SB(1, 1), b3 + hstep, voffB);
;             PG8_WAIT_V(6); PG8_BAR; PG8_MMA(1, 1, At, B1); PG8_BAR;
	v_mfma_f32_16x16x32_bf16 v[62:65], v[140:143], v[160:163], v[62:65]
	v_mfma_f32_16x16x32_bf16 v[58:61], v[148:151], v[160:163], v[58:61]
	v_mfma_f32_16x16x32_bf16 v[54:57], v[140:143], v[168:171], v[54:57]
	v_mfma_f32_16x16x32_bf16 v[50:53], v[148:151], v[168:171], v[50:53]
	v_mfma_f32_16x16x32_bf16 v[38:41], v[140:143], v[176:179], v[38:41]
	v_mfma_f32_16x16x32_bf16 v[34:37], v[148:151], v[176:179], v[34:37]
	v_mfma_f32_16x16x32_bf16 v[22:25], v[140:143], v[184:187], v[22:25]
	v_mfma_f32_16x16x32_bf16 v[18:21], v[148:151], v[184:187], v[18:21]
	v_mfma_f32_16x16x32_bf16 v[62:65], v[144:147], v[164:167], v[62:65]
	v_mfma_f32_16x16x32_bf16 v[58:61], v[152:155], v[164:167], v[58:61]
	v_mfma_f32_16x16x32_bf16 v[54:57], v[144:147], v[172:175], v[54:57]
	v_mfma_f32_16x16x32_bf16 v[50:53], v[152:155], v[172:175], v[50:53]
	v_mfma_f32_16x16x32_bf16 v[38:41], v[144:147], v[180:183], v[38:41]
	v_mfma_f32_16x16x32_bf16 v[34:37], v[152:155], v[180:183], v[34:37]
	v_mfma_f32_16x16x32_bf16 v[22:25], v[144:147], v[188:191], v[22:25]
	v_mfma_f32_16x16x32_bf16 v[18:21], v[152:155], v[188:191], v[18:21]
	s_add_u32 s38, s56, 0x80080
	s_addc_u32 s39, s57, 0
	s_add_i32 s52, s53, s65
	v_lshl_add_u64 v[140:141], s[38:39], 0, v[0:1]
	s_mov_b32 m0, s52
	s_nop 0
	global_load_lds_dwordx4 v[140:141], off
	v_lshl_add_u64 v[140:141], s[38:39], 0, v[130:131]
	s_add_i32 m0, s52, 0x2000
	s_nop 0
	global_load_lds_dwordx4 v[140:141], off
	v_mfma_f32_16x16x32_bf16 v[46:49], v[192:195], v[160:163], v[46:49]
	v_mfma_f32_16x16x32_bf16 v[42:45], v[200:203], v[160:163], v[42:45]
	v_mfma_f32_16x16x32_bf16 v[30:33], v[192:195], v[168:171], v[30:33]
	v_mfma_f32_16x16x32_bf16 v[26:29], v[200:203], v[168:171], v[26:29]
	v_mfma_f32_16x16x32_bf16 v[14:17], v[192:195], v[176:179], v[14:17]
	v_mfma_f32_16x16x32_bf16 v[10:13], v[200:203], v[176:179], v[10:13]
	v_mfma_f32_16x16x32_bf16 v[6:9], v[192:195], v[184:187], v[6:9]
	v_mfma_f32_16x16x32_bf16 v[2:5], v[200:203], v[184:187], v[2:5]
	v_mfma_f32_16x16x32_bf16 v[46:49], v[196:199], v[164:167], v[46:49]
	v_mfma_f32_16x16x32_bf16 v[42:45], v[204:207], v[164:167], v[42:45]
	v_mfma_f32_16x16x32_bf16 v[30:33], v[196:199], v[172:175], v[30:33]
	v_mfma_f32_16x16x32_bf16 v[26:29], v[204:207], v[172:175], v[26:29]
	v_mfma_f32_16x16x32_bf16 v[14:17], v[196:199], v[180:183], v[14:17]
	v_mfma_f32_16x16x32_bf16 v[10:13], v[204:207], v[180:183], v[10:13]
	v_mfma_f32_16x16x32_bf16 v[6:9], v[196:199], v[188:191], v[6:9]
	v_mfma_f32_16x16x32_bf16 v[2:5], v[204:207], v[188:191], v[2:5]
	s_add_i32 s73, s73, 2
	s_add_u32 s71, s71, 0x100
	s_addc_u32 s72, s72, 0
	s_cmp_gt_u32 s73, 5
	s_mov_b64 s[52:53], s[54:55]
	s_barrier
	s_cbranch_scc0 .LBB0_113
	s_ashr_i32 s11, s10, 31
	s_lshl_b64 s[10:11], s[10:11], 24
	v_lshl_or_b32 v140, s26, 8, v138
	s_add_u32 s10, s8, s10
	v_lshl_add_u32 v142, s24, 8, v136
	s_addc_u32 s11, s9, s11
	v_ashrrev_i32_e32 v141, 31, v140
	v_ashrrev_i32_e32 v143, 31, v142
	v_lshl_add_u64 v[140:141], v[140:141], 2, s[10:11]
	v_lshlrev_b64 v[144:145], 13, v[142:143]
	v_lshl_add_u64 v[144:145], v[140:141], 0, v[144:145]
	global_store_dwordx4 v[144:145], v[126:129], off
	global_store_dwordx4 v[144:145], v[122:125], off offset:64
	global_store_dwordx4 v[144:145], v[110:113], off offset:512
	global_store_dwordx4 v[144:145], v[102:105], off offset:576
	s_mov_b64 s[10:11], 0x100000
	s_mov_b32 s26, s40
	v_or_b32_e32 v102, 16, v142
	v_ashrrev_i32_e32 v103, 31, v102
	v_lshlrev_b64 v[102:103], 13, v[102:103]
	v_lshl_add_u64 v[102:103], v[140:141], 0, v[102:103]
	global_store_dwordx4 v[102:103], v[118:121], off
	global_store_dwordx4 v[102:103], v[114:117], off offset:64
	global_store_dwordx4 v[102:103], v[94:97], off offset:512
	global_store_dwordx4 v[102:103], v[86:89], off offset:576
	s_mov_b32 s24, s44
	s_mov_b64 s[54:55], s[50:51]
	v_or_b32_e32 v86, 32, v142
	v_ashrrev_i32_e32 v87, 31, v86
	v_lshlrev_b64 v[86:87], 13, v[86:87]
	v_lshl_add_u64 v[86:87], v[140:141], 0, v[86:87]
	global_store_dwordx4 v[86:87], v[106:109], off
	global_store_dwordx4 v[86:87], v[98:101], off offset:64
	global_store_dwordx4 v[86:87], v[78:81], off offset:512
	global_store_dwordx4 v[86:87], v[74:77], off offset:576
	s_mov_b64 s[52:53], s[48:49]
	s_nop 0
	v_or_b32_e32 v74, 48, v142
	v_ashrrev_i32_e32 v75, 31, v74
	v_lshlrev_b64 v[74:75], 13, v[74:75]
	v_lshl_add_u64 v[74:75], v[140:141], 0, v[74:75]
	global_store_dwordx4 v[74:75], v[90:93], off
	global_store_dwordx4 v[74:75], v[82:85], off offset:64
	global_store_dwordx4 v[74:75], v[70:73], off offset:512
	global_store_dwordx4 v[74:75], v[66:69], off offset:576
	s_nop 1
	v_add_co_u32_e32 v68, vcc, s93, v144
	v_lshl_add_u64 v[66:67], v[144:145], 0, s[10:11]
	s_nop 0
	v_addc_co_u32_e32 v69, vcc, 0, v145, vcc
	s_mov_b64 s[10:11], 0x120000
	global_store_dwordx4 v[68:69], v[62:65], off
	global_store_dwordx4 v[66:67], v[58:61], off offset:64
	global_store_dwordx4 v[66:67], v[46:49], off offset:512
	global_store_dwordx4 v[66:67], v[42:45], off offset:576
	s_nop 1
	v_lshl_add_u64 v[42:43], v[144:145], 0, s[10:11]
	s_mov_b32 s10, 0x120000
	v_add_co_u32_e32 v44, vcc, s10, v144
	s_mov_b64 s[10:11], 0x140000
	s_nop 0
	v_addc_co_u32_e32 v45, vcc, 0, v145, vcc
	global_store_dwordx4 v[44:45], v[54:57], off
	global_store_dwordx4 v[42:43], v[50:53], off offset:64
	global_store_dwordx4 v[42:43], v[30:33], off offset:512
	global_store_dwordx4 v[42:43], v[26:29], off offset:576
	s_nop 1
	v_lshl_add_u64 v[26:27], v[144:145], 0, s[10:11]
	s_mov_b32 s10, 0x140000
	v_add_co_u32_e32 v28, vcc, s10, v144
	s_mov_b64 s[10:11], 0x160000
	s_nop 0
	v_addc_co_u32_e32 v29, vcc, 0, v145, vcc
	global_store_dwordx4 v[28:29], v[38:41], off
	global_store_dwordx4 v[26:27], v[34:37], off offset:64
	global_store_dwordx4 v[26:27], v[14:17], off offset:512
	global_store_dwordx4 v[26:27], v[10:13], off offset:576
	s_nop 1
	v_add_co_u32_e32 v12, vcc, 0x160000, v144
	v_lshl_add_u64 v[10:11], v[144:145], 0, s[10:11]
	s_nop 0
	v_addc_co_u32_e32 v13, vcc, 0, v145, vcc
	s_and_b64 vcc, exec, s[46:47]
	s_mov_b32 s10, s28
	global_store_dwordx4 v[12:13], v[22:25], off
	global_store_dwordx4 v[10:11], v[18:21], off offset:64
	global_store_dwordx4 v[10:11], v[6:9], off offset:512
	global_store_dwordx4 v[10:11], v[2:5], off offset:576
	s_cbranch_vccz .LBB0_110
	s_waitcnt vmcnt(0)
	s_cmpk_gt_u32 s60, 0xff
	s_cbranch_scc1 .LBB0_117
	s_barrier

; #define PG8_STAGE(bufoff, gbase, voff) do { _Pragma("unroll") for (int _i = 0; _i < 2; ++_i) \
;         __builtin_amdgcn_global_load_lds((const unsigned*)((const char*)(gbase) + (voff)[_i]), (LAS unsigned*)(lds + (bufoff) + ldsw + _i * 8192), 16, 0, 0); } while (0)
; #define PG8_LDA(dst, b, h) do { _Pragma("unroll") for (int m = 0; m < 4; ++m) _Pragma("unroll") for (int k = 0; k < 2; ++k) dst[m][k] = *(const LAS bf16x8*)(lds + PG8_SA(b, h) + aoff + m * 2048 + k * 1024); } while (0)
; #define PG8_LDB(dst, b, h) do { _Pragma("unroll") for (int n = 0; n < 2; ++n) _Pragma("unroll") for (int k = 0; k < 2; ++k) dst[n][k] = *(const LAS bf16x8*)(lds + PG8_SB(b, h) + boff + n * 2048 + k * 1024); } while (0)
; #define PG8_MMA(ai, bj, At, Bt) do { __builtin_amdgcn_s_setprio(1); _Pragma("unroll") for (int m = 0; m < 4; ++m) _Pragma("unroll") for (int n = 0; n < 2; ++n) _Pragma("unroll") for (int k = 0; k < 2; ++k) \
;         acc[ai][bj][m][n] = __builtin_amdgcn_mfma_f32_16x16x32_bf16(Bt[n][k], At[m][k], acc[ai][bj][m][n], 0, 0, 0); __builtin_amdgcn_s_setprio(0); } while (0)
; #define PG8_WAIT_L(n) asm volatile("s_waitcnt lgkmcnt(" #n ")" ::: "memory")
; #define PG8_BAR __builtin_amdgcn_s_barrier()
; #define PG8_SCHED __builtin_amdgcn_sched_barrier(0)
; template <class Epi, class Sched>
; __device__ __forceinline__ void gemm_phase(LAS unsigned char* lds, const Gemm g, const Sched& S, const Epi& E) {
;     ...
;         for (int t = 0; t < nt; t += 2) {
;             const bool last = (t == nt - 2);
;             const char* a1 = cA + (size_t)(t + 1) * kstep;
;             const char* a2 = last ? nA : cA + (size_t)(t + 2) * kstep; const char* b2 = last ? nB : cB + (size_t)(t + 2) * kstep;
;             const char* a3 = a2 + kstep; const char* b3 = b2 + kstep;
;             PG8_LDB(B0, 0, 0); PG8_SCHED; PG8_LDA(At, 0, 0); PG8_STAGE(PG8_SA(1, 1), a1 + hstep, voffA);
;             PG8_WAIT_L(8); PG8_BAR; PG8_WAIT_L(0); PG8_MMA(0, 0, At, B0); PG8_BAR; PG8_SCHED;
;             PG8_LDB(B1, 0, 1); PG8_STAGE(PG8_SB(0, 0), b2, voffB);
;             PG8_BAR; PG8_WAIT_L(0); PG8_MMA(0, 1, At, B1); PG8_BAR;
;             PG8_LDA(At, 0, 1); PG8_STAGE(PG8_SA(0, 0), a2, voffA);
;             PG8_BAR; PG8_WAIT_L(0); PG8_MMA(1, 0, At, B0); PG8_BAR; PG8_SCHED;
.LBB0_354:
	s_add_u32 s38, s50, 0xfff80080
	s_addc_u32 s39, s51, -1
	s_cmp_eq_u32 s70, 28
	s_cselect_b32 s55, s9, s39
	s_cselect_b32 s54, s66, s38
	s_cselect_b32 s53, s43, s69
	s_cselect_b32 s52, s67, s68
	v_lshl_add_u64 v[156:157], s[50:51], 0, v[138:139]
	s_add_i32 m0, s29, 0xc000
	s_nop 0
	global_load_lds_dwordx4 v[156:157], off
	v_lshl_add_u64 v[156:157], s[50:51], 0, v[136:137]
	s_add_i32 m0, s29, 0xe000
	s_nop 0
	global_load_lds_dwordx4 v[156:157], off
	s_add_i32 s71, 0, 0x10000
	v_add_u32_e32 v156, s71, v145
	ds_read_b128 v[140:143], v156
	ds_read_b128 v[148:151], v156 offset:1024
	ds_read_b128 v[152:155], v156 offset:2048
	ds_read_b128 v[160:163], v156 offset:3072
	ds_read_b128 v[164:167], v147
	ds_read_b128 v[168:171], v147 offset:1024
	ds_read_b128 v[172:175], v147 offset:2048
	ds_read_b128 v[176:179], v147 offset:3072
	ds_read_b128 v[180:183], v147 offset:4096
	ds_read_b128 v[184:187], v147 offset:5120
	ds_read_b128 v[188:191], v147 offset:6144
	ds_read_b128 v[192:195], v147 offset:7168
	s_add_i32 s38, 0, 0x14000
	v_add_u32_e32 v156, s38, v145
	ds_read_b128 v[196:199], v156
	ds_read_b128 v[200:203], v156 offset:1024
	ds_read_b128 v[204:207], v156 offset:2048
	ds_read_b128 v[210:213], v156 offset:3072
	s_waitcnt lgkmcnt(4)
	s_barrier
	s_waitcnt lgkmcnt(0)
	v_mfma_f32_16x16x32_bf16 v[126:129], v[140:143], v[164:167], v[126:129]
	v_mfma_f32_16x16x32_bf16 v[122:125], v[152:155], v[164:167], v[122:125]
	v_mfma_f32_16x16x32_bf16 v[118:121], v[140:143], v[172:175], v[118:121]
	v_mfma_f32_16x16x32_bf16 v[110:113], v[152:155], v[172:175], v[110:113]
	v_mfma_f32_16x16x32_bf16 v[102:105], v[140:143], v[180:183], v[102:105]
	v_mfma_f32_16x16x32_bf16 v[94:97], v[152:155], v[180:183], v[94:97]
	v_mfma_f32_16x16x32_bf16 v[86:89], v[140:143], v[188:191], v[86:89]
	v_mfma_f32_16x16x32_bf16 v[78:81], v[152:155], v[188:191], v[78:81]
	v_mfma_f32_16x16x32_bf16 v[126:129], v[148:151], v[168:171], v[126:129]
	v_mfma_f32_16x16x32_bf16 v[122:125], v[160:163], v[168:171], v[122:125]
	v_mfma_f32_16x16x32_bf16 v[118:121], v[148:151], v[176:179], v[118:121]
	v_mfma_f32_16x16x32_bf16 v[110:113], v[160:163], v[176:179], v[110:113]
	v_mfma_f32_16x16x32_bf16 v[102:105], v[148:151], v[184:187], v[102:105]
	v_mfma_f32_16x16x32_bf16 v[94:97], v[160:163], v[184:187], v[94:97]
	v_mfma_f32_16x16x32_bf16 v[86:89], v[148:151], v[192:195], v[86:89]
	v_mfma_f32_16x16x32_bf16 v[78:81], v[160:163], v[192:195], v[78:81]
	v_mfma_f32_16x16x32_bf16 v[114:117], v[196:199], v[164:167], v[114:117]
	v_mfma_f32_16x16x32_bf16 v[106:109], v[204:207], v[164:167], v[106:109]
	v_mfma_f32_16x16x32_bf16 v[98:101], v[196:199], v[172:175], v[98:101]
	v_mfma_f32_16x16x32_bf16 v[90:93], v[204:207], v[172:175], v[90:93]
	v_mfma_f32_16x16x32_bf16 v[82:85], v[196:199], v[180:183], v[82:85]
	v_mfma_f32_16x16x32_bf16 v[74:77], v[204:207], v[180:183], v[74:77]
	v_mfma_f32_16x16x32_bf16 v[70:73], v[196:199], v[188:191], v[70:73]
	v_mfma_f32_16x16x32_bf16 v[66:69], v[204:207], v[188:191], v[66:69]
	v_mfma_f32_16x16x32_bf16 v[114:117], v[200:203], v[168:171], v[114:117]
	v_mfma_f32_16x16x32_bf16 v[106:109], v[210:213], v[168:171], v[106:109]
	v_mfma_f32_16x16x32_bf16 v[98:101], v[200:203], v[176:179], v[98:101]
	v_mfma_f32_16x16x32_bf16 v[90:93], v[210:213], v[176:179], v[90:93]
	v_mfma_f32_16x16x32_bf16 v[82:85], v[200:203], v[184:187], v[82:85]
	v_mfma_f32_16x16x32_bf16 v[74:77], v[210:213], v[184:187], v[74:77]
	v_mfma_f32_16x16x32_bf16 v[70:73], v[200:203], v[192:195], v[70:73]
	v_mfma_f32_16x16x32_bf16 v[66:69], v[210:213], v[192:195], v[66:69]
	s_barrier
	s_add_i32 s39, s71, s56
	v_lshl_add_u64 v[156:157], s[52:53], 0, v[0:1]
	s_mov_b32 m0, s39
	v_lshl_add_u64 v[214:215], s[52:53], 0, v[134:135]
	global_load_lds_dwordx4 v[156:157], off
	s_add_i32 m0, s39, 0x2000
	s_nop 0
	global_load_lds_dwordx4 v[214:215], off
	s_mov_b32 m0, s29
	v_lshl_add_u64 v[216:217], s[54:55], 0, v[130:131]
	global_load_lds_dwordx4 v[216:217], off
	v_lshl_add_u64 v[224:225], s[54:55], 0, v[132:133]
	s_mov_b32 m0, s41
	s_nop 0
	global_load_lds_dwordx4 v[224:225], off
	ds_read_b128 v[164:167], v147 offset:16384
	ds_read_b128 v[168:171], v147 offset:17408
	ds_read_b128 v[172:175], v147 offset:18432
	ds_read_b128 v[176:179], v147 offset:19456
	ds_read_b128 v[180:183], v147 offset:20480
	ds_read_b128 v[184:187], v147 offset:21504
	ds_read_b128 v[188:191], v147 offset:22528
	ds_read_b128 v[192:195], v147 offset:23552
	s_waitcnt vmcnt(4)
	s_waitcnt lgkmcnt(0)
	s_barrier
	v_mfma_f32_16x16x32_bf16 v[62:65], v[140:143], v[164:167], v[62:65]
	v_mfma_f32_16x16x32_bf16 v[58:61], v[152:155], v[164:167], v[58:61]
	v_mfma_f32_16x16x32_bf16 v[54:57], v[140:143], v[172:175], v[54:57]
	v_mfma_f32_16x16x32_bf16 v[46:49], v[152:155], v[172:175], v[46:49]
	v_mfma_f32_16x16x32_bf16 v[38:41], v[140:143], v[180:183], v[38:41]
	v_mfma_f32_16x16x32_bf16 v[30:33], v[152:155], v[180:183], v[30:33]
	v_mfma_f32_16x16x32_bf16 v[22:25], v[140:143], v[188:191], v[22:25]
	v_mfma_f32_16x16x32_bf16 v[14:17], v[152:155], v[188:191], v[14:17]
	v_mfma_f32_16x16x32_bf16 v[62:65], v[148:151], v[168:171], v[62:65]
	v_mfma_f32_16x16x32_bf16 v[58:61], v[160:163], v[168:171], v[58:61]
	v_mfma_f32_16x16x32_bf16 v[54:57], v[148:151], v[176:179], v[54:57]
	v_mfma_f32_16x16x32_bf16 v[46:49], v[160:163], v[176:179], v[46:49]
	v_mfma_f32_16x16x32_bf16 v[38:41], v[148:151], v[184:187], v[38:41]
	v_mfma_f32_16x16x32_bf16 v[30:33], v[160:163], v[184:187], v[30:33]
	v_mfma_f32_16x16x32_bf16 v[22:25], v[148:151], v[192:195], v[22:25]
	v_mfma_f32_16x16x32_bf16 v[14:17], v[160:163], v[192:195], v[14:17]
	v_mfma_f32_16x16x32_bf16 v[50:53], v[196:199], v[164:167], v[50:53]
	v_mfma_f32_16x16x32_bf16 v[42:45], v[204:207], v[164:167], v[42:45]
	v_mfma_f32_16x16x32_bf16 v[34:37], v[196:199], v[172:175], v[34:37]
	v_mfma_f32_16x16x32_bf16 v[26:29], v[204:207], v[172:175], v[26:29]
	v_mfma_f32_16x16x32_bf16 v[18:21], v[196:199], v[180:183], v[18:21]
	v_mfma_f32_16x16x32_bf16 v[10:13], v[204:207], v[180:183], v[10:13]
	v_mfma_f32_16x16x32_bf16 v[6:9], v[196:199], v[188:191], v[6:9]
	v_mfma_f32_16x16x32_bf16 v[2:5], v[204:207], v[188:191], v[2:5]
	v_mfma_f32_16x16x32_bf16 v[50:53], v[200:203], v[168:171], v[50:53]
	v_mfma_f32_16x16x32_bf16 v[42:45], v[210:213], v[168:171], v[42:45]
	v_mfma_f32_16x16x32_bf16 v[34:37], v[200:203], v[176:179], v[34:37]
	v_mfma_f32_16x16x32_bf16 v[26:29], v[210:213], v[176:179], v[26:29]
	v_mfma_f32_16x16x32_bf16 v[18:21], v[200:203], v[184:187], v[18:21]
	v_mfma_f32_16x16x32_bf16 v[10:13], v[210:213], v[184:187], v[10:13]
	v_mfma_f32_16x16x32_bf16 v[6:9], v[200:203], v[192:195], v[6:9]
	v_mfma_f32_16x16x32_bf16 v[2:5], v[210:213], v[192:195], v[2:5]
	s_barrier
; #define PG8_STAGE(bufoff, gbase, voff) do { _Pragma("unroll") for (int _i = 0; _i < 2; ++_i) \
;         __builtin_amdgcn_global_load_lds((const unsigned*)((const char*)(gbase) + (voff)[_i]), (LAS unsigned*)(lds + (bufoff) + ldsw + _i * 8192), 16, 0, 0); } while (0)
; #define PG8_LDA(dst, b, h) do { _Pragma("unroll") for (int m = 0; m < 4; ++m) _Pragma("unroll") for (int k = 0; k < 2; ++k) dst[m][k] = *(const LAS bf16x8*)(lds + PG8_SA(b, h) + aoff + m * 2048 + k * 1024); } while (0)
; #define PG8_LDB(dst, b, h) do { _Pragma("unroll") for (int n = 0; n < 2; ++n) _Pragma("unroll") for (int k = 0; k < 2; ++k) dst[n][k] = *(const LAS bf16x8*)(lds + PG8_SB(b, h) + boff + n * 2048 + k * 1024); } while (0)
; #define PG8_MMA(ai, bj, At, Bt) do { __builtin_amdgcn_s_setprio(1); _Pragma("unroll") for (int m = 0; m < 4; ++m) _Pragma("unroll") for (int n = 0; n < 2; ++n) _Pragma("unroll") for (int k = 0; k < 2; ++k) \
;         acc[ai][bj][m][n] = __builtin_amdgcn_mfma_f32_16x16x32_bf16(Bt[n][k], At[m][k], acc[ai][bj][m][n], 0, 0, 0); __builtin_amdgcn_s_setprio(0); } while (0)
; #define PG8_WAIT_V(n) asm volatile("s_waitcnt vmcnt(" #n ")" ::: "memory")
; #define PG8_WAIT_L(n) asm volatile("s_waitcnt lgkmcnt(" #n ")" ::: "memory")
; #define PG8_BAR __builtin_amdgcn_s_barrier()
; #define PG8_SCHED __builtin_amdgcn_sched_barrier(0)
; template <class Epi, class Sched>
; __device__ __forceinline__ void gemm_phase(LAS unsigned char* lds, const Gemm g, const Sched& S, const Epi& E) {
;     ...
;             PG8_STAGE(PG8_SB(0, 1), b2 + hstep, voffB);
;             PG8_WAIT_V(6); PG8_BAR; PG8_MMA(1, 1, At, B1); PG8_BAR;
;             PG8_LDB(B0, 1, 0); PG8_SCHED; PG8_LDA(At, 1, 0); PG8_STAGE(PG8_SA(0, 1), a2 + hstep, voffA);
;             PG8_WAIT_L(8); PG8_BAR; PG8_WAIT_L(0); PG8_MMA(0, 0, At, B0); PG8_BAR; PG8_SCHED;
	s_add_u32 s72, s52, 0x80000
	s_addc_u32 s73, s53, 0
	s_add_i32 s38, s38, s56
	v_lshl_add_u64 v[140:141], s[72:73], 0, v[0:1]
	s_mov_b32 m0, s38
	s_nop 0
	global_load_lds_dwordx4 v[140:141], off
	v_lshl_add_u64 v[140:141], s[72:73], 0, v[134:135]
	s_add_i32 m0, s38, 0x2000
	s_nop 0
	global_load_lds_dwordx4 v[140:141], off
	s_add_u32 s54, s54, 0x80000
	s_addc_u32 s55, s55, 0
	s_mov_b32 m0, s57
	v_lshl_add_u64 v[196:197], s[54:55], 0, v[130:131]
	global_load_lds_dwordx4 v[196:197], off
	v_lshl_add_u64 v[196:197], s[54:55], 0, v[132:133]
	s_mov_b32 m0, s58
	s_nop 0
	global_load_lds_dwordx4 v[196:197], off
	s_add_i32 s38, 0, 0x18000
	v_add_u32_e32 v160, s38, v145
	ds_read_b128 v[140:143], v160
	ds_read_b128 v[148:151], v160 offset:1024
	ds_read_b128 v[152:155], v160 offset:2048
	ds_read_b128 v[160:163], v160 offset:3072
	ds_read_b128 v[164:167], v147 offset:32768
	ds_read_b128 v[168:171], v147 offset:33792
	ds_read_b128 v[172:175], v147 offset:34816
	ds_read_b128 v[176:179], v147 offset:35840
	ds_read_b128 v[180:183], v147 offset:36864
	ds_read_b128 v[184:187], v147 offset:37888
	ds_read_b128 v[188:191], v147 offset:38912
	ds_read_b128 v[192:195], v147 offset:39936
	s_add_i32 s39, 0, 0x1c000
	v_add_u32_e32 v210, s39, v145
	ds_read_b128 v[196:199], v210
	ds_read_b128 v[200:203], v210 offset:1024
	ds_read_b128 v[204:207], v210 offset:2048
	ds_read_b128 v[210:213], v210 offset:3072
	s_waitcnt lgkmcnt(4)
	s_barrier
	s_waitcnt lgkmcnt(0)
	v_mfma_f32_16x16x32_bf16 v[126:129], v[140:143], v[164:167], v[126:129]
	v_mfma_f32_16x16x32_bf16 v[122:125], v[152:155], v[164:167], v[122:125]
	v_mfma_f32_16x16x32_bf16 v[118:121], v[140:143], v[172:175], v[118:121]
	v_mfma_f32_16x16x32_bf16 v[110:113], v[152:155], v[172:175], v[110:113]
	v_mfma_f32_16x16x32_bf16 v[102:105], v[140:143], v[180:183], v[102:105]
	v_mfma_f32_16x16x32_bf16 v[94:97], v[152:155], v[180:183], v[94:97]
	v_mfma_f32_16x16x32_bf16 v[86:89], v[140:143], v[188:191], v[86:89]
	v_mfma_f32_16x16x32_bf16 v[78:81], v[152:155], v[188:191], v[78:81]
	v_mfma_f32_16x16x32_bf16 v[126:129], v[148:151], v[168:171], v[126:129]
	v_mfma_f32_16x16x32_bf16 v[122:125], v[160:163], v[168:171], v[122:125]
	v_mfma_f32_16x16x32_bf16 v[118:121], v[148:151], v[176:179], v[118:121]
	v_mfma_f32_16x16x32_bf16 v[110:113], v[160:163], v[176:179], v[110:113]
	v_mfma_f32_16x16x32_bf16 v[102:105], v[148:151], v[184:187], v[102:105]
	v_mfma_f32_16x16x32_bf16 v[94:97], v[160:163], v[184:187], v[94:97]
	v_mfma_f32_16x16x32_bf16 v[86:89], v[148:151], v[192:195], v[86:89]
	v_mfma_f32_16x16x32_bf16 v[78:81], v[160:163], v[192:195], v[78:81]
	v_mfma_f32_16x16x32_bf16 v[114:117], v[196:199], v[164:167], v[114:117]
	v_mfma_f32_16x16x32_bf16 v[106:109], v[204:207], v[164:167], v[106:109]
	v_mfma_f32_16x16x32_bf16 v[98:101], v[196:199], v[172:175], v[98:101]
	v_mfma_f32_16x16x32_bf16 v[90:93], v[204:207], v[172:175], v[90:93]
	v_mfma_f32_16x16x32_bf16 v[82:85], v[196:199], v[180:183], v[82:85]
	v_mfma_f32_16x16x32_bf16 v[74:77], v[204:207], v[180:183], v[74:77]
	v_mfma_f32_16x16x32_bf16 v[70:73], v[196:199], v[188:191], v[70:73]
	v_mfma_f32_16x16x32_bf16 v[66:69], v[204:207], v[188:191], v[66:69]
	v_mfma_f32_16x16x32_bf16 v[114:117], v[200:203], v[168:171], v[114:117]
	v_mfma_f32_16x16x32_bf16 v[106:109], v[210:213], v[168:171], v[106:109]
	v_mfma_f32_16x16x32_bf16 v[98:101], v[200:203], v[176:179], v[98:101]
	v_mfma_f32_16x16x32_bf16 v[90:93], v[210:213], v[176:179], v[90:93]
	v_mfma_f32_16x16x32_bf16 v[82:85], v[200:203], v[184:187], v[82:85]
	v_mfma_f32_16x16x32_bf16 v[74:77], v[210:213], v[184:187], v[74:77]
	v_mfma_f32_16x16x32_bf16 v[70:73], v[200:203], v[192:195], v[70:73]
	v_mfma_f32_16x16x32_bf16 v[66:69], v[210:213], v[192:195], v[66:69]
	s_barrier
	s_add_i32 s38, s38, s56
	v_lshl_add_u64 v[156:157], v[156:157], 0, s[36:37]
	s_mov_b32 m0, s38
	s_nop 0
	global_load_lds_dwordx4 v[156:157], off
	v_lshl_add_u64 v[156:157], v[214:215], 0, s[36:37]
	s_add_i32 m0, s38, 0x2000
	s_nop 0
	global_load_lds_dwordx4 v[156:157], off
	s_mov_b32 m0, s59
	v_lshl_add_u64 v[156:157], v[216:217], 0, s[36:37]
	global_load_lds_dwordx4 v[156:157], off
	v_lshl_add_u64 v[156:157], v[224:225], 0, s[36:37]
	s_mov_b32 m0, s60
	s_nop 0
	global_load_lds_dwordx4 v[156:157], off
	ds_read_b128 v[164:167], v147 offset:49152
	ds_read_b128 v[168:171], v147 offset:50176
	ds_read_b128 v[172:175], v147 offset:51200
	ds_read_b128 v[176:179], v147 offset:52224
	ds_read_b128 v[180:183], v147 offset:53248
	ds_read_b128 v[184:187], v147 offset:54272
	ds_read_b128 v[188:191], v147 offset:55296
	ds_read_b128 v[192:195], v147 offset:56320
	s_waitcnt vmcnt(4)
	s_waitcnt lgkmcnt(0)
	s_barrier
; #define PG8_STAGE(bufoff, gbase, voff) do { _Pragma("unroll") for (int _i = 0; _i < 2; ++_i) \
;         __builtin_amdgcn_global_load_lds((const unsigned*)((const char*)(gbase) + (voff)[_i]), (LAS unsigned*)(lds + (bufoff) + ldsw + _i * 8192), 16, 0, 0); } while (0)
; #define PG8_LDA(dst, b, h) do { _Pragma("unroll") for (int m = 0; m < 4; ++m) _Pragma("unroll") for (int k = 0; k < 2; ++k) dst[m][k] = *(const LAS bf16x8*)(lds + PG8_SA(b, h) + aoff + m * 2048 + k * 1024); } while (0)
; #define PG8_LDB(dst, b, h) do { _Pragma("unroll") for (int n = 0; n < 2; ++n) _Pragma("unroll") for (int k = 0; k < 2; ++k) dst[n][k] = *(const LAS bf16x8*)(lds + PG8_SB(b, h) + boff + n * 2048 + k * 1024); } while (0)
; #define PG8_MMA(ai, bj, At, Bt) do { __builtin_amdgcn_s_setprio(1); _Pragma("unroll") for (int m = 0; m < 4; ++m) _Pragma("unroll") for (int n = 0; n < 2; ++n) _Pragma("unroll") for (int k = 0; k < 2; ++k) \
;         acc[ai][bj][m][n] = __builtin_amdgcn_mfma_f32_16x16x32_bf16(Bt[n][k], At[m][k], acc[ai][bj][m][n], 0, 0, 0); __builtin_amdgcn_s_setprio(0); } while (0)
; #define PG8_WAIT_V(n) asm volatile("s_waitcnt vmcnt(" #n ")" ::: "memory")
; #define PG8_WAIT_L(n) asm volatile("s_waitcnt lgkmcnt(" #n ")" ::: "memory")
; #define PG8_BAR __builtin_amdgcn_s_barrier()
; #define PG8_SCHED __builtin_amdgcn_sched_barrier(0)
; template <class Epi, class Sched>
; __device__ __forceinline__ void gemm_phase(LAS unsigned char* lds, const Gemm g, const Sched& S, const Epi& E) {
;     ...
;             PG8_LDB(B1, 1, 1); PG8_STAGE(PG8_SB(1, 0), b3, voffB);
;             PG8_BAR; PG8_WAIT_L(0); PG8_MMA(0, 1, At, B1); PG8_BAR;
;             PG8_LDA(At, 1, 1); PG8_STAGE(PG8_SA(1, 0), a3, voffA);
;             PG8_BAR; PG8_WAIT_L(0); PG8_MMA(1, 0, At, B0); PG8_BAR; PG8_SCHED;
;             PG8_STAGE(PG8_SB(1, 1), b3 + hstep, voffB);
;             PG8_WAIT_V(6); PG8_BAR; PG8_MMA(1, 1, At, B1); PG8_BAR;
	v_mfma_f32_16x16x32_bf16 v[62:65], v[140:143], v[164:167], v[62:65]
	v_mfma_f32_16x16x32_bf16 v[58:61], v[152:155], v[164:167], v[58:61]
	v_mfma_f32_16x16x32_bf16 v[54:57], v[140:143], v[172:175], v[54:57]
	v_mfma_f32_16x16x32_bf16 v[46:49], v[152:155], v[172:175], v[46:49]
	v_mfma_f32_16x16x32_bf16 v[38:41], v[140:143], v[180:183], v[38:41]
	v_mfma_f32_16x16x32_bf16 v[30:33], v[152:155], v[180:183], v[30:33]
	v_mfma_f32_16x16x32_bf16 v[22:25], v[140:143], v[188:191], v[22:25]
	v_mfma_f32_16x16x32_bf16 v[14:17], v[152:155], v[188:191], v[14:17]
	v_mfma_f32_16x16x32_bf16 v[62:65], v[148:151], v[168:171], v[62:65]
	v_mfma_f32_16x16x32_bf16 v[58:61], v[160:163], v[168:171], v[58:61]
	v_mfma_f32_16x16x32_bf16 v[54:57], v[148:151], v[176:179], v[54:57]
	v_mfma_f32_16x16x32_bf16 v[46:49], v[160:163], v[176:179], v[46:49]
	v_mfma_f32_16x16x32_bf16 v[38:41], v[148:151], v[184:187], v[38:41]
	v_mfma_f32_16x16x32_bf16 v[30:33], v[160:163], v[184:187], v[30:33]
	v_mfma_f32_16x16x32_bf16 v[22:25], v[148:151], v[192:195], v[22:25]
	v_mfma_f32_16x16x32_bf16 v[14:17], v[160:163], v[192:195], v[14:17]
	s_add_u32 s52, s52, 0x80080
	s_addc_u32 s53, s53, 0
	s_add_i32 s38, s39, s56
	v_lshl_add_u64 v[140:141], s[52:53], 0, v[0:1]
	s_mov_b32 m0, s38
	s_nop 0
	global_load_lds_dwordx4 v[140:141], off
	v_lshl_add_u64 v[140:141], s[52:53], 0, v[134:135]
	s_add_i32 m0, s38, 0x2000
	s_nop 0
	global_load_lds_dwordx4 v[140:141], off
	v_mfma_f32_16x16x32_bf16 v[50:53], v[196:199], v[164:167], v[50:53]
	v_mfma_f32_16x16x32_bf16 v[42:45], v[204:207], v[164:167], v[42:45]
	v_mfma_f32_16x16x32_bf16 v[34:37], v[196:199], v[172:175], v[34:37]
	v_mfma_f32_16x16x32_bf16 v[26:29], v[204:207], v[172:175], v[26:29]
	v_mfma_f32_16x16x32_bf16 v[18:21], v[196:199], v[180:183], v[18:21]
	v_mfma_f32_16x16x32_bf16 v[10:13], v[204:207], v[180:183], v[10:13]
	v_mfma_f32_16x16x32_bf16 v[6:9], v[196:199], v[188:191], v[6:9]
	v_mfma_f32_16x16x32_bf16 v[2:5], v[204:207], v[188:191], v[2:5]
	v_mfma_f32_16x16x32_bf16 v[50:53], v[200:203], v[168:171], v[50:53]
	v_mfma_f32_16x16x32_bf16 v[42:45], v[210:213], v[168:171], v[42:45]
	v_mfma_f32_16x16x32_bf16 v[34:37], v[200:203], v[176:179], v[34:37]
	v_mfma_f32_16x16x32_bf16 v[26:29], v[210:213], v[176:179], v[26:29]
	v_mfma_f32_16x16x32_bf16 v[18:21], v[200:203], v[184:187], v[18:21]
	v_mfma_f32_16x16x32_bf16 v[10:13], v[210:213], v[184:187], v[10:13]
	v_mfma_f32_16x16x32_bf16 v[6:9], v[200:203], v[192:195], v[6:9]
	v_mfma_f32_16x16x32_bf16 v[2:5], v[210:213], v[192:195], v[2:5]
	s_add_i32 s70, s70, 2
	s_add_u32 s68, s68, 0x100
	s_addc_u32 s69, s69, 0
	s_add_u32 s50, s50, 0x100
	s_addc_u32 s51, s51, 0
	s_cmp_gt_u32 s70, 29
	s_barrier
	s_cbranch_scc0 .LBB0_354
; __device__ __forceinline__ unsigned cvt_pk_bf16(float lo, float hi) { unsigned r; asm("v_cvt_pk_bf16_f32 %0, %1, %2" : "=v"(r) : "v"(lo), "v"(hi)); return r; }
;     __device__ __forceinline__ void operator()(const f32x4 (&acc)[2][2][4][2], const Unit& u, int wr, int wc, int fr, int fq) const {
;         const int row0 = u.pm * BM + wr * 64 + fr, col0 = u.pn * BM + wc * 32 + 8 * fq;
; #pragma unroll
;         for (int ai = 0; ai < 2; ++ai)
; #pragma unroll
;             for (int m = 0; m < 4; ++m) { bf16_t* rowp = O + (size_t)(row0 + ai * HALF + m * 16) * ldc + col0;
; #pragma unroll
;                 for (int bj = 0; bj < 2; ++bj) { f32x4 v0 = acc[ai][bj][m][0], v1 = acc[ai][bj][m][1];
;                     if (ACT == 1) {
; #pragma unroll
;                         for (int j = 0; j < 4; ++j) { float a = fmaxf(v0[j], 0.f), b = fmaxf(v1[j], 0.f); v0[j] = a * a; v1[j] = b * b; } }
;                     u32x4 w; w.x = cvt_pk_bf16(v0[0], v0[1]); w.y = cvt_pk_bf16(v0[2], v0[3]); w.z = cvt_pk_bf16(v1[0], v1[1]); w.w = cvt_pk_bf16(v1[2], v1[3]);
;                     if (ACT == 1) __builtin_nontemporal_store(w, (u32x4*)(rowp + bj * HALF));
;                     else *(u32x4*)(rowp + bj * HALF) = w; } }
	s_load_dwordx2 s[50:51], s[0:1], 0xc0
	v_lshl_add_u32 v150, s28, 8, v144
	v_lshl_or_b32 v142, s40, 8, v146
	v_ashrrev_i32_e32 v143, 31, v142
	v_cvt_pk_bf16_f32 v70, v70, v71
	s_waitcnt lgkmcnt(0)
	v_mov_b64_e32 v[140:141], s[50:51]
	v_cvt_pk_bf16_f32 v71, v72, v73
	v_cvt_pk_bf16_f32 v72, v66, v67
	v_add_u32_e32 v66, 0x80, v150
	v_mad_i64_i32 v[148:149], s[50:51], v150, s17, v[140:141]
	v_lshlrev_b64 v[142:143], 1, v[142:143]
	v_cvt_pk_bf16_f32 v114, v114, v115
	v_cvt_pk_bf16_f32 v115, v116, v117
	v_cvt_pk_bf16_f32 v116, v106, v107
	v_or_b32_e32 v106, 16, v150
	v_mad_i64_i32 v[66:67], s[50:51], v66, s17, v[140:141]
	v_cvt_pk_bf16_f32 v50, v50, v51
	v_cvt_pk_bf16_f32 v51, v52, v53
	v_cvt_pk_bf16_f32 v52, v42, v43
	v_add_u32_e32 v42, 0x90, v150
	v_lshl_add_u64 v[148:149], v[148:149], 0, v[142:143]
	v_mad_i64_i32 v[106:107], s[50:51], v106, s17, v[140:141]
	v_cvt_pk_bf16_f32 v98, v98, v99
	v_cvt_pk_bf16_f32 v99, v100, v101
	v_cvt_pk_bf16_f32 v100, v90, v91
	v_or_b32_e32 v90, 32, v150
	v_lshl_add_u64 v[66:67], v[66:67], 0, v[142:143]
	v_mad_i64_i32 v[42:43], s[50:51], v42, s17, v[140:141]
	v_cvt_pk_bf16_f32 v34, v34, v35
	v_cvt_pk_bf16_f32 v35, v36, v37
	v_cvt_pk_bf16_f32 v36, v26, v27
	v_add_u32_e32 v26, 0xa0, v150
	v_cvt_pk_bf16_f32 v117, v108, v109
	global_store_dwordx4 v[148:149], v[114:117], off offset:256
	v_mad_i64_i32 v[90:91], s[50:51], v90, s17, v[140:141]
	s_nop 0
	v_lshl_add_u64 v[114:115], v[106:107], 0, v[142:143]
	v_cvt_pk_bf16_f32 v82, v82, v83
	v_cvt_pk_bf16_f32 v83, v84, v85
	v_cvt_pk_bf16_f32 v84, v74, v75
	v_or_b32_e32 v74, 48, v150
	v_cvt_pk_bf16_f32 v53, v44, v45
	global_store_dwordx4 v[66:67], v[50:53], off offset:256
	v_mad_i64_i32 v[26:27], s[50:51], v26, s17, v[140:141]
	s_nop 0
	v_lshl_add_u64 v[50:51], v[42:43], 0, v[142:143]
	v_cvt_pk_bf16_f32 v18, v18, v19
	v_cvt_pk_bf16_f32 v19, v20, v21
	v_cvt_pk_bf16_f32 v20, v10, v11
	v_add_u32_e32 v10, 0xb0, v150
	v_cvt_pk_bf16_f32 v101, v92, v93
	global_store_dwordx4 v[114:115], v[98:101], off offset:256
	v_mad_i64_i32 v[74:75], s[50:51], v74, s17, v[140:141]
	s_nop 0
	v_lshl_add_u64 v[98:99], v[90:91], 0, v[142:143]
	v_cvt_pk_bf16_f32 v37, v28, v29
	global_store_dwordx4 v[50:51], v[34:37], off offset:256
	v_mad_i64_i32 v[10:11], s[50:51], v10, s17, v[140:141]
	s_nop 0
	v_lshl_add_u64 v[34:35], v[26:27], 0, v[142:143]
	v_cvt_pk_bf16_f32 v85, v76, v77
	global_store_dwordx4 v[98:99], v[82:85], off offset:256
	v_cvt_pk_bf16_f32 v21, v12, v13
	global_store_dwordx4 v[34:35], v[18:21], off offset:256
	s_and_b64 vcc, exec, s[46:47]
	v_lshl_add_u64 v[82:83], v[74:75], 0, v[142:143]
	v_lshl_add_u64 v[18:19], v[10:11], 0, v[142:143]
	s_mov_b32 s40, s42
	s_mov_b32 s28, s8
	s_mov_b32 s43, s42
	s_mov_b32 s46, s8
	s_mov_b64 s[50:51], s[48:49]
	s_mov_b64 s[52:53], s[44:45]
	v_cvt_pk_bf16_f32 v126, v126, v127
	v_cvt_pk_bf16_f32 v127, v128, v129
	v_cvt_pk_bf16_f32 v128, v122, v123
	v_cvt_pk_bf16_f32 v129, v124, v125
	global_store_dwordx4 v[148:149], v[126:129], off
	v_cvt_pk_bf16_f32 v106, v118, v119
	v_cvt_pk_bf16_f32 v107, v120, v121
	v_cvt_pk_bf16_f32 v108, v110, v111
	v_cvt_pk_bf16_f32 v109, v112, v113
	global_store_dwordx4 v[114:115], v[106:109], off
	v_cvt_pk_bf16_f32 v90, v102, v103
	v_cvt_pk_bf16_f32 v91, v104, v105
	v_cvt_pk_bf16_f32 v92, v94, v95
	v_cvt_pk_bf16_f32 v93, v96, v97
	global_store_dwordx4 v[98:99], v[90:93], off
	v_cvt_pk_bf16_f32 v74, v86, v87
	v_cvt_pk_bf16_f32 v75, v88, v89
	v_cvt_pk_bf16_f32 v76, v78, v79
	v_cvt_pk_bf16_f32 v77, v80, v81
	global_store_dwordx4 v[82:83], v[74:77], off
	v_cvt_pk_bf16_f32 v73, v68, v69
	global_store_dwordx4 v[82:83], v[70:73], off offset:256
	v_cvt_pk_bf16_f32 v62, v62, v63
	v_cvt_pk_bf16_f32 v63, v64, v65
	v_cvt_pk_bf16_f32 v64, v58, v59
	v_cvt_pk_bf16_f32 v65, v60, v61
	global_store_dwordx4 v[66:67], v[62:65], off
	v_cvt_pk_bf16_f32 v42, v54, v55
	v_cvt_pk_bf16_f32 v43, v56, v57
	v_cvt_pk_bf16_f32 v44, v46, v47
	v_cvt_pk_bf16_f32 v45, v48, v49
	global_store_dwordx4 v[50:51], v[42:45], off
	v_cvt_pk_bf16_f32 v26, v38, v39
	v_cvt_pk_bf16_f32 v27, v40, v41
	v_cvt_pk_bf16_f32 v28, v30, v31
	v_cvt_pk_bf16_f32 v29, v32, v33
	global_store_dwordx4 v[34:35], v[26:29], off
	v_cvt_pk_bf16_f32 v10, v22, v23
	v_cvt_pk_bf16_f32 v11, v24, v25
	v_cvt_pk_bf16_f32 v12, v14, v15
	v_cvt_pk_bf16_f32 v13, v16, v17
	global_store_dwordx4 v[18:19], v[10:13], off
	v_cvt_pk_bf16_f32 v6, v6, v7
	v_cvt_pk_bf16_f32 v7, v8, v9
	v_cvt_pk_bf16_f32 v8, v2, v3
	v_cvt_pk_bf16_f32 v9, v4, v5
	global_store_dwordx4 v[18:19], v[6:9], off offset:256
	s_cbranch_vccz .LBB0_346
	s_waitcnt vmcnt(0)
	s_cmpk_gt_u32 s25, 0xff
	s_cbranch_scc1 .LBB0_358
	s_barrier
